# v35 + L2X: hand-written LRU pass-2 unit (all carry-in loads at once, 47-63 row deep AD ring, prefetched gate rows)
# speedup vs baseline: 1.0009x; 1.0009x over previous
; #define LAS __attribute__((address_space(3)))
; __device__ __forceinline__ void lru_pass2_unit(int cu, const h2* AD, const float2* LCS, const bf16* LG, bf16* MIX, lds_t* lds, int tid) {
;     const int b = cu < 256 ? cu >> 5 : (cu - 256) >> 1, c = cu < 256 ? cu & 31 : 32 + ((cu - 256) & 1);
;     const int m0 = chunk_row0(b, c); const int dir = tid >> 8, ch = tid & 255;
;     LAS _Float16* HS = (LAS _Float16*)lds;
;     float h = 0.f;
;     const float2* cs = LCS + (size_t)b * 34 * 512 + dir * 256 + ch;
;     const int n = dir == 0 ? (c < 32 ? c + 2 : c - 32) : 33 - c;
;     for (int i0 = 0; i0 < n; i0 += 8) { float2 s[8];
; #pragma unroll
;         for (int j = 0; j < 8; ++j) { const int ii = (i0 + j < n) ? i0 + j : 0; const int cc = dir == 0 ? (ii < 2 ? 32 + ii : ii - 2) : 33 - ii; s[j] = cs[(size_t)cc * 512]; }
.Ll2x_unit:
	v_and_b32_e32 v3, 0xff, v212
	v_lshlrev_b32_e32 v2, 3, v3
	v_lshlrev_b32_e32 v3, 2, v3
	v_lshlrev_b32_e32 v4, 1, v212
	v_add_u32_e32 v5, 0x10000, v4
	v_and_b32_e32 v8, 31, v212
	v_lshlrev_b32_e32 v8, 4, v8
	v_lshrrev_b32_e32 v11, 5, v212
	v_lshl_add_u32 v6, v11, 10, v8
	v_add_u32_e32 v7, 0x10000, v6
	v_lshl_add_u32 v9, v11, 11, v8
	v_lshl_add_u32 v8, v11, 9, v8
	v_readfirstlane_b32 s0, v212
	v_readlane_b32 s24, v252, 24
	v_readlane_b32 s25, v252, 25
	v_readlane_b32 s12, v252, 43
	v_readlane_b32 s13, v252, 44
	v_readlane_b32 s14, v252, 41
	v_readlane_b32 s15, v252, 42
	s_nop 3
	s_lshr_b32 s1, s0, 8
	s_cmpk_lt_i32 s26, 0x100
	s_cbranch_scc0 .Ll2x_ctx
	s_lshr_b32 s2, s26, 5
	s_and_b32 s3, s26, 31
	s_lshl_b32 s8, s2, 12
	s_lshl_b32 s18, s3, 7
	s_add_u32 s8, s8, s18
	s_branch .Ll2x_dec
.Ll2x_ctx:
	s_sub_u32 s18, s26, 0x100
	s_lshr_b32 s2, s18, 1
	s_and_b32 s18, s18, 1
	s_add_u32 s3, s18, 32
	s_lshl_b32 s8, s2, 8
	s_lshl_b32 s18, s18, 7
	s_add_u32 s8, s8, s18
	s_add_u32 s8, s8, 0x8000
.Ll2x_dec:
	s_lshl_b32 s18, s8, 11
	s_add_u32 s12, s12, s18
	s_addc_u32 s13, s13, 0
	s_add_u32 s16, s68, s18
	s_addc_u32 s17, s69, 0
	s_lshl_b32 s18, s8, 9
	s_add_u32 s14, s14, s18
	s_addc_u32 s15, s15, 0
	s_cmp_eq_u32 s1, 0
	s_cbranch_scc0 .Ll2x_dir1
	s_mul_i32 s18, s2, 0x22000
	s_add_u32 s10, s24, s18
	s_addc_u32 s11, s25, 0
	s_add_u32 s9, s3, 2
	s_sub_u32 s18, s3, 32
	s_cmp_lt_u32 s3, 32
	s_cselect_b32 s9, s9, s18
	s_mov_b32 s19, 0x20000
	s_cmp_gt_u32 s9, 0
	s_cselect_b32 s18, 0x20000, s19
	s_add_u32 s20, s10, s18
	s_addc_u32 s21, s11, 0
	global_load_dwordx2 v[14:15], v2, s[20:21]
	s_cmp_gt_u32 s9, 1
	s_cselect_b32 s18, 0x21000, s19
	s_add_u32 s20, s10, s18
	s_addc_u32 s21, s11, 0
	global_load_dwordx2 v[16:17], v2, s[20:21]
	s_cmp_gt_u32 s9, 2
	s_cselect_b32 s18, 0x0, s19
	s_add_u32 s20, s10, s18
	s_addc_u32 s21, s11, 0
	global_load_dwordx2 v[18:19], v2, s[20:21]
	s_cmp_gt_u32 s9, 3
	s_cselect_b32 s18, 0x1000, s19
	s_add_u32 s20, s10, s18
	s_addc_u32 s21, s11, 0
	global_load_dwordx2 v[20:21], v2, s[20:21]
	s_cmp_gt_u32 s9, 4
	s_cselect_b32 s18, 0x2000, s19
	s_add_u32 s20, s10, s18
	s_addc_u32 s21, s11, 0
	global_load_dwordx2 v[22:23], v2, s[20:21]
	s_cmp_gt_u32 s9, 5
	s_cselect_b32 s18, 0x3000, s19
	s_add_u32 s20, s10, s18
	s_addc_u32 s21, s11, 0
	global_load_dwordx2 v[24:25], v2, s[20:21]
	s_cmp_gt_u32 s9, 6
	s_cselect_b32 s18, 0x4000, s19
	s_add_u32 s20, s10, s18
	s_addc_u32 s21, s11, 0
	global_load_dwordx2 v[26:27], v2, s[20:21]
	s_cmp_gt_u32 s9, 7
	s_cselect_b32 s18, 0x5000, s19
	s_add_u32 s20, s10, s18
	s_addc_u32 s21, s11, 0
	global_load_dwordx2 v[28:29], v2, s[20:21]
	s_cmp_gt_u32 s9, 8
	s_cselect_b32 s18, 0x6000, s19
	s_add_u32 s20, s10, s18
	s_addc_u32 s21, s11, 0
	global_load_dwordx2 v[30:31], v2, s[20:21]
	s_cmp_gt_u32 s9, 9
	s_cselect_b32 s18, 0x7000, s19
	s_add_u32 s20, s10, s18
	s_addc_u32 s21, s11, 0
	global_load_dwordx2 v[32:33], v2, s[20:21]
	s_cmp_gt_u32 s9, 10
	s_cselect_b32 s18, 0x8000, s19
	s_add_u32 s20, s10, s18
	s_addc_u32 s21, s11, 0
	global_load_dwordx2 v[34:35], v2, s[20:21]
	s_cmp_gt_u32 s9, 11
	s_cselect_b32 s18, 0x9000, s19
	s_add_u32 s20, s10, s18
	s_addc_u32 s21, s11, 0
	global_load_dwordx2 v[36:37], v2, s[20:21]
	s_cmp_gt_u32 s9, 12
	s_cselect_b32 s18, 0xa000, s19
	s_add_u32 s20, s10, s18
	s_addc_u32 s21, s11, 0
	global_load_dwordx2 v[38:39], v2, s[20:21]
	s_cmp_gt_u32 s9, 13
	s_cselect_b32 s18, 0xb000, s19
	s_add_u32 s20, s10, s18
	s_addc_u32 s21, s11, 0
	global_load_dwordx2 v[40:41], v2, s[20:21]
	s_cmp_gt_u32 s9, 14
	s_cselect_b32 s18, 0xc000, s19
	s_add_u32 s20, s10, s18
	s_addc_u32 s21, s11, 0
	global_load_dwordx2 v[42:43], v2, s[20:21]
	s_cmp_gt_u32 s9, 15
	s_cselect_b32 s18, 0xd000, s19
	s_add_u32 s20, s10, s18
	s_addc_u32 s21, s11, 0
	global_load_dwordx2 v[44:45], v2, s[20:21]
	s_cmp_gt_u32 s9, 16
	s_cselect_b32 s18, 0xe000, s19
	s_add_u32 s20, s10, s18
	s_addc_u32 s21, s11, 0
	global_load_dwordx2 v[46:47], v2, s[20:21]
	s_cmp_gt_u32 s9, 17
	s_cselect_b32 s18, 0xf000, s19
	s_add_u32 s20, s10, s18
	s_addc_u32 s21, s11, 0
	global_load_dwordx2 v[48:49], v2, s[20:21]
	s_cmp_gt_u32 s9, 18
	s_cselect_b32 s18, 0x10000, s19
	s_add_u32 s20, s10, s18
	s_addc_u32 s21, s11, 0
	global_load_dwordx2 v[50:51], v2, s[20:21]
	s_cmp_gt_u32 s9, 19
	s_cselect_b32 s18, 0x11000, s19
	s_add_u32 s20, s10, s18
	s_addc_u32 s21, s11, 0
	global_load_dwordx2 v[52:53], v2, s[20:21]
	s_cmp_gt_u32 s9, 20
	s_cselect_b32 s18, 0x12000, s19
	s_add_u32 s20, s10, s18
	s_addc_u32 s21, s11, 0
	global_load_dwordx2 v[54:55], v2, s[20:21]
	s_cmp_gt_u32 s9, 21
	s_cselect_b32 s18, 0x13000, s19
	s_add_u32 s20, s10, s18
	s_addc_u32 s21, s11, 0
	global_load_dwordx2 v[56:57], v2, s[20:21]
	s_cmp_gt_u32 s9, 22
	s_cselect_b32 s18, 0x14000, s19
	s_add_u32 s20, s10, s18
	s_addc_u32 s21, s11, 0
	global_load_dwordx2 v[58:59], v2, s[20:21]
	s_cmp_gt_u32 s9, 23
	s_cselect_b32 s18, 0x15000, s19
	s_add_u32 s20, s10, s18
	s_addc_u32 s21, s11, 0
	global_load_dwordx2 v[60:61], v2, s[20:21]
	s_cmp_gt_u32 s9, 24
	s_cselect_b32 s18, 0x16000, s19
	s_add_u32 s20, s10, s18
	s_addc_u32 s21, s11, 0
	global_load_dwordx2 v[62:63], v2, s[20:21]
	s_cmp_gt_u32 s9, 25
	s_cselect_b32 s18, 0x17000, s19
	s_add_u32 s20, s10, s18
	s_addc_u32 s21, s11, 0
	global_load_dwordx2 v[64:65], v2, s[20:21]
	s_cmp_gt_u32 s9, 26
	s_cselect_b32 s18, 0x18000, s19
	s_add_u32 s20, s10, s18
	s_addc_u32 s21, s11, 0
	global_load_dwordx2 v[66:67], v2, s[20:21]
	s_cmp_gt_u32 s9, 27
	s_cselect_b32 s18, 0x19000, s19
	s_add_u32 s20, s10, s18
	s_addc_u32 s21, s11, 0
	global_load_dwordx2 v[68:69], v2, s[20:21]
	s_cmp_gt_u32 s9, 28
	s_cselect_b32 s18, 0x1a000, s19
	s_add_u32 s20, s10, s18
	s_addc_u32 s21, s11, 0
; __device__ __forceinline__ void lru_pass2_unit(int cu, const h2* AD, const float2* LCS, const bf16* LG, bf16* MIX, lds_t* lds, int tid) {
;     ...
;     const float2* cs = LCS + (size_t)b * 34 * 512 + dir * 256 + ch;
;     const int n = dir == 0 ? (c < 32 ? c + 2 : c - 32) : 33 - c;
;     for (int i0 = 0; i0 < n; i0 += 8) { float2 s[8];
; #pragma unroll
;         for (int j = 0; j < 8; ++j) { const int ii = (i0 + j < n) ? i0 + j : 0; const int cc = dir == 0 ? (ii < 2 ? 32 + ii : ii - 2) : 33 - ii; s[j] = cs[(size_t)cc * 512]; }
; #pragma unroll
;         for (int j = 0; j < 8; ++j) if (i0 + j < n) h = s[j].x * h + s[j].y; }
;     const h2* ad = AD + ((size_t)m0 * 2 + dir) * 256 + ch;
;     {
;         h2 fa[16], fb[16];
; #pragma unroll
;         for (int j = 0; j < 16; ++j) { const int r = dir == 0 ? j : 127 - j; fa[j] = ad[(size_t)r * 512]; }
	global_load_dwordx2 v[70:71], v2, s[20:21]
	s_cmp_gt_u32 s9, 29
	s_cselect_b32 s18, 0x1b000, s19
	s_add_u32 s20, s10, s18
	s_addc_u32 s21, s11, 0
	global_load_dwordx2 v[72:73], v2, s[20:21]
	s_cmp_gt_u32 s9, 30
	s_cselect_b32 s18, 0x1c000, s19
	s_add_u32 s20, s10, s18
	s_addc_u32 s21, s11, 0
	global_load_dwordx2 v[74:75], v2, s[20:21]
	s_cmp_gt_u32 s9, 31
	s_cselect_b32 s18, 0x1d000, s19
	s_add_u32 s20, s10, s18
	s_addc_u32 s21, s11, 0
	global_load_dwordx2 v[76:77], v2, s[20:21]
	s_cmp_gt_u32 s9, 32
	s_cselect_b32 s18, 0x1e000, s19
	s_add_u32 s20, s10, s18
	s_addc_u32 s21, s11, 0
	global_load_dwordx2 v[78:79], v2, s[20:21]
	s_cmp_gt_u32 s9, 33
	s_cselect_b32 s18, 0x1f000, s19
	s_add_u32 s20, s10, s18
	s_addc_u32 s21, s11, 0
	global_load_dwordx2 v[80:81], v2, s[20:21]
	s_add_u32 s22, s12, 0x0
	s_addc_u32 s23, s13, 0
	global_load_dword v130, v3, s[22:23]
	global_load_dword v131, v3, s[22:23] offset:2048
	s_add_u32 s22, s12, 0x1000
	s_addc_u32 s23, s13, 0
	global_load_dword v132, v3, s[22:23]
	global_load_dword v133, v3, s[22:23] offset:2048
	s_add_u32 s22, s12, 0x2000
	s_addc_u32 s23, s13, 0
	global_load_dword v134, v3, s[22:23]
	global_load_dword v135, v3, s[22:23] offset:2048
	s_add_u32 s22, s12, 0x3000
	s_addc_u32 s23, s13, 0
	global_load_dword v136, v3, s[22:23]
	global_load_dword v137, v3, s[22:23] offset:2048
	s_add_u32 s22, s12, 0x4000
	s_addc_u32 s23, s13, 0
	global_load_dword v138, v3, s[22:23]
	global_load_dword v139, v3, s[22:23] offset:2048
	s_add_u32 s22, s12, 0x5000
	s_addc_u32 s23, s13, 0
	global_load_dword v140, v3, s[22:23]
	global_load_dword v141, v3, s[22:23] offset:2048
	s_add_u32 s22, s12, 0x6000
	s_addc_u32 s23, s13, 0
	global_load_dword v142, v3, s[22:23]
	global_load_dword v143, v3, s[22:23] offset:2048
	s_add_u32 s22, s12, 0x7000
	s_addc_u32 s23, s13, 0
	global_load_dword v144, v3, s[22:23]
	global_load_dword v145, v3, s[22:23] offset:2048
	s_add_u32 s22, s12, 0x8000
	s_addc_u32 s23, s13, 0
	global_load_dword v146, v3, s[22:23]
	global_load_dword v147, v3, s[22:23] offset:2048
	s_add_u32 s22, s12, 0x9000
	s_addc_u32 s23, s13, 0
	global_load_dword v148, v3, s[22:23]
	global_load_dword v149, v3, s[22:23] offset:2048
	s_add_u32 s22, s12, 0xa000
	s_addc_u32 s23, s13, 0
	global_load_dword v150, v3, s[22:23]
	global_load_dword v151, v3, s[22:23] offset:2048
	s_add_u32 s22, s12, 0xb000
	s_addc_u32 s23, s13, 0
	global_load_dword v152, v3, s[22:23]
	global_load_dword v153, v3, s[22:23] offset:2048
	s_add_u32 s22, s12, 0xc000
	s_addc_u32 s23, s13, 0
	global_load_dword v154, v3, s[22:23]
	global_load_dword v155, v3, s[22:23] offset:2048
	s_add_u32 s22, s12, 0xd000
	s_addc_u32 s23, s13, 0
	global_load_dword v156, v3, s[22:23]
	global_load_dword v157, v3, s[22:23] offset:2048
	s_add_u32 s22, s12, 0xe000
	s_addc_u32 s23, s13, 0
	global_load_dword v158, v3, s[22:23]
	s_waitcnt vmcnt(29)
	v_mov_b32_e32 v10, 0
	s_cmp_gt_u32 s9, 0
	s_cbranch_scc0 .Ll2x_d0_cdone
	v_fma_f32 v10, v14, v10, v15
	s_cmp_gt_u32 s9, 1
	s_cbranch_scc0 .Ll2x_d0_cdone
	v_fma_f32 v10, v16, v10, v17
	s_cmp_gt_u32 s9, 2
	s_cbranch_scc0 .Ll2x_d0_cdone
	v_fma_f32 v10, v18, v10, v19
	s_cmp_gt_u32 s9, 3
	s_cbranch_scc0 .Ll2x_d0_cdone
	v_fma_f32 v10, v20, v10, v21
	s_cmp_gt_u32 s9, 4
	s_cbranch_scc0 .Ll2x_d0_cdone
	v_fma_f32 v10, v22, v10, v23
	s_cmp_gt_u32 s9, 5
	s_cbranch_scc0 .Ll2x_d0_cdone
	v_fma_f32 v10, v24, v10, v25
	s_cmp_gt_u32 s9, 6
	s_cbranch_scc0 .Ll2x_d0_cdone
	v_fma_f32 v10, v26, v10, v27
	s_cmp_gt_u32 s9, 7
	s_cbranch_scc0 .Ll2x_d0_cdone
	v_fma_f32 v10, v28, v10, v29
	s_cmp_gt_u32 s9, 8
	s_cbranch_scc0 .Ll2x_d0_cdone
	v_fma_f32 v10, v30, v10, v31
	s_cmp_gt_u32 s9, 9
	s_cbranch_scc0 .Ll2x_d0_cdone
	v_fma_f32 v10, v32, v10, v33
	s_cmp_gt_u32 s9, 10
	s_cbranch_scc0 .Ll2x_d0_cdone
	v_fma_f32 v10, v34, v10, v35
	s_cmp_gt_u32 s9, 11
	s_cbranch_scc0 .Ll2x_d0_cdone
	v_fma_f32 v10, v36, v10, v37
	s_cmp_gt_u32 s9, 12
	s_cbranch_scc0 .Ll2x_d0_cdone
	v_fma_f32 v10, v38, v10, v39
	s_cmp_gt_u32 s9, 13
	s_cbranch_scc0 .Ll2x_d0_cdone
	v_fma_f32 v10, v40, v10, v41
	s_cmp_gt_u32 s9, 14
	s_cbranch_scc0 .Ll2x_d0_cdone
	v_fma_f32 v10, v42, v10, v43
	s_cmp_gt_u32 s9, 15
	s_cbranch_scc0 .Ll2x_d0_cdone
	v_fma_f32 v10, v44, v10, v45
	s_cmp_gt_u32 s9, 16
	s_cbranch_scc0 .Ll2x_d0_cdone
	v_fma_f32 v10, v46, v10, v47
	s_cmp_gt_u32 s9, 17
	s_cbranch_scc0 .Ll2x_d0_cdone
	v_fma_f32 v10, v48, v10, v49
	s_cmp_gt_u32 s9, 18
	s_cbranch_scc0 .Ll2x_d0_cdone
	v_fma_f32 v10, v50, v10, v51
	s_cmp_gt_u32 s9, 19
	s_cbranch_scc0 .Ll2x_d0_cdone
	v_fma_f32 v10, v52, v10, v53
	s_cmp_gt_u32 s9, 20
	s_cbranch_scc0 .Ll2x_d0_cdone
	v_fma_f32 v10, v54, v10, v55
	s_cmp_gt_u32 s9, 21
	s_cbranch_scc0 .Ll2x_d0_cdone
	v_fma_f32 v10, v56, v10, v57
	s_cmp_gt_u32 s9, 22
	s_cbranch_scc0 .Ll2x_d0_cdone
	v_fma_f32 v10, v58, v10, v59
	s_cmp_gt_u32 s9, 23
	s_cbranch_scc0 .Ll2x_d0_cdone
	v_fma_f32 v10, v60, v10, v61
	s_cmp_gt_u32 s9, 24
	s_cbranch_scc0 .Ll2x_d0_cdone
	v_fma_f32 v10, v62, v10, v63
	s_cmp_gt_u32 s9, 25
	s_cbranch_scc0 .Ll2x_d0_cdone
	v_fma_f32 v10, v64, v10, v65
	s_cmp_gt_u32 s9, 26
	s_cbranch_scc0 .Ll2x_d0_cdone
	v_fma_f32 v10, v66, v10, v67
	s_cmp_gt_u32 s9, 27
	s_cbranch_scc0 .Ll2x_d0_cdone
	v_fma_f32 v10, v68, v10, v69
	s_cmp_gt_u32 s9, 28
	s_cbranch_scc0 .Ll2x_d0_cdone
	v_fma_f32 v10, v70, v10, v71
	s_cmp_gt_u32 s9, 29
	s_cbranch_scc0 .Ll2x_d0_cdone
	v_fma_f32 v10, v72, v10, v73
	s_cmp_gt_u32 s9, 30
	s_cbranch_scc0 .Ll2x_d0_cdone
	v_fma_f32 v10, v74, v10, v75
	s_cmp_gt_u32 s9, 31
	s_cbranch_scc0 .Ll2x_d0_cdone
	v_fma_f32 v10, v76, v10, v77
	s_cmp_gt_u32 s9, 32
	s_cbranch_scc0 .Ll2x_d0_cdone
	v_fma_f32 v10, v78, v10, v79
	s_cmp_gt_u32 s9, 33
	s_cbranch_scc0 .Ll2x_d0_cdone
	v_fma_f32 v10, v80, v10, v81
; __device__ __forceinline__ void lru_pass2_unit(int cu, const h2* AD, const float2* LCS, const bf16* LG, bf16* MIX, lds_t* lds, int tid) {
;     ...
;     const h2* ad = AD + ((size_t)m0 * 2 + dir) * 256 + ch;
;     {
;         h2 fa[16], fb[16];
; #pragma unroll
;         for (int j = 0; j < 16; ++j) { const int r = dir == 0 ? j : 127 - j; fa[j] = ad[(size_t)r * 512]; }
; #pragma unroll 1
;         for (int r0 = 0; r0 < 128; r0 += 32) {
; #pragma unroll
;             for (int j = 0; j < 16; ++j) { const int r = dir == 0 ? r0 + 16 + j : 127 - (r0 + 16 + j); fb[j] = ad[(size_t)r * 512]; }
; #pragma unroll
;             for (int j = 0; j < 16; ++j) { const int r = dir == 0 ? r0 + j : 127 - (r0 + j); h = (1.0f - (float)fa[j][0]) * h + (float)fa[j][1]; HS[r * 512 + dir * 256 + ch] = (_Float16)h; }
;             if (r0 + 32 < 128) {
; #pragma unroll
;                 for (int j = 0; j < 16; ++j) { const int r = dir == 0 ? r0 + 32 + j : 127 - (r0 + 32 + j); fa[j] = ad[(size_t)r * 512]; } }
; #pragma unroll
;             for (int j = 0; j < 16; ++j) { const int r = dir == 0 ? r0 + 16 + j : 127 - (r0 + 16 + j); h = (1.0f - (float)fb[j][0]) * h + (float)fb[j][1]; HS[r * 512 + dir * 256 + ch] = (_Float16)h; } } }
.Ll2x_d0_cdone:
	global_load_dword v159, v3, s[22:23] offset:2048
	s_add_u32 s22, s12, 0xf000
	s_addc_u32 s23, s13, 0
	global_load_dword v160, v3, s[22:23]
	global_load_dword v161, v3, s[22:23] offset:2048
	s_add_u32 s22, s12, 0x10000
	s_addc_u32 s23, s13, 0
	global_load_dword v162, v3, s[22:23]
	global_load_dword v163, v3, s[22:23] offset:2048
	s_add_u32 s22, s12, 0x11000
	s_addc_u32 s23, s13, 0
	global_load_dword v164, v3, s[22:23]
	global_load_dword v165, v3, s[22:23] offset:2048
	s_add_u32 s22, s12, 0x12000
	s_addc_u32 s23, s13, 0
	global_load_dword v166, v3, s[22:23]
	global_load_dword v167, v3, s[22:23] offset:2048
	s_add_u32 s22, s12, 0x13000
	s_addc_u32 s23, s13, 0
	global_load_dword v168, v3, s[22:23]
	global_load_dword v169, v3, s[22:23] offset:2048
	s_add_u32 s22, s12, 0x14000
	s_addc_u32 s23, s13, 0
	global_load_dword v170, v3, s[22:23]
	global_load_dword v171, v3, s[22:23] offset:2048
	s_add_u32 s22, s12, 0x15000
	s_addc_u32 s23, s13, 0
	global_load_dword v172, v3, s[22:23]
	global_load_dword v173, v3, s[22:23] offset:2048
	s_add_u32 s22, s12, 0x16000
	s_addc_u32 s23, s13, 0
	global_load_dword v174, v3, s[22:23]
	global_load_dword v175, v3, s[22:23] offset:2048
	s_add_u32 s22, s12, 0x17000
	s_addc_u32 s23, s13, 0
	global_load_dword v176, v3, s[22:23]
	global_load_dword v177, v3, s[22:23] offset:2048
	s_add_u32 s22, s12, 0x18000
	s_addc_u32 s23, s13, 0
	global_load_dword v178, v3, s[22:23]
	global_load_dword v179, v3, s[22:23] offset:2048
	s_add_u32 s22, s12, 0x19000
	s_addc_u32 s23, s13, 0
	global_load_dword v180, v3, s[22:23]
	global_load_dword v181, v3, s[22:23] offset:2048
	s_add_u32 s22, s12, 0x1a000
	s_addc_u32 s23, s13, 0
	global_load_dword v182, v3, s[22:23]
	global_load_dword v183, v3, s[22:23] offset:2048
	s_add_u32 s22, s12, 0x1b000
	s_addc_u32 s23, s13, 0
	global_load_dword v184, v3, s[22:23]
	global_load_dword v185, v3, s[22:23] offset:2048
	s_add_u32 s22, s12, 0x1c000
	s_addc_u32 s23, s13, 0
	global_load_dword v186, v3, s[22:23]
	global_load_dword v187, v3, s[22:23] offset:2048
	s_add_u32 s22, s12, 0x1d000
	s_addc_u32 s23, s13, 0
	global_load_dword v188, v3, s[22:23]
	global_load_dword v189, v3, s[22:23] offset:2048
	s_add_u32 s22, s12, 0x1e000
	s_addc_u32 s23, s13, 0
	global_load_dword v190, v3, s[22:23]
	global_load_dword v191, v3, s[22:23] offset:2048
	s_add_u32 s22, s12, 0x1f000
	s_addc_u32 s23, s13, 0
	global_load_dword v192, v3, s[22:23]
	s_waitcnt vmcnt(47)
	v_cvt_f32_f16_e32 v11, v130
	v_sub_f32_e32 v11, 1.0, v11
	v_fma_mixlo_f16 v12, v11, v10, v130 op_sel:[0,0,1] op_sel_hi:[0,0,1]
	v_fma_mix_f32 v10, v11, v10, v130 op_sel:[0,0,1] op_sel_hi:[0,0,1]
	ds_write_b16 v4, v12 offset:0
	v_cvt_f32_f16_e32 v11, v131
	v_sub_f32_e32 v11, 1.0, v11
	v_fma_mixlo_f16 v12, v11, v10, v131 op_sel:[0,0,1] op_sel_hi:[0,0,1]
	v_fma_mix_f32 v10, v11, v10, v131 op_sel:[0,0,1] op_sel_hi:[0,0,1]
	ds_write_b16 v4, v12 offset:1024
	v_cvt_f32_f16_e32 v11, v132
	v_sub_f32_e32 v11, 1.0, v11
	v_fma_mixlo_f16 v12, v11, v10, v132 op_sel:[0,0,1] op_sel_hi:[0,0,1]
	v_fma_mix_f32 v10, v11, v10, v132 op_sel:[0,0,1] op_sel_hi:[0,0,1]
	ds_write_b16 v4, v12 offset:2048
	v_cvt_f32_f16_e32 v11, v133
	v_sub_f32_e32 v11, 1.0, v11
	v_fma_mixlo_f16 v12, v11, v10, v133 op_sel:[0,0,1] op_sel_hi:[0,0,1]
	v_fma_mix_f32 v10, v11, v10, v133 op_sel:[0,0,1] op_sel_hi:[0,0,1]
	ds_write_b16 v4, v12 offset:3072
	v_cvt_f32_f16_e32 v11, v134
	v_sub_f32_e32 v11, 1.0, v11
	v_fma_mixlo_f16 v12, v11, v10, v134 op_sel:[0,0,1] op_sel_hi:[0,0,1]
	v_fma_mix_f32 v10, v11, v10, v134 op_sel:[0,0,1] op_sel_hi:[0,0,1]
	ds_write_b16 v4, v12 offset:4096
	v_cvt_f32_f16_e32 v11, v135
	v_sub_f32_e32 v11, 1.0, v11
	v_fma_mixlo_f16 v12, v11, v10, v135 op_sel:[0,0,1] op_sel_hi:[0,0,1]
	v_fma_mix_f32 v10, v11, v10, v135 op_sel:[0,0,1] op_sel_hi:[0,0,1]
	ds_write_b16 v4, v12 offset:5120
	v_cvt_f32_f16_e32 v11, v136
	v_sub_f32_e32 v11, 1.0, v11
	v_fma_mixlo_f16 v12, v11, v10, v136 op_sel:[0,0,1] op_sel_hi:[0,0,1]
	v_fma_mix_f32 v10, v11, v10, v136 op_sel:[0,0,1] op_sel_hi:[0,0,1]
	ds_write_b16 v4, v12 offset:6144
	v_cvt_f32_f16_e32 v11, v137
	v_sub_f32_e32 v11, 1.0, v11
	v_fma_mixlo_f16 v12, v11, v10, v137 op_sel:[0,0,1] op_sel_hi:[0,0,1]
	v_fma_mix_f32 v10, v11, v10, v137 op_sel:[0,0,1] op_sel_hi:[0,0,1]
	ds_write_b16 v4, v12 offset:7168
	v_cvt_f32_f16_e32 v11, v138
	v_sub_f32_e32 v11, 1.0, v11
	v_fma_mixlo_f16 v12, v11, v10, v138 op_sel:[0,0,1] op_sel_hi:[0,0,1]
	v_fma_mix_f32 v10, v11, v10, v138 op_sel:[0,0,1] op_sel_hi:[0,0,1]
	ds_write_b16 v4, v12 offset:8192
	v_cvt_f32_f16_e32 v11, v139
	v_sub_f32_e32 v11, 1.0, v11
	v_fma_mixlo_f16 v12, v11, v10, v139 op_sel:[0,0,1] op_sel_hi:[0,0,1]
	v_fma_mix_f32 v10, v11, v10, v139 op_sel:[0,0,1] op_sel_hi:[0,0,1]
	ds_write_b16 v4, v12 offset:9216
	v_cvt_f32_f16_e32 v11, v140
	v_sub_f32_e32 v11, 1.0, v11
	v_fma_mixlo_f16 v12, v11, v10, v140 op_sel:[0,0,1] op_sel_hi:[0,0,1]
	v_fma_mix_f32 v10, v11, v10, v140 op_sel:[0,0,1] op_sel_hi:[0,0,1]
	ds_write_b16 v4, v12 offset:10240
	v_cvt_f32_f16_e32 v11, v141
	v_sub_f32_e32 v11, 1.0, v11
	v_fma_mixlo_f16 v12, v11, v10, v141 op_sel:[0,0,1] op_sel_hi:[0,0,1]
	v_fma_mix_f32 v10, v11, v10, v141 op_sel:[0,0,1] op_sel_hi:[0,0,1]
	ds_write_b16 v4, v12 offset:11264
	v_cvt_f32_f16_e32 v11, v142
	v_sub_f32_e32 v11, 1.0, v11
	v_fma_mixlo_f16 v12, v11, v10, v142 op_sel:[0,0,1] op_sel_hi:[0,0,1]
	v_fma_mix_f32 v10, v11, v10, v142 op_sel:[0,0,1] op_sel_hi:[0,0,1]
	ds_write_b16 v4, v12 offset:12288
	v_cvt_f32_f16_e32 v11, v143
	v_sub_f32_e32 v11, 1.0, v11
	v_fma_mixlo_f16 v12, v11, v10, v143 op_sel:[0,0,1] op_sel_hi:[0,0,1]
	v_fma_mix_f32 v10, v11, v10, v143 op_sel:[0,0,1] op_sel_hi:[0,0,1]
	ds_write_b16 v4, v12 offset:13312
; __device__ __forceinline__ void lru_pass2_unit(int cu, const h2* AD, const float2* LCS, const bf16* LG, bf16* MIX, lds_t* lds, int tid) {
;     ...
;     const h2* ad = AD + ((size_t)m0 * 2 + dir) * 256 + ch;
;     {
;         h2 fa[16], fb[16];
; #pragma unroll
;         for (int j = 0; j < 16; ++j) { const int r = dir == 0 ? j : 127 - j; fa[j] = ad[(size_t)r * 512]; }
; #pragma unroll 1
;         for (int r0 = 0; r0 < 128; r0 += 32) {
; #pragma unroll
;             for (int j = 0; j < 16; ++j) { const int r = dir == 0 ? r0 + 16 + j : 127 - (r0 + 16 + j); fb[j] = ad[(size_t)r * 512]; }
; #pragma unroll
;             for (int j = 0; j < 16; ++j) { const int r = dir == 0 ? r0 + j : 127 - (r0 + j); h = (1.0f - (float)fa[j][0]) * h + (float)fa[j][1]; HS[r * 512 + dir * 256 + ch] = (_Float16)h; }
;             if (r0 + 32 < 128) {
; #pragma unroll
;                 for (int j = 0; j < 16; ++j) { const int r = dir == 0 ? r0 + 32 + j : 127 - (r0 + 32 + j); fa[j] = ad[(size_t)r * 512]; } }
; #pragma unroll
;             for (int j = 0; j < 16; ++j) { const int r = dir == 0 ? r0 + 16 + j : 127 - (r0 + 16 + j); h = (1.0f - (float)fb[j][0]) * h + (float)fb[j][1]; HS[r * 512 + dir * 256 + ch] = (_Float16)h; } } }
	v_cvt_f32_f16_e32 v11, v144
	v_sub_f32_e32 v11, 1.0, v11
	v_fma_mixlo_f16 v12, v11, v10, v144 op_sel:[0,0,1] op_sel_hi:[0,0,1]
	v_fma_mix_f32 v10, v11, v10, v144 op_sel:[0,0,1] op_sel_hi:[0,0,1]
	ds_write_b16 v4, v12 offset:14336
	v_cvt_f32_f16_e32 v11, v145
	v_sub_f32_e32 v11, 1.0, v11
	v_fma_mixlo_f16 v12, v11, v10, v145 op_sel:[0,0,1] op_sel_hi:[0,0,1]
	v_fma_mix_f32 v10, v11, v10, v145 op_sel:[0,0,1] op_sel_hi:[0,0,1]
	ds_write_b16 v4, v12 offset:15360
	global_load_dword v193, v3, s[22:23] offset:2048
	s_add_u32 s22, s12, 0x20000
	s_addc_u32 s23, s13, 0
	global_load_dword v130, v3, s[22:23]
	global_load_dword v131, v3, s[22:23] offset:2048
	s_add_u32 s22, s12, 0x21000
	s_addc_u32 s23, s13, 0
	global_load_dword v132, v3, s[22:23]
	global_load_dword v133, v3, s[22:23] offset:2048
	s_add_u32 s22, s12, 0x22000
	s_addc_u32 s23, s13, 0
	global_load_dword v134, v3, s[22:23]
	global_load_dword v135, v3, s[22:23] offset:2048
	s_add_u32 s22, s12, 0x23000
	s_addc_u32 s23, s13, 0
	global_load_dword v136, v3, s[22:23]
	global_load_dword v137, v3, s[22:23] offset:2048
	s_add_u32 s22, s12, 0x24000
	s_addc_u32 s23, s13, 0
	global_load_dword v138, v3, s[22:23]
	global_load_dword v139, v3, s[22:23] offset:2048
	s_add_u32 s22, s12, 0x25000
	s_addc_u32 s23, s13, 0
	global_load_dword v140, v3, s[22:23]
	global_load_dword v141, v3, s[22:23] offset:2048
	s_add_u32 s22, s12, 0x26000
	s_addc_u32 s23, s13, 0
	global_load_dword v142, v3, s[22:23]
	global_load_dword v143, v3, s[22:23] offset:2048
	s_add_u32 s22, s12, 0x27000
	s_addc_u32 s23, s13, 0
	global_load_dword v144, v3, s[22:23]
	s_waitcnt vmcnt(47)
	v_cvt_f32_f16_e32 v11, v146
	v_sub_f32_e32 v11, 1.0, v11
	v_fma_mixlo_f16 v12, v11, v10, v146 op_sel:[0,0,1] op_sel_hi:[0,0,1]
	v_fma_mix_f32 v10, v11, v10, v146 op_sel:[0,0,1] op_sel_hi:[0,0,1]
	ds_write_b16 v4, v12 offset:16384
	v_cvt_f32_f16_e32 v11, v147
	v_sub_f32_e32 v11, 1.0, v11
	v_fma_mixlo_f16 v12, v11, v10, v147 op_sel:[0,0,1] op_sel_hi:[0,0,1]
	v_fma_mix_f32 v10, v11, v10, v147 op_sel:[0,0,1] op_sel_hi:[0,0,1]
	ds_write_b16 v4, v12 offset:17408
	v_cvt_f32_f16_e32 v11, v148
	v_sub_f32_e32 v11, 1.0, v11
	v_fma_mixlo_f16 v12, v11, v10, v148 op_sel:[0,0,1] op_sel_hi:[0,0,1]
	v_fma_mix_f32 v10, v11, v10, v148 op_sel:[0,0,1] op_sel_hi:[0,0,1]
	ds_write_b16 v4, v12 offset:18432
	v_cvt_f32_f16_e32 v11, v149
	v_sub_f32_e32 v11, 1.0, v11
	v_fma_mixlo_f16 v12, v11, v10, v149 op_sel:[0,0,1] op_sel_hi:[0,0,1]
	v_fma_mix_f32 v10, v11, v10, v149 op_sel:[0,0,1] op_sel_hi:[0,0,1]
	ds_write_b16 v4, v12 offset:19456
	v_cvt_f32_f16_e32 v11, v150
	v_sub_f32_e32 v11, 1.0, v11
	v_fma_mixlo_f16 v12, v11, v10, v150 op_sel:[0,0,1] op_sel_hi:[0,0,1]
	v_fma_mix_f32 v10, v11, v10, v150 op_sel:[0,0,1] op_sel_hi:[0,0,1]
	ds_write_b16 v4, v12 offset:20480
	v_cvt_f32_f16_e32 v11, v151
	v_sub_f32_e32 v11, 1.0, v11
	v_fma_mixlo_f16 v12, v11, v10, v151 op_sel:[0,0,1] op_sel_hi:[0,0,1]
	v_fma_mix_f32 v10, v11, v10, v151 op_sel:[0,0,1] op_sel_hi:[0,0,1]
	ds_write_b16 v4, v12 offset:21504
	v_cvt_f32_f16_e32 v11, v152
	v_sub_f32_e32 v11, 1.0, v11
	v_fma_mixlo_f16 v12, v11, v10, v152 op_sel:[0,0,1] op_sel_hi:[0,0,1]
	v_fma_mix_f32 v10, v11, v10, v152 op_sel:[0,0,1] op_sel_hi:[0,0,1]
	ds_write_b16 v4, v12 offset:22528
	v_cvt_f32_f16_e32 v11, v153
	v_sub_f32_e32 v11, 1.0, v11
	v_fma_mixlo_f16 v12, v11, v10, v153 op_sel:[0,0,1] op_sel_hi:[0,0,1]
	v_fma_mix_f32 v10, v11, v10, v153 op_sel:[0,0,1] op_sel_hi:[0,0,1]
	ds_write_b16 v4, v12 offset:23552
	v_cvt_f32_f16_e32 v11, v154
	v_sub_f32_e32 v11, 1.0, v11
	v_fma_mixlo_f16 v12, v11, v10, v154 op_sel:[0,0,1] op_sel_hi:[0,0,1]
	v_fma_mix_f32 v10, v11, v10, v154 op_sel:[0,0,1] op_sel_hi:[0,0,1]
	ds_write_b16 v4, v12 offset:24576
	v_cvt_f32_f16_e32 v11, v155
	v_sub_f32_e32 v11, 1.0, v11
	v_fma_mixlo_f16 v12, v11, v10, v155 op_sel:[0,0,1] op_sel_hi:[0,0,1]
	v_fma_mix_f32 v10, v11, v10, v155 op_sel:[0,0,1] op_sel_hi:[0,0,1]
	ds_write_b16 v4, v12 offset:25600
	v_cvt_f32_f16_e32 v11, v156
	v_sub_f32_e32 v11, 1.0, v11
	v_fma_mixlo_f16 v12, v11, v10, v156 op_sel:[0,0,1] op_sel_hi:[0,0,1]
	v_fma_mix_f32 v10, v11, v10, v156 op_sel:[0,0,1] op_sel_hi:[0,0,1]
	ds_write_b16 v4, v12 offset:26624
	v_cvt_f32_f16_e32 v11, v157
	v_sub_f32_e32 v11, 1.0, v11
	v_fma_mixlo_f16 v12, v11, v10, v157 op_sel:[0,0,1] op_sel_hi:[0,0,1]
	v_fma_mix_f32 v10, v11, v10, v157 op_sel:[0,0,1] op_sel_hi:[0,0,1]
	ds_write_b16 v4, v12 offset:27648
	v_cvt_f32_f16_e32 v11, v158
	v_sub_f32_e32 v11, 1.0, v11
	v_fma_mixlo_f16 v12, v11, v10, v158 op_sel:[0,0,1] op_sel_hi:[0,0,1]
	v_fma_mix_f32 v10, v11, v10, v158 op_sel:[0,0,1] op_sel_hi:[0,0,1]
	ds_write_b16 v4, v12 offset:28672
	v_cvt_f32_f16_e32 v11, v159
	v_sub_f32_e32 v11, 1.0, v11
	v_fma_mixlo_f16 v12, v11, v10, v159 op_sel:[0,0,1] op_sel_hi:[0,0,1]
	v_fma_mix_f32 v10, v11, v10, v159 op_sel:[0,0,1] op_sel_hi:[0,0,1]
	ds_write_b16 v4, v12 offset:29696
	v_cvt_f32_f16_e32 v11, v160
	v_sub_f32_e32 v11, 1.0, v11
	v_fma_mixlo_f16 v12, v11, v10, v160 op_sel:[0,0,1] op_sel_hi:[0,0,1]
	v_fma_mix_f32 v10, v11, v10, v160 op_sel:[0,0,1] op_sel_hi:[0,0,1]
	ds_write_b16 v4, v12 offset:30720
	v_cvt_f32_f16_e32 v11, v161
	v_sub_f32_e32 v11, 1.0, v11
	v_fma_mixlo_f16 v12, v11, v10, v161 op_sel:[0,0,1] op_sel_hi:[0,0,1]
	v_fma_mix_f32 v10, v11, v10, v161 op_sel:[0,0,1] op_sel_hi:[0,0,1]
	ds_write_b16 v4, v12 offset:31744
	global_load_dword v145, v3, s[22:23] offset:2048
	s_add_u32 s22, s12, 0x28000
	s_addc_u32 s23, s13, 0
	global_load_dword v146, v3, s[22:23]
	global_load_dword v147, v3, s[22:23] offset:2048
	s_add_u32 s22, s12, 0x29000
	s_addc_u32 s23, s13, 0
	global_load_dword v148, v3, s[22:23]
	global_load_dword v149, v3, s[22:23] offset:2048
	s_add_u32 s22, s12, 0x2a000
	s_addc_u32 s23, s13, 0
	global_load_dword v150, v3, s[22:23]
	global_load_dword v151, v3, s[22:23] offset:2048
	s_add_u32 s22, s12, 0x2b000
	s_addc_u32 s23, s13, 0
	global_load_dword v152, v3, s[22:23]
	global_load_dword v153, v3, s[22:23] offset:2048
	s_add_u32 s22, s12, 0x2c000
	s_addc_u32 s23, s13, 0
	global_load_dword v154, v3, s[22:23]
	global_load_dword v155, v3, s[22:23] offset:2048
	s_add_u32 s22, s12, 0x2d000
	s_addc_u32 s23, s13, 0
	global_load_dword v156, v3, s[22:23]
	global_load_dword v157, v3, s[22:23] offset:2048
	s_add_u32 s22, s12, 0x2e000
	s_addc_u32 s23, s13, 0
	global_load_dword v158, v3, s[22:23]
	global_load_dword v159, v3, s[22:23] offset:2048
	s_add_u32 s22, s12, 0x2f000
	s_addc_u32 s23, s13, 0
	global_load_dword v160, v3, s[22:23]
	s_waitcnt vmcnt(47)
; __device__ __forceinline__ void lru_pass2_unit(int cu, const h2* AD, const float2* LCS, const bf16* LG, bf16* MIX, lds_t* lds, int tid) {
;     ...
;     const h2* ad = AD + ((size_t)m0 * 2 + dir) * 256 + ch;
;     {
;         h2 fa[16], fb[16];
; #pragma unroll
;         for (int j = 0; j < 16; ++j) { const int r = dir == 0 ? j : 127 - j; fa[j] = ad[(size_t)r * 512]; }
; #pragma unroll 1
;         for (int r0 = 0; r0 < 128; r0 += 32) {
; #pragma unroll
;             for (int j = 0; j < 16; ++j) { const int r = dir == 0 ? r0 + 16 + j : 127 - (r0 + 16 + j); fb[j] = ad[(size_t)r * 512]; }
; #pragma unroll
;             for (int j = 0; j < 16; ++j) { const int r = dir == 0 ? r0 + j : 127 - (r0 + j); h = (1.0f - (float)fa[j][0]) * h + (float)fa[j][1]; HS[r * 512 + dir * 256 + ch] = (_Float16)h; }
;             if (r0 + 32 < 128) {
; #pragma unroll
;                 for (int j = 0; j < 16; ++j) { const int r = dir == 0 ? r0 + 32 + j : 127 - (r0 + 32 + j); fa[j] = ad[(size_t)r * 512]; } }
; #pragma unroll
;             for (int j = 0; j < 16; ++j) { const int r = dir == 0 ? r0 + 16 + j : 127 - (r0 + 16 + j); h = (1.0f - (float)fb[j][0]) * h + (float)fb[j][1]; HS[r * 512 + dir * 256 + ch] = (_Float16)h; } } }
	v_cvt_f32_f16_e32 v11, v162
	v_sub_f32_e32 v11, 1.0, v11
	v_fma_mixlo_f16 v12, v11, v10, v162 op_sel:[0,0,1] op_sel_hi:[0,0,1]
	v_fma_mix_f32 v10, v11, v10, v162 op_sel:[0,0,1] op_sel_hi:[0,0,1]
	ds_write_b16 v4, v12 offset:32768
	v_cvt_f32_f16_e32 v11, v163
	v_sub_f32_e32 v11, 1.0, v11
	v_fma_mixlo_f16 v12, v11, v10, v163 op_sel:[0,0,1] op_sel_hi:[0,0,1]
	v_fma_mix_f32 v10, v11, v10, v163 op_sel:[0,0,1] op_sel_hi:[0,0,1]
	ds_write_b16 v4, v12 offset:33792
	v_cvt_f32_f16_e32 v11, v164
	v_sub_f32_e32 v11, 1.0, v11
	v_fma_mixlo_f16 v12, v11, v10, v164 op_sel:[0,0,1] op_sel_hi:[0,0,1]
	v_fma_mix_f32 v10, v11, v10, v164 op_sel:[0,0,1] op_sel_hi:[0,0,1]
	ds_write_b16 v4, v12 offset:34816
	v_cvt_f32_f16_e32 v11, v165
	v_sub_f32_e32 v11, 1.0, v11
	v_fma_mixlo_f16 v12, v11, v10, v165 op_sel:[0,0,1] op_sel_hi:[0,0,1]
	v_fma_mix_f32 v10, v11, v10, v165 op_sel:[0,0,1] op_sel_hi:[0,0,1]
	ds_write_b16 v4, v12 offset:35840
	v_cvt_f32_f16_e32 v11, v166
	v_sub_f32_e32 v11, 1.0, v11
	v_fma_mixlo_f16 v12, v11, v10, v166 op_sel:[0,0,1] op_sel_hi:[0,0,1]
	v_fma_mix_f32 v10, v11, v10, v166 op_sel:[0,0,1] op_sel_hi:[0,0,1]
	ds_write_b16 v4, v12 offset:36864
	v_cvt_f32_f16_e32 v11, v167
	v_sub_f32_e32 v11, 1.0, v11
	v_fma_mixlo_f16 v12, v11, v10, v167 op_sel:[0,0,1] op_sel_hi:[0,0,1]
	v_fma_mix_f32 v10, v11, v10, v167 op_sel:[0,0,1] op_sel_hi:[0,0,1]
	ds_write_b16 v4, v12 offset:37888
	v_cvt_f32_f16_e32 v11, v168
	v_sub_f32_e32 v11, 1.0, v11
	v_fma_mixlo_f16 v12, v11, v10, v168 op_sel:[0,0,1] op_sel_hi:[0,0,1]
	v_fma_mix_f32 v10, v11, v10, v168 op_sel:[0,0,1] op_sel_hi:[0,0,1]
	ds_write_b16 v4, v12 offset:38912
	v_cvt_f32_f16_e32 v11, v169
	v_sub_f32_e32 v11, 1.0, v11
	v_fma_mixlo_f16 v12, v11, v10, v169 op_sel:[0,0,1] op_sel_hi:[0,0,1]
	v_fma_mix_f32 v10, v11, v10, v169 op_sel:[0,0,1] op_sel_hi:[0,0,1]
	ds_write_b16 v4, v12 offset:39936
	v_cvt_f32_f16_e32 v11, v170
	v_sub_f32_e32 v11, 1.0, v11
	v_fma_mixlo_f16 v12, v11, v10, v170 op_sel:[0,0,1] op_sel_hi:[0,0,1]
	v_fma_mix_f32 v10, v11, v10, v170 op_sel:[0,0,1] op_sel_hi:[0,0,1]
	ds_write_b16 v4, v12 offset:40960
	v_cvt_f32_f16_e32 v11, v171
	v_sub_f32_e32 v11, 1.0, v11
	v_fma_mixlo_f16 v12, v11, v10, v171 op_sel:[0,0,1] op_sel_hi:[0,0,1]
	v_fma_mix_f32 v10, v11, v10, v171 op_sel:[0,0,1] op_sel_hi:[0,0,1]
	ds_write_b16 v4, v12 offset:41984
	v_cvt_f32_f16_e32 v11, v172
	v_sub_f32_e32 v11, 1.0, v11
	v_fma_mixlo_f16 v12, v11, v10, v172 op_sel:[0,0,1] op_sel_hi:[0,0,1]
	v_fma_mix_f32 v10, v11, v10, v172 op_sel:[0,0,1] op_sel_hi:[0,0,1]
	ds_write_b16 v4, v12 offset:43008
	v_cvt_f32_f16_e32 v11, v173
	v_sub_f32_e32 v11, 1.0, v11
	v_fma_mixlo_f16 v12, v11, v10, v173 op_sel:[0,0,1] op_sel_hi:[0,0,1]
	v_fma_mix_f32 v10, v11, v10, v173 op_sel:[0,0,1] op_sel_hi:[0,0,1]
	ds_write_b16 v4, v12 offset:44032
	v_cvt_f32_f16_e32 v11, v174
	v_sub_f32_e32 v11, 1.0, v11
	v_fma_mixlo_f16 v12, v11, v10, v174 op_sel:[0,0,1] op_sel_hi:[0,0,1]
	v_fma_mix_f32 v10, v11, v10, v174 op_sel:[0,0,1] op_sel_hi:[0,0,1]
	ds_write_b16 v4, v12 offset:45056
	v_cvt_f32_f16_e32 v11, v175
	v_sub_f32_e32 v11, 1.0, v11
	v_fma_mixlo_f16 v12, v11, v10, v175 op_sel:[0,0,1] op_sel_hi:[0,0,1]
	v_fma_mix_f32 v10, v11, v10, v175 op_sel:[0,0,1] op_sel_hi:[0,0,1]
	ds_write_b16 v4, v12 offset:46080
	v_cvt_f32_f16_e32 v11, v176
	v_sub_f32_e32 v11, 1.0, v11
	v_fma_mixlo_f16 v12, v11, v10, v176 op_sel:[0,0,1] op_sel_hi:[0,0,1]
	v_fma_mix_f32 v10, v11, v10, v176 op_sel:[0,0,1] op_sel_hi:[0,0,1]
	ds_write_b16 v4, v12 offset:47104
	v_cvt_f32_f16_e32 v11, v177
	v_sub_f32_e32 v11, 1.0, v11
	v_fma_mixlo_f16 v12, v11, v10, v177 op_sel:[0,0,1] op_sel_hi:[0,0,1]
	v_fma_mix_f32 v10, v11, v10, v177 op_sel:[0,0,1] op_sel_hi:[0,0,1]
	ds_write_b16 v4, v12 offset:48128
	global_load_dword v161, v3, s[22:23] offset:2048
	s_add_u32 s22, s12, 0x30000
	s_addc_u32 s23, s13, 0
	global_load_dword v162, v3, s[22:23]
	global_load_dword v163, v3, s[22:23] offset:2048
	s_add_u32 s22, s12, 0x31000
	s_addc_u32 s23, s13, 0
	global_load_dword v164, v3, s[22:23]
	global_load_dword v165, v3, s[22:23] offset:2048
	s_add_u32 s22, s12, 0x32000
	s_addc_u32 s23, s13, 0
	global_load_dword v166, v3, s[22:23]
	global_load_dword v167, v3, s[22:23] offset:2048
	s_add_u32 s22, s12, 0x33000
	s_addc_u32 s23, s13, 0
	global_load_dword v168, v3, s[22:23]
	global_load_dword v169, v3, s[22:23] offset:2048
	s_add_u32 s22, s12, 0x34000
	s_addc_u32 s23, s13, 0
	global_load_dword v170, v3, s[22:23]
	global_load_dword v171, v3, s[22:23] offset:2048
	s_add_u32 s22, s12, 0x35000
	s_addc_u32 s23, s13, 0
	global_load_dword v172, v3, s[22:23]
	global_load_dword v173, v3, s[22:23] offset:2048
	s_add_u32 s22, s12, 0x36000
	s_addc_u32 s23, s13, 0
	global_load_dword v174, v3, s[22:23]
	global_load_dword v175, v3, s[22:23] offset:2048
	s_add_u32 s22, s12, 0x37000
	s_addc_u32 s23, s13, 0
	global_load_dword v176, v3, s[22:23]
	s_waitcnt vmcnt(47)
; __device__ __forceinline__ void lru_pass2_unit(int cu, const h2* AD, const float2* LCS, const bf16* LG, bf16* MIX, lds_t* lds, int tid) {
;     ...
;     const h2* ad = AD + ((size_t)m0 * 2 + dir) * 256 + ch;
;     {
;         h2 fa[16], fb[16];
; #pragma unroll
;         for (int j = 0; j < 16; ++j) { const int r = dir == 0 ? j : 127 - j; fa[j] = ad[(size_t)r * 512]; }
; #pragma unroll 1
;         for (int r0 = 0; r0 < 128; r0 += 32) {
; #pragma unroll
;             for (int j = 0; j < 16; ++j) { const int r = dir == 0 ? r0 + 16 + j : 127 - (r0 + 16 + j); fb[j] = ad[(size_t)r * 512]; }
; #pragma unroll
;             for (int j = 0; j < 16; ++j) { const int r = dir == 0 ? r0 + j : 127 - (r0 + j); h = (1.0f - (float)fa[j][0]) * h + (float)fa[j][1]; HS[r * 512 + dir * 256 + ch] = (_Float16)h; }
;             if (r0 + 32 < 128) {
; #pragma unroll
;                 for (int j = 0; j < 16; ++j) { const int r = dir == 0 ? r0 + 32 + j : 127 - (r0 + 32 + j); fa[j] = ad[(size_t)r * 512]; } }
; #pragma unroll
;             for (int j = 0; j < 16; ++j) { const int r = dir == 0 ? r0 + 16 + j : 127 - (r0 + 16 + j); h = (1.0f - (float)fb[j][0]) * h + (float)fb[j][1]; HS[r * 512 + dir * 256 + ch] = (_Float16)h; } } }
	v_cvt_f32_f16_e32 v11, v178
	v_sub_f32_e32 v11, 1.0, v11
	v_fma_mixlo_f16 v12, v11, v10, v178 op_sel:[0,0,1] op_sel_hi:[0,0,1]
	v_fma_mix_f32 v10, v11, v10, v178 op_sel:[0,0,1] op_sel_hi:[0,0,1]
	ds_write_b16 v4, v12 offset:49152
	v_cvt_f32_f16_e32 v11, v179
	v_sub_f32_e32 v11, 1.0, v11
	v_fma_mixlo_f16 v12, v11, v10, v179 op_sel:[0,0,1] op_sel_hi:[0,0,1]
	v_fma_mix_f32 v10, v11, v10, v179 op_sel:[0,0,1] op_sel_hi:[0,0,1]
	ds_write_b16 v4, v12 offset:50176
	v_cvt_f32_f16_e32 v11, v180
	v_sub_f32_e32 v11, 1.0, v11
	v_fma_mixlo_f16 v12, v11, v10, v180 op_sel:[0,0,1] op_sel_hi:[0,0,1]
	v_fma_mix_f32 v10, v11, v10, v180 op_sel:[0,0,1] op_sel_hi:[0,0,1]
	ds_write_b16 v4, v12 offset:51200
	v_cvt_f32_f16_e32 v11, v181
	v_sub_f32_e32 v11, 1.0, v11
	v_fma_mixlo_f16 v12, v11, v10, v181 op_sel:[0,0,1] op_sel_hi:[0,0,1]
	v_fma_mix_f32 v10, v11, v10, v181 op_sel:[0,0,1] op_sel_hi:[0,0,1]
	ds_write_b16 v4, v12 offset:52224
	v_cvt_f32_f16_e32 v11, v182
	v_sub_f32_e32 v11, 1.0, v11
	v_fma_mixlo_f16 v12, v11, v10, v182 op_sel:[0,0,1] op_sel_hi:[0,0,1]
	v_fma_mix_f32 v10, v11, v10, v182 op_sel:[0,0,1] op_sel_hi:[0,0,1]
	ds_write_b16 v4, v12 offset:53248
	v_cvt_f32_f16_e32 v11, v183
	v_sub_f32_e32 v11, 1.0, v11
	v_fma_mixlo_f16 v12, v11, v10, v183 op_sel:[0,0,1] op_sel_hi:[0,0,1]
	v_fma_mix_f32 v10, v11, v10, v183 op_sel:[0,0,1] op_sel_hi:[0,0,1]
	ds_write_b16 v4, v12 offset:54272
	v_cvt_f32_f16_e32 v11, v184
	v_sub_f32_e32 v11, 1.0, v11
	v_fma_mixlo_f16 v12, v11, v10, v184 op_sel:[0,0,1] op_sel_hi:[0,0,1]
	v_fma_mix_f32 v10, v11, v10, v184 op_sel:[0,0,1] op_sel_hi:[0,0,1]
	ds_write_b16 v4, v12 offset:55296
	v_cvt_f32_f16_e32 v11, v185
	v_sub_f32_e32 v11, 1.0, v11
	v_fma_mixlo_f16 v12, v11, v10, v185 op_sel:[0,0,1] op_sel_hi:[0,0,1]
	v_fma_mix_f32 v10, v11, v10, v185 op_sel:[0,0,1] op_sel_hi:[0,0,1]
	ds_write_b16 v4, v12 offset:56320
	v_cvt_f32_f16_e32 v11, v186
	v_sub_f32_e32 v11, 1.0, v11
	v_fma_mixlo_f16 v12, v11, v10, v186 op_sel:[0,0,1] op_sel_hi:[0,0,1]
	v_fma_mix_f32 v10, v11, v10, v186 op_sel:[0,0,1] op_sel_hi:[0,0,1]
	ds_write_b16 v4, v12 offset:57344
	v_cvt_f32_f16_e32 v11, v187
	v_sub_f32_e32 v11, 1.0, v11
	v_fma_mixlo_f16 v12, v11, v10, v187 op_sel:[0,0,1] op_sel_hi:[0,0,1]
	v_fma_mix_f32 v10, v11, v10, v187 op_sel:[0,0,1] op_sel_hi:[0,0,1]
	ds_write_b16 v4, v12 offset:58368
	v_cvt_f32_f16_e32 v11, v188
	v_sub_f32_e32 v11, 1.0, v11
	v_fma_mixlo_f16 v12, v11, v10, v188 op_sel:[0,0,1] op_sel_hi:[0,0,1]
	v_fma_mix_f32 v10, v11, v10, v188 op_sel:[0,0,1] op_sel_hi:[0,0,1]
	ds_write_b16 v4, v12 offset:59392
	v_cvt_f32_f16_e32 v11, v189
	v_sub_f32_e32 v11, 1.0, v11
	v_fma_mixlo_f16 v12, v11, v10, v189 op_sel:[0,0,1] op_sel_hi:[0,0,1]
	v_fma_mix_f32 v10, v11, v10, v189 op_sel:[0,0,1] op_sel_hi:[0,0,1]
	ds_write_b16 v4, v12 offset:60416
	v_cvt_f32_f16_e32 v11, v190
	v_sub_f32_e32 v11, 1.0, v11
	v_fma_mixlo_f16 v12, v11, v10, v190 op_sel:[0,0,1] op_sel_hi:[0,0,1]
	v_fma_mix_f32 v10, v11, v10, v190 op_sel:[0,0,1] op_sel_hi:[0,0,1]
	ds_write_b16 v4, v12 offset:61440
	v_cvt_f32_f16_e32 v11, v191
	v_sub_f32_e32 v11, 1.0, v11
	v_fma_mixlo_f16 v12, v11, v10, v191 op_sel:[0,0,1] op_sel_hi:[0,0,1]
	v_fma_mix_f32 v10, v11, v10, v191 op_sel:[0,0,1] op_sel_hi:[0,0,1]
	ds_write_b16 v4, v12 offset:62464
	v_cvt_f32_f16_e32 v11, v192
	v_sub_f32_e32 v11, 1.0, v11
	v_fma_mixlo_f16 v12, v11, v10, v192 op_sel:[0,0,1] op_sel_hi:[0,0,1]
	v_fma_mix_f32 v10, v11, v10, v192 op_sel:[0,0,1] op_sel_hi:[0,0,1]
	ds_write_b16 v4, v12 offset:63488
	v_cvt_f32_f16_e32 v11, v193
	v_sub_f32_e32 v11, 1.0, v11
	v_fma_mixlo_f16 v12, v11, v10, v193 op_sel:[0,0,1] op_sel_hi:[0,0,1]
	v_fma_mix_f32 v10, v11, v10, v193 op_sel:[0,0,1] op_sel_hi:[0,0,1]
	ds_write_b16 v4, v12 offset:64512
	global_load_dword v177, v3, s[22:23] offset:2048
	s_add_u32 s22, s12, 0x38000
	s_addc_u32 s23, s13, 0
	global_load_dword v178, v3, s[22:23]
	global_load_dword v179, v3, s[22:23] offset:2048
	s_add_u32 s22, s12, 0x39000
	s_addc_u32 s23, s13, 0
	global_load_dword v180, v3, s[22:23]
	global_load_dword v181, v3, s[22:23] offset:2048
	s_add_u32 s22, s12, 0x3a000
	s_addc_u32 s23, s13, 0
	global_load_dword v182, v3, s[22:23]
	global_load_dword v183, v3, s[22:23] offset:2048
	s_add_u32 s22, s12, 0x3b000
	s_addc_u32 s23, s13, 0
	global_load_dword v184, v3, s[22:23]
	global_load_dword v185, v3, s[22:23] offset:2048
	s_add_u32 s22, s12, 0x3c000
	s_addc_u32 s23, s13, 0
	global_load_dword v186, v3, s[22:23]
	global_load_dword v187, v3, s[22:23] offset:2048
	s_add_u32 s22, s12, 0x3d000
	s_addc_u32 s23, s13, 0
	global_load_dword v188, v3, s[22:23]
	global_load_dword v189, v3, s[22:23] offset:2048
	s_add_u32 s22, s12, 0x3e000
	s_addc_u32 s23, s13, 0
	global_load_dword v190, v3, s[22:23]
	global_load_dword v191, v3, s[22:23] offset:2048
	s_add_u32 s22, s12, 0x3f000
	s_addc_u32 s23, s13, 0
	global_load_dword v192, v3, s[22:23]
	s_waitcnt vmcnt(47)
; #define LAS __attribute__((address_space(3)))
; __device__ __forceinline__ void lru_pass2_unit(int cu, const h2* AD, const float2* LCS, const bf16* LG, bf16* MIX, lds_t* lds, int tid) {
;     ...
;         for (int r0 = 0; r0 < 128; r0 += 32) {
; #pragma unroll
;             for (int j = 0; j < 16; ++j) { const int r = dir == 0 ? r0 + 16 + j : 127 - (r0 + 16 + j); fb[j] = ad[(size_t)r * 512]; }
; #pragma unroll
;             for (int j = 0; j < 16; ++j) { const int r = dir == 0 ? r0 + j : 127 - (r0 + j); h = (1.0f - (float)fa[j][0]) * h + (float)fa[j][1]; HS[r * 512 + dir * 256 + ch] = (_Float16)h; }
;             if (r0 + 32 < 128) {
; #pragma unroll
;                 for (int j = 0; j < 16; ++j) { const int r = dir == 0 ? r0 + 32 + j : 127 - (r0 + 32 + j); fa[j] = ad[(size_t)r * 512]; } }
; #pragma unroll
;             for (int j = 0; j < 16; ++j) { const int r = dir == 0 ? r0 + 16 + j : 127 - (r0 + 16 + j); h = (1.0f - (float)fb[j][0]) * h + (float)fb[j][1]; HS[r * 512 + dir * 256 + ch] = (_Float16)h; } } }
;     __syncthreads();
;     { typedef _Float16 h8 __attribute__((ext_vector_type(8))); const int c8 = (tid & 31) * 8;
; #pragma unroll 4
;         for (int i = 0; i < 8; ++i) { const int r = (tid >> 5) + 16 * i; const h8 hf = *(const LAS h8*)(HS + r * 512 + c8), hb = *(const LAS h8*)(HS + r * 512 + 256 + c8);
;             const v4u g = *(const v4u*)(LG + (size_t)(m0 + r) * 256 + c8); v4u o;
	v_cvt_f32_f16_e32 v11, v130
	v_sub_f32_e32 v11, 1.0, v11
	v_fma_mixlo_f16 v12, v11, v10, v130 op_sel:[0,0,1] op_sel_hi:[0,0,1]
	v_fma_mix_f32 v10, v11, v10, v130 op_sel:[0,0,1] op_sel_hi:[0,0,1]
	ds_write_b16 v5, v12 offset:0
	v_cvt_f32_f16_e32 v11, v131
	v_sub_f32_e32 v11, 1.0, v11
	v_fma_mixlo_f16 v12, v11, v10, v131 op_sel:[0,0,1] op_sel_hi:[0,0,1]
	v_fma_mix_f32 v10, v11, v10, v131 op_sel:[0,0,1] op_sel_hi:[0,0,1]
	ds_write_b16 v5, v12 offset:1024
	v_cvt_f32_f16_e32 v11, v132
	v_sub_f32_e32 v11, 1.0, v11
	v_fma_mixlo_f16 v12, v11, v10, v132 op_sel:[0,0,1] op_sel_hi:[0,0,1]
	v_fma_mix_f32 v10, v11, v10, v132 op_sel:[0,0,1] op_sel_hi:[0,0,1]
	ds_write_b16 v5, v12 offset:2048
	v_cvt_f32_f16_e32 v11, v133
	v_sub_f32_e32 v11, 1.0, v11
	v_fma_mixlo_f16 v12, v11, v10, v133 op_sel:[0,0,1] op_sel_hi:[0,0,1]
	v_fma_mix_f32 v10, v11, v10, v133 op_sel:[0,0,1] op_sel_hi:[0,0,1]
	ds_write_b16 v5, v12 offset:3072
	v_cvt_f32_f16_e32 v11, v134
	v_sub_f32_e32 v11, 1.0, v11
	v_fma_mixlo_f16 v12, v11, v10, v134 op_sel:[0,0,1] op_sel_hi:[0,0,1]
	v_fma_mix_f32 v10, v11, v10, v134 op_sel:[0,0,1] op_sel_hi:[0,0,1]
	ds_write_b16 v5, v12 offset:4096
	v_cvt_f32_f16_e32 v11, v135
	v_sub_f32_e32 v11, 1.0, v11
	v_fma_mixlo_f16 v12, v11, v10, v135 op_sel:[0,0,1] op_sel_hi:[0,0,1]
	v_fma_mix_f32 v10, v11, v10, v135 op_sel:[0,0,1] op_sel_hi:[0,0,1]
	ds_write_b16 v5, v12 offset:5120
	v_cvt_f32_f16_e32 v11, v136
	v_sub_f32_e32 v11, 1.0, v11
	v_fma_mixlo_f16 v12, v11, v10, v136 op_sel:[0,0,1] op_sel_hi:[0,0,1]
	v_fma_mix_f32 v10, v11, v10, v136 op_sel:[0,0,1] op_sel_hi:[0,0,1]
	ds_write_b16 v5, v12 offset:6144
	v_cvt_f32_f16_e32 v11, v137
	v_sub_f32_e32 v11, 1.0, v11
	v_fma_mixlo_f16 v12, v11, v10, v137 op_sel:[0,0,1] op_sel_hi:[0,0,1]
	v_fma_mix_f32 v10, v11, v10, v137 op_sel:[0,0,1] op_sel_hi:[0,0,1]
	ds_write_b16 v5, v12 offset:7168
	v_cvt_f32_f16_e32 v11, v138
	v_sub_f32_e32 v11, 1.0, v11
	v_fma_mixlo_f16 v12, v11, v10, v138 op_sel:[0,0,1] op_sel_hi:[0,0,1]
	v_fma_mix_f32 v10, v11, v10, v138 op_sel:[0,0,1] op_sel_hi:[0,0,1]
	ds_write_b16 v5, v12 offset:8192
	v_cvt_f32_f16_e32 v11, v139
	v_sub_f32_e32 v11, 1.0, v11
	v_fma_mixlo_f16 v12, v11, v10, v139 op_sel:[0,0,1] op_sel_hi:[0,0,1]
	v_fma_mix_f32 v10, v11, v10, v139 op_sel:[0,0,1] op_sel_hi:[0,0,1]
	ds_write_b16 v5, v12 offset:9216
	v_cvt_f32_f16_e32 v11, v140
	v_sub_f32_e32 v11, 1.0, v11
	v_fma_mixlo_f16 v12, v11, v10, v140 op_sel:[0,0,1] op_sel_hi:[0,0,1]
	v_fma_mix_f32 v10, v11, v10, v140 op_sel:[0,0,1] op_sel_hi:[0,0,1]
	ds_write_b16 v5, v12 offset:10240
	v_cvt_f32_f16_e32 v11, v141
	v_sub_f32_e32 v11, 1.0, v11
	v_fma_mixlo_f16 v12, v11, v10, v141 op_sel:[0,0,1] op_sel_hi:[0,0,1]
	v_fma_mix_f32 v10, v11, v10, v141 op_sel:[0,0,1] op_sel_hi:[0,0,1]
	ds_write_b16 v5, v12 offset:11264
	v_cvt_f32_f16_e32 v11, v142
	v_sub_f32_e32 v11, 1.0, v11
	v_fma_mixlo_f16 v12, v11, v10, v142 op_sel:[0,0,1] op_sel_hi:[0,0,1]
	v_fma_mix_f32 v10, v11, v10, v142 op_sel:[0,0,1] op_sel_hi:[0,0,1]
	ds_write_b16 v5, v12 offset:12288
	v_cvt_f32_f16_e32 v11, v143
	v_sub_f32_e32 v11, 1.0, v11
	v_fma_mixlo_f16 v12, v11, v10, v143 op_sel:[0,0,1] op_sel_hi:[0,0,1]
	v_fma_mix_f32 v10, v11, v10, v143 op_sel:[0,0,1] op_sel_hi:[0,0,1]
	ds_write_b16 v5, v12 offset:13312
	v_cvt_f32_f16_e32 v11, v144
	v_sub_f32_e32 v11, 1.0, v11
	v_fma_mixlo_f16 v12, v11, v10, v144 op_sel:[0,0,1] op_sel_hi:[0,0,1]
	v_fma_mix_f32 v10, v11, v10, v144 op_sel:[0,0,1] op_sel_hi:[0,0,1]
	ds_write_b16 v5, v12 offset:14336
	v_cvt_f32_f16_e32 v11, v145
	v_sub_f32_e32 v11, 1.0, v11
	v_fma_mixlo_f16 v12, v11, v10, v145 op_sel:[0,0,1] op_sel_hi:[0,0,1]
	v_fma_mix_f32 v10, v11, v10, v145 op_sel:[0,0,1] op_sel_hi:[0,0,1]
	ds_write_b16 v5, v12 offset:15360
	global_load_dword v193, v3, s[22:23] offset:2048
	s_mov_b32 s20, s14
	s_mov_b32 s21, s15
	global_load_dwordx4 v[86:89], v8, s[20:21]
	s_add_u32 s20, s20, 0x2000
	s_addc_u32 s21, s21, 0
	global_load_dwordx4 v[90:93], v8, s[20:21]
	s_add_u32 s20, s20, 0x2000
	s_addc_u32 s21, s21, 0
	global_load_dwordx4 v[94:97], v8, s[20:21]
	s_add_u32 s20, s20, 0x2000
	s_addc_u32 s21, s21, 0
	global_load_dwordx4 v[98:101], v8, s[20:21]
	s_add_u32 s20, s20, 0x2000
	s_addc_u32 s21, s21, 0
	global_load_dwordx4 v[102:105], v8, s[20:21]
	s_add_u32 s20, s20, 0x2000
	s_addc_u32 s21, s21, 0
	global_load_dwordx4 v[106:109], v8, s[20:21]
	s_add_u32 s20, s20, 0x2000
	s_addc_u32 s21, s21, 0
	global_load_dwordx4 v[110:113], v8, s[20:21]
	s_add_u32 s20, s20, 0x2000
	s_addc_u32 s21, s21, 0
	global_load_dwordx4 v[226:229], v8, s[20:21]
	s_waitcnt vmcnt(40)
; __device__ __forceinline__ void lru_pass2_unit(int cu, const h2* AD, const float2* LCS, const bf16* LG, bf16* MIX, lds_t* lds, int tid) {
;     ...
;         for (int r0 = 0; r0 < 128; r0 += 32) {
; #pragma unroll
;             for (int j = 0; j < 16; ++j) { const int r = dir == 0 ? r0 + 16 + j : 127 - (r0 + 16 + j); fb[j] = ad[(size_t)r * 512]; }
; #pragma unroll
;             for (int j = 0; j < 16; ++j) { const int r = dir == 0 ? r0 + j : 127 - (r0 + j); h = (1.0f - (float)fa[j][0]) * h + (float)fa[j][1]; HS[r * 512 + dir * 256 + ch] = (_Float16)h; }
;             if (r0 + 32 < 128) {
; #pragma unroll
;                 for (int j = 0; j < 16; ++j) { const int r = dir == 0 ? r0 + 32 + j : 127 - (r0 + 32 + j); fa[j] = ad[(size_t)r * 512]; } }
; #pragma unroll
;             for (int j = 0; j < 16; ++j) { const int r = dir == 0 ? r0 + 16 + j : 127 - (r0 + 16 + j); h = (1.0f - (float)fb[j][0]) * h + (float)fb[j][1]; HS[r * 512 + dir * 256 + ch] = (_Float16)h; } } }
	v_cvt_f32_f16_e32 v11, v146
	v_sub_f32_e32 v11, 1.0, v11
	v_fma_mixlo_f16 v12, v11, v10, v146 op_sel:[0,0,1] op_sel_hi:[0,0,1]
	v_fma_mix_f32 v10, v11, v10, v146 op_sel:[0,0,1] op_sel_hi:[0,0,1]
	ds_write_b16 v5, v12 offset:16384
	v_cvt_f32_f16_e32 v11, v147
	v_sub_f32_e32 v11, 1.0, v11
	v_fma_mixlo_f16 v12, v11, v10, v147 op_sel:[0,0,1] op_sel_hi:[0,0,1]
	v_fma_mix_f32 v10, v11, v10, v147 op_sel:[0,0,1] op_sel_hi:[0,0,1]
	ds_write_b16 v5, v12 offset:17408
	v_cvt_f32_f16_e32 v11, v148
	v_sub_f32_e32 v11, 1.0, v11
	v_fma_mixlo_f16 v12, v11, v10, v148 op_sel:[0,0,1] op_sel_hi:[0,0,1]
	v_fma_mix_f32 v10, v11, v10, v148 op_sel:[0,0,1] op_sel_hi:[0,0,1]
	ds_write_b16 v5, v12 offset:18432
	v_cvt_f32_f16_e32 v11, v149
	v_sub_f32_e32 v11, 1.0, v11
	v_fma_mixlo_f16 v12, v11, v10, v149 op_sel:[0,0,1] op_sel_hi:[0,0,1]
	v_fma_mix_f32 v10, v11, v10, v149 op_sel:[0,0,1] op_sel_hi:[0,0,1]
	ds_write_b16 v5, v12 offset:19456
	v_cvt_f32_f16_e32 v11, v150
	v_sub_f32_e32 v11, 1.0, v11
	v_fma_mixlo_f16 v12, v11, v10, v150 op_sel:[0,0,1] op_sel_hi:[0,0,1]
	v_fma_mix_f32 v10, v11, v10, v150 op_sel:[0,0,1] op_sel_hi:[0,0,1]
	ds_write_b16 v5, v12 offset:20480
	v_cvt_f32_f16_e32 v11, v151
	v_sub_f32_e32 v11, 1.0, v11
	v_fma_mixlo_f16 v12, v11, v10, v151 op_sel:[0,0,1] op_sel_hi:[0,0,1]
	v_fma_mix_f32 v10, v11, v10, v151 op_sel:[0,0,1] op_sel_hi:[0,0,1]
	ds_write_b16 v5, v12 offset:21504
	v_cvt_f32_f16_e32 v11, v152
	v_sub_f32_e32 v11, 1.0, v11
	v_fma_mixlo_f16 v12, v11, v10, v152 op_sel:[0,0,1] op_sel_hi:[0,0,1]
	v_fma_mix_f32 v10, v11, v10, v152 op_sel:[0,0,1] op_sel_hi:[0,0,1]
	ds_write_b16 v5, v12 offset:22528
	v_cvt_f32_f16_e32 v11, v153
	v_sub_f32_e32 v11, 1.0, v11
	v_fma_mixlo_f16 v12, v11, v10, v153 op_sel:[0,0,1] op_sel_hi:[0,0,1]
	v_fma_mix_f32 v10, v11, v10, v153 op_sel:[0,0,1] op_sel_hi:[0,0,1]
	ds_write_b16 v5, v12 offset:23552
	v_cvt_f32_f16_e32 v11, v154
	v_sub_f32_e32 v11, 1.0, v11
	v_fma_mixlo_f16 v12, v11, v10, v154 op_sel:[0,0,1] op_sel_hi:[0,0,1]
	v_fma_mix_f32 v10, v11, v10, v154 op_sel:[0,0,1] op_sel_hi:[0,0,1]
	ds_write_b16 v5, v12 offset:24576
	v_cvt_f32_f16_e32 v11, v155
	v_sub_f32_e32 v11, 1.0, v11
	v_fma_mixlo_f16 v12, v11, v10, v155 op_sel:[0,0,1] op_sel_hi:[0,0,1]
	v_fma_mix_f32 v10, v11, v10, v155 op_sel:[0,0,1] op_sel_hi:[0,0,1]
	ds_write_b16 v5, v12 offset:25600
	v_cvt_f32_f16_e32 v11, v156
	v_sub_f32_e32 v11, 1.0, v11
	v_fma_mixlo_f16 v12, v11, v10, v156 op_sel:[0,0,1] op_sel_hi:[0,0,1]
	v_fma_mix_f32 v10, v11, v10, v156 op_sel:[0,0,1] op_sel_hi:[0,0,1]
	ds_write_b16 v5, v12 offset:26624
	v_cvt_f32_f16_e32 v11, v157
	v_sub_f32_e32 v11, 1.0, v11
	v_fma_mixlo_f16 v12, v11, v10, v157 op_sel:[0,0,1] op_sel_hi:[0,0,1]
	v_fma_mix_f32 v10, v11, v10, v157 op_sel:[0,0,1] op_sel_hi:[0,0,1]
	ds_write_b16 v5, v12 offset:27648
	v_cvt_f32_f16_e32 v11, v158
	v_sub_f32_e32 v11, 1.0, v11
	v_fma_mixlo_f16 v12, v11, v10, v158 op_sel:[0,0,1] op_sel_hi:[0,0,1]
	v_fma_mix_f32 v10, v11, v10, v158 op_sel:[0,0,1] op_sel_hi:[0,0,1]
	ds_write_b16 v5, v12 offset:28672
	v_cvt_f32_f16_e32 v11, v159
	v_sub_f32_e32 v11, 1.0, v11
	v_fma_mixlo_f16 v12, v11, v10, v159 op_sel:[0,0,1] op_sel_hi:[0,0,1]
	v_fma_mix_f32 v10, v11, v10, v159 op_sel:[0,0,1] op_sel_hi:[0,0,1]
	ds_write_b16 v5, v12 offset:29696
	v_cvt_f32_f16_e32 v11, v160
	v_sub_f32_e32 v11, 1.0, v11
	v_fma_mixlo_f16 v12, v11, v10, v160 op_sel:[0,0,1] op_sel_hi:[0,0,1]
	v_fma_mix_f32 v10, v11, v10, v160 op_sel:[0,0,1] op_sel_hi:[0,0,1]
	ds_write_b16 v5, v12 offset:30720
	v_cvt_f32_f16_e32 v11, v161
	v_sub_f32_e32 v11, 1.0, v11
	v_fma_mixlo_f16 v12, v11, v10, v161 op_sel:[0,0,1] op_sel_hi:[0,0,1]
	v_fma_mix_f32 v10, v11, v10, v161 op_sel:[0,0,1] op_sel_hi:[0,0,1]
	ds_write_b16 v5, v12 offset:31744
	s_waitcnt vmcnt(24)
	v_cvt_f32_f16_e32 v11, v162
	v_sub_f32_e32 v11, 1.0, v11
	v_fma_mixlo_f16 v12, v11, v10, v162 op_sel:[0,0,1] op_sel_hi:[0,0,1]
	v_fma_mix_f32 v10, v11, v10, v162 op_sel:[0,0,1] op_sel_hi:[0,0,1]
	ds_write_b16 v5, v12 offset:32768
	v_cvt_f32_f16_e32 v11, v163
	v_sub_f32_e32 v11, 1.0, v11
	v_fma_mixlo_f16 v12, v11, v10, v163 op_sel:[0,0,1] op_sel_hi:[0,0,1]
	v_fma_mix_f32 v10, v11, v10, v163 op_sel:[0,0,1] op_sel_hi:[0,0,1]
	ds_write_b16 v5, v12 offset:33792
	v_cvt_f32_f16_e32 v11, v164
	v_sub_f32_e32 v11, 1.0, v11
	v_fma_mixlo_f16 v12, v11, v10, v164 op_sel:[0,0,1] op_sel_hi:[0,0,1]
	v_fma_mix_f32 v10, v11, v10, v164 op_sel:[0,0,1] op_sel_hi:[0,0,1]
	ds_write_b16 v5, v12 offset:34816
	v_cvt_f32_f16_e32 v11, v165
	v_sub_f32_e32 v11, 1.0, v11
	v_fma_mixlo_f16 v12, v11, v10, v165 op_sel:[0,0,1] op_sel_hi:[0,0,1]
	v_fma_mix_f32 v10, v11, v10, v165 op_sel:[0,0,1] op_sel_hi:[0,0,1]
	ds_write_b16 v5, v12 offset:35840
	v_cvt_f32_f16_e32 v11, v166
	v_sub_f32_e32 v11, 1.0, v11
	v_fma_mixlo_f16 v12, v11, v10, v166 op_sel:[0,0,1] op_sel_hi:[0,0,1]
	v_fma_mix_f32 v10, v11, v10, v166 op_sel:[0,0,1] op_sel_hi:[0,0,1]
	ds_write_b16 v5, v12 offset:36864
	v_cvt_f32_f16_e32 v11, v167
	v_sub_f32_e32 v11, 1.0, v11
	v_fma_mixlo_f16 v12, v11, v10, v167 op_sel:[0,0,1] op_sel_hi:[0,0,1]
	v_fma_mix_f32 v10, v11, v10, v167 op_sel:[0,0,1] op_sel_hi:[0,0,1]
	ds_write_b16 v5, v12 offset:37888
	v_cvt_f32_f16_e32 v11, v168
	v_sub_f32_e32 v11, 1.0, v11
	v_fma_mixlo_f16 v12, v11, v10, v168 op_sel:[0,0,1] op_sel_hi:[0,0,1]
	v_fma_mix_f32 v10, v11, v10, v168 op_sel:[0,0,1] op_sel_hi:[0,0,1]
	ds_write_b16 v5, v12 offset:38912
	v_cvt_f32_f16_e32 v11, v169
	v_sub_f32_e32 v11, 1.0, v11
	v_fma_mixlo_f16 v12, v11, v10, v169 op_sel:[0,0,1] op_sel_hi:[0,0,1]
	v_fma_mix_f32 v10, v11, v10, v169 op_sel:[0,0,1] op_sel_hi:[0,0,1]
	ds_write_b16 v5, v12 offset:39936
	v_cvt_f32_f16_e32 v11, v170
	v_sub_f32_e32 v11, 1.0, v11
; __device__ __forceinline__ void lru_pass2_unit(int cu, const h2* AD, const float2* LCS, const bf16* LG, bf16* MIX, lds_t* lds, int tid) {
;     ...
;         for (int r0 = 0; r0 < 128; r0 += 32) {
; #pragma unroll
;             for (int j = 0; j < 16; ++j) { const int r = dir == 0 ? r0 + 16 + j : 127 - (r0 + 16 + j); fb[j] = ad[(size_t)r * 512]; }
; #pragma unroll
;             for (int j = 0; j < 16; ++j) { const int r = dir == 0 ? r0 + j : 127 - (r0 + j); h = (1.0f - (float)fa[j][0]) * h + (float)fa[j][1]; HS[r * 512 + dir * 256 + ch] = (_Float16)h; }
;             if (r0 + 32 < 128) {
; #pragma unroll
;                 for (int j = 0; j < 16; ++j) { const int r = dir == 0 ? r0 + 32 + j : 127 - (r0 + 32 + j); fa[j] = ad[(size_t)r * 512]; } }
; #pragma unroll
;             for (int j = 0; j < 16; ++j) { const int r = dir == 0 ? r0 + 16 + j : 127 - (r0 + 16 + j); h = (1.0f - (float)fb[j][0]) * h + (float)fb[j][1]; HS[r * 512 + dir * 256 + ch] = (_Float16)h; } } }
	v_fma_mixlo_f16 v12, v11, v10, v170 op_sel:[0,0,1] op_sel_hi:[0,0,1]
	v_fma_mix_f32 v10, v11, v10, v170 op_sel:[0,0,1] op_sel_hi:[0,0,1]
	ds_write_b16 v5, v12 offset:40960
	v_cvt_f32_f16_e32 v11, v171
	v_sub_f32_e32 v11, 1.0, v11
	v_fma_mixlo_f16 v12, v11, v10, v171 op_sel:[0,0,1] op_sel_hi:[0,0,1]
	v_fma_mix_f32 v10, v11, v10, v171 op_sel:[0,0,1] op_sel_hi:[0,0,1]
	ds_write_b16 v5, v12 offset:41984
	v_cvt_f32_f16_e32 v11, v172
	v_sub_f32_e32 v11, 1.0, v11
	v_fma_mixlo_f16 v12, v11, v10, v172 op_sel:[0,0,1] op_sel_hi:[0,0,1]
	v_fma_mix_f32 v10, v11, v10, v172 op_sel:[0,0,1] op_sel_hi:[0,0,1]
	ds_write_b16 v5, v12 offset:43008
	v_cvt_f32_f16_e32 v11, v173
	v_sub_f32_e32 v11, 1.0, v11
	v_fma_mixlo_f16 v12, v11, v10, v173 op_sel:[0,0,1] op_sel_hi:[0,0,1]
	v_fma_mix_f32 v10, v11, v10, v173 op_sel:[0,0,1] op_sel_hi:[0,0,1]
	ds_write_b16 v5, v12 offset:44032
	v_cvt_f32_f16_e32 v11, v174
	v_sub_f32_e32 v11, 1.0, v11
	v_fma_mixlo_f16 v12, v11, v10, v174 op_sel:[0,0,1] op_sel_hi:[0,0,1]
	v_fma_mix_f32 v10, v11, v10, v174 op_sel:[0,0,1] op_sel_hi:[0,0,1]
	ds_write_b16 v5, v12 offset:45056
	v_cvt_f32_f16_e32 v11, v175
	v_sub_f32_e32 v11, 1.0, v11
	v_fma_mixlo_f16 v12, v11, v10, v175 op_sel:[0,0,1] op_sel_hi:[0,0,1]
	v_fma_mix_f32 v10, v11, v10, v175 op_sel:[0,0,1] op_sel_hi:[0,0,1]
	ds_write_b16 v5, v12 offset:46080
	v_cvt_f32_f16_e32 v11, v176
	v_sub_f32_e32 v11, 1.0, v11
	v_fma_mixlo_f16 v12, v11, v10, v176 op_sel:[0,0,1] op_sel_hi:[0,0,1]
	v_fma_mix_f32 v10, v11, v10, v176 op_sel:[0,0,1] op_sel_hi:[0,0,1]
	ds_write_b16 v5, v12 offset:47104
	v_cvt_f32_f16_e32 v11, v177
	v_sub_f32_e32 v11, 1.0, v11
	v_fma_mixlo_f16 v12, v11, v10, v177 op_sel:[0,0,1] op_sel_hi:[0,0,1]
	v_fma_mix_f32 v10, v11, v10, v177 op_sel:[0,0,1] op_sel_hi:[0,0,1]
	ds_write_b16 v5, v12 offset:48128
	s_waitcnt vmcnt(8)
	v_cvt_f32_f16_e32 v11, v178
	v_sub_f32_e32 v11, 1.0, v11
	v_fma_mixlo_f16 v12, v11, v10, v178 op_sel:[0,0,1] op_sel_hi:[0,0,1]
	v_fma_mix_f32 v10, v11, v10, v178 op_sel:[0,0,1] op_sel_hi:[0,0,1]
	ds_write_b16 v5, v12 offset:49152
	v_cvt_f32_f16_e32 v11, v179
	v_sub_f32_e32 v11, 1.0, v11
	v_fma_mixlo_f16 v12, v11, v10, v179 op_sel:[0,0,1] op_sel_hi:[0,0,1]
	v_fma_mix_f32 v10, v11, v10, v179 op_sel:[0,0,1] op_sel_hi:[0,0,1]
	ds_write_b16 v5, v12 offset:50176
	v_cvt_f32_f16_e32 v11, v180
	v_sub_f32_e32 v11, 1.0, v11
	v_fma_mixlo_f16 v12, v11, v10, v180 op_sel:[0,0,1] op_sel_hi:[0,0,1]
	v_fma_mix_f32 v10, v11, v10, v180 op_sel:[0,0,1] op_sel_hi:[0,0,1]
	ds_write_b16 v5, v12 offset:51200
	v_cvt_f32_f16_e32 v11, v181
	v_sub_f32_e32 v11, 1.0, v11
	v_fma_mixlo_f16 v12, v11, v10, v181 op_sel:[0,0,1] op_sel_hi:[0,0,1]
	v_fma_mix_f32 v10, v11, v10, v181 op_sel:[0,0,1] op_sel_hi:[0,0,1]
	ds_write_b16 v5, v12 offset:52224
	v_cvt_f32_f16_e32 v11, v182
	v_sub_f32_e32 v11, 1.0, v11
	v_fma_mixlo_f16 v12, v11, v10, v182 op_sel:[0,0,1] op_sel_hi:[0,0,1]
	v_fma_mix_f32 v10, v11, v10, v182 op_sel:[0,0,1] op_sel_hi:[0,0,1]
	ds_write_b16 v5, v12 offset:53248
	v_cvt_f32_f16_e32 v11, v183
	v_sub_f32_e32 v11, 1.0, v11
	v_fma_mixlo_f16 v12, v11, v10, v183 op_sel:[0,0,1] op_sel_hi:[0,0,1]
	v_fma_mix_f32 v10, v11, v10, v183 op_sel:[0,0,1] op_sel_hi:[0,0,1]
	ds_write_b16 v5, v12 offset:54272
	v_cvt_f32_f16_e32 v11, v184
	v_sub_f32_e32 v11, 1.0, v11
	v_fma_mixlo_f16 v12, v11, v10, v184 op_sel:[0,0,1] op_sel_hi:[0,0,1]
	v_fma_mix_f32 v10, v11, v10, v184 op_sel:[0,0,1] op_sel_hi:[0,0,1]
	ds_write_b16 v5, v12 offset:55296
	v_cvt_f32_f16_e32 v11, v185
	v_sub_f32_e32 v11, 1.0, v11
	v_fma_mixlo_f16 v12, v11, v10, v185 op_sel:[0,0,1] op_sel_hi:[0,0,1]
	v_fma_mix_f32 v10, v11, v10, v185 op_sel:[0,0,1] op_sel_hi:[0,0,1]
	ds_write_b16 v5, v12 offset:56320
	v_cvt_f32_f16_e32 v11, v186
	v_sub_f32_e32 v11, 1.0, v11
	v_fma_mixlo_f16 v12, v11, v10, v186 op_sel:[0,0,1] op_sel_hi:[0,0,1]
	v_fma_mix_f32 v10, v11, v10, v186 op_sel:[0,0,1] op_sel_hi:[0,0,1]
	ds_write_b16 v5, v12 offset:57344
	v_cvt_f32_f16_e32 v11, v187
	v_sub_f32_e32 v11, 1.0, v11
	v_fma_mixlo_f16 v12, v11, v10, v187 op_sel:[0,0,1] op_sel_hi:[0,0,1]
	v_fma_mix_f32 v10, v11, v10, v187 op_sel:[0,0,1] op_sel_hi:[0,0,1]
	ds_write_b16 v5, v12 offset:58368
	v_cvt_f32_f16_e32 v11, v188
	v_sub_f32_e32 v11, 1.0, v11
	v_fma_mixlo_f16 v12, v11, v10, v188 op_sel:[0,0,1] op_sel_hi:[0,0,1]
	v_fma_mix_f32 v10, v11, v10, v188 op_sel:[0,0,1] op_sel_hi:[0,0,1]
	ds_write_b16 v5, v12 offset:59392
	v_cvt_f32_f16_e32 v11, v189
	v_sub_f32_e32 v11, 1.0, v11
	v_fma_mixlo_f16 v12, v11, v10, v189 op_sel:[0,0,1] op_sel_hi:[0,0,1]
	v_fma_mix_f32 v10, v11, v10, v189 op_sel:[0,0,1] op_sel_hi:[0,0,1]
	ds_write_b16 v5, v12 offset:60416
	v_cvt_f32_f16_e32 v11, v190
	v_sub_f32_e32 v11, 1.0, v11
	v_fma_mixlo_f16 v12, v11, v10, v190 op_sel:[0,0,1] op_sel_hi:[0,0,1]
	v_fma_mix_f32 v10, v11, v10, v190 op_sel:[0,0,1] op_sel_hi:[0,0,1]
	ds_write_b16 v5, v12 offset:61440
	v_cvt_f32_f16_e32 v11, v191
	v_sub_f32_e32 v11, 1.0, v11
	v_fma_mixlo_f16 v12, v11, v10, v191 op_sel:[0,0,1] op_sel_hi:[0,0,1]
	v_fma_mix_f32 v10, v11, v10, v191 op_sel:[0,0,1] op_sel_hi:[0,0,1]
	ds_write_b16 v5, v12 offset:62464
	v_cvt_f32_f16_e32 v11, v192
	v_sub_f32_e32 v11, 1.0, v11
	v_fma_mixlo_f16 v12, v11, v10, v192 op_sel:[0,0,1] op_sel_hi:[0,0,1]
	v_fma_mix_f32 v10, v11, v10, v192 op_sel:[0,0,1] op_sel_hi:[0,0,1]
	ds_write_b16 v5, v12 offset:63488
	v_cvt_f32_f16_e32 v11, v193
	v_sub_f32_e32 v11, 1.0, v11
	v_fma_mixlo_f16 v12, v11, v10, v193 op_sel:[0,0,1] op_sel_hi:[0,0,1]
	v_fma_mix_f32 v10, v11, v10, v193 op_sel:[0,0,1] op_sel_hi:[0,0,1]
	ds_write_b16 v5, v12 offset:64512
	s_branch .Ll2x_out
; #define LAS __attribute__((address_space(3)))
; __device__ __forceinline__ void lru_pass2_unit(int cu, const h2* AD, const float2* LCS, const bf16* LG, bf16* MIX, lds_t* lds, int tid) {
;     const int b = cu < 256 ? cu >> 5 : (cu - 256) >> 1, c = cu < 256 ? cu & 31 : 32 + ((cu - 256) & 1);
;     const int m0 = chunk_row0(b, c); const int dir = tid >> 8, ch = tid & 255;
;     LAS _Float16* HS = (LAS _Float16*)lds;
;     float h = 0.f;
;     const float2* cs = LCS + (size_t)b * 34 * 512 + dir * 256 + ch;
;     const int n = dir == 0 ? (c < 32 ? c + 2 : c - 32) : 33 - c;
;     for (int i0 = 0; i0 < n; i0 += 8) { float2 s[8];
; #pragma unroll
;         for (int j = 0; j < 8; ++j) { const int ii = (i0 + j < n) ? i0 + j : 0; const int cc = dir == 0 ? (ii < 2 ? 32 + ii : ii - 2) : 33 - ii; s[j] = cs[(size_t)cc * 512]; }
; #pragma unroll
;         for (int j = 0; j < 8; ++j) if (i0 + j < n) h = s[j].x * h + s[j].y; }
;     const h2* ad = AD + ((size_t)m0 * 2 + dir) * 256 + ch;
;     {
;         h2 fa[16], fb[16];
; #pragma unroll
;         for (int j = 0; j < 16; ++j) { const int r = dir == 0 ? j : 127 - j; fa[j] = ad[(size_t)r * 512]; }
.Ll2x_dir1:
	s_add_u32 s12, s12, 0x400
	s_addc_u32 s13, s13, 0
	s_mul_i32 s18, s2, 0x22000
	s_add_u32 s10, s24, s18
	s_addc_u32 s11, s25, 0
	s_add_u32 s10, s10, 0x800
	s_addc_u32 s11, s11, 0
	s_sub_u32 s9, 33, s3
	s_mov_b32 s19, 0x21000
	s_cmp_gt_u32 s9, 0
	s_cselect_b32 s18, 0x21000, s19
	s_add_u32 s20, s10, s18
	s_addc_u32 s21, s11, 0
	global_load_dwordx2 v[14:15], v2, s[20:21]
	s_cmp_gt_u32 s9, 1
	s_cselect_b32 s18, 0x20000, s19
	s_add_u32 s20, s10, s18
	s_addc_u32 s21, s11, 0
	global_load_dwordx2 v[16:17], v2, s[20:21]
	s_cmp_gt_u32 s9, 2
	s_cselect_b32 s18, 0x1f000, s19
	s_add_u32 s20, s10, s18
	s_addc_u32 s21, s11, 0
	global_load_dwordx2 v[18:19], v2, s[20:21]
	s_cmp_gt_u32 s9, 3
	s_cselect_b32 s18, 0x1e000, s19
	s_add_u32 s20, s10, s18
	s_addc_u32 s21, s11, 0
	global_load_dwordx2 v[20:21], v2, s[20:21]
	s_cmp_gt_u32 s9, 4
	s_cselect_b32 s18, 0x1d000, s19
	s_add_u32 s20, s10, s18
	s_addc_u32 s21, s11, 0
	global_load_dwordx2 v[22:23], v2, s[20:21]
	s_cmp_gt_u32 s9, 5
	s_cselect_b32 s18, 0x1c000, s19
	s_add_u32 s20, s10, s18
	s_addc_u32 s21, s11, 0
	global_load_dwordx2 v[24:25], v2, s[20:21]
	s_cmp_gt_u32 s9, 6
	s_cselect_b32 s18, 0x1b000, s19
	s_add_u32 s20, s10, s18
	s_addc_u32 s21, s11, 0
	global_load_dwordx2 v[26:27], v2, s[20:21]
	s_cmp_gt_u32 s9, 7
	s_cselect_b32 s18, 0x1a000, s19
	s_add_u32 s20, s10, s18
	s_addc_u32 s21, s11, 0
	global_load_dwordx2 v[28:29], v2, s[20:21]
	s_cmp_gt_u32 s9, 8
	s_cselect_b32 s18, 0x19000, s19
	s_add_u32 s20, s10, s18
	s_addc_u32 s21, s11, 0
	global_load_dwordx2 v[30:31], v2, s[20:21]
	s_cmp_gt_u32 s9, 9
	s_cselect_b32 s18, 0x18000, s19
	s_add_u32 s20, s10, s18
	s_addc_u32 s21, s11, 0
	global_load_dwordx2 v[32:33], v2, s[20:21]
	s_cmp_gt_u32 s9, 10
	s_cselect_b32 s18, 0x17000, s19
	s_add_u32 s20, s10, s18
	s_addc_u32 s21, s11, 0
	global_load_dwordx2 v[34:35], v2, s[20:21]
	s_cmp_gt_u32 s9, 11
	s_cselect_b32 s18, 0x16000, s19
	s_add_u32 s20, s10, s18
	s_addc_u32 s21, s11, 0
	global_load_dwordx2 v[36:37], v2, s[20:21]
	s_cmp_gt_u32 s9, 12
	s_cselect_b32 s18, 0x15000, s19
	s_add_u32 s20, s10, s18
	s_addc_u32 s21, s11, 0
	global_load_dwordx2 v[38:39], v2, s[20:21]
	s_cmp_gt_u32 s9, 13
	s_cselect_b32 s18, 0x14000, s19
	s_add_u32 s20, s10, s18
	s_addc_u32 s21, s11, 0
	global_load_dwordx2 v[40:41], v2, s[20:21]
	s_cmp_gt_u32 s9, 14
	s_cselect_b32 s18, 0x13000, s19
	s_add_u32 s20, s10, s18
	s_addc_u32 s21, s11, 0
	global_load_dwordx2 v[42:43], v2, s[20:21]
	s_cmp_gt_u32 s9, 15
	s_cselect_b32 s18, 0x12000, s19
	s_add_u32 s20, s10, s18
	s_addc_u32 s21, s11, 0
	global_load_dwordx2 v[44:45], v2, s[20:21]
	s_cmp_gt_u32 s9, 16
	s_cselect_b32 s18, 0x11000, s19
	s_add_u32 s20, s10, s18
	s_addc_u32 s21, s11, 0
	global_load_dwordx2 v[46:47], v2, s[20:21]
	s_cmp_gt_u32 s9, 17
	s_cselect_b32 s18, 0x10000, s19
	s_add_u32 s20, s10, s18
	s_addc_u32 s21, s11, 0
	global_load_dwordx2 v[48:49], v2, s[20:21]
	s_cmp_gt_u32 s9, 18
	s_cselect_b32 s18, 0xf000, s19
	s_add_u32 s20, s10, s18
	s_addc_u32 s21, s11, 0
	global_load_dwordx2 v[50:51], v2, s[20:21]
	s_cmp_gt_u32 s9, 19
	s_cselect_b32 s18, 0xe000, s19
	s_add_u32 s20, s10, s18
	s_addc_u32 s21, s11, 0
	global_load_dwordx2 v[52:53], v2, s[20:21]
	s_cmp_gt_u32 s9, 20
	s_cselect_b32 s18, 0xd000, s19
	s_add_u32 s20, s10, s18
	s_addc_u32 s21, s11, 0
	global_load_dwordx2 v[54:55], v2, s[20:21]
	s_cmp_gt_u32 s9, 21
	s_cselect_b32 s18, 0xc000, s19
	s_add_u32 s20, s10, s18
	s_addc_u32 s21, s11, 0
	global_load_dwordx2 v[56:57], v2, s[20:21]
	s_cmp_gt_u32 s9, 22
	s_cselect_b32 s18, 0xb000, s19
	s_add_u32 s20, s10, s18
	s_addc_u32 s21, s11, 0
	global_load_dwordx2 v[58:59], v2, s[20:21]
	s_cmp_gt_u32 s9, 23
	s_cselect_b32 s18, 0xa000, s19
	s_add_u32 s20, s10, s18
	s_addc_u32 s21, s11, 0
	global_load_dwordx2 v[60:61], v2, s[20:21]
	s_cmp_gt_u32 s9, 24
	s_cselect_b32 s18, 0x9000, s19
	s_add_u32 s20, s10, s18
	s_addc_u32 s21, s11, 0
	global_load_dwordx2 v[62:63], v2, s[20:21]
	s_cmp_gt_u32 s9, 25
	s_cselect_b32 s18, 0x8000, s19
	s_add_u32 s20, s10, s18
	s_addc_u32 s21, s11, 0
	global_load_dwordx2 v[64:65], v2, s[20:21]
	s_cmp_gt_u32 s9, 26
	s_cselect_b32 s18, 0x7000, s19
	s_add_u32 s20, s10, s18
	s_addc_u32 s21, s11, 0
	global_load_dwordx2 v[66:67], v2, s[20:21]
	s_cmp_gt_u32 s9, 27
	s_cselect_b32 s18, 0x6000, s19
	s_add_u32 s20, s10, s18
	s_addc_u32 s21, s11, 0
	global_load_dwordx2 v[68:69], v2, s[20:21]
	s_cmp_gt_u32 s9, 28
	s_cselect_b32 s18, 0x5000, s19
	s_add_u32 s20, s10, s18
	s_addc_u32 s21, s11, 0
	global_load_dwordx2 v[70:71], v2, s[20:21]
	s_cmp_gt_u32 s9, 29
	s_cselect_b32 s18, 0x4000, s19
	s_add_u32 s20, s10, s18
	s_addc_u32 s21, s11, 0
	global_load_dwordx2 v[72:73], v2, s[20:21]
	s_cmp_gt_u32 s9, 30
	s_cselect_b32 s18, 0x3000, s19
	s_add_u32 s20, s10, s18
	s_addc_u32 s21, s11, 0
	global_load_dwordx2 v[74:75], v2, s[20:21]
	s_cmp_gt_u32 s9, 31
	s_cselect_b32 s18, 0x2000, s19
	s_add_u32 s20, s10, s18
	s_addc_u32 s21, s11, 0
	global_load_dwordx2 v[76:77], v2, s[20:21]
	s_cmp_gt_u32 s9, 32
	s_cselect_b32 s18, 0x1000, s19
	s_add_u32 s20, s10, s18
	s_addc_u32 s21, s11, 0
	global_load_dwordx2 v[78:79], v2, s[20:21]
	s_cmp_gt_u32 s9, 33
	s_cselect_b32 s18, 0x0, s19
	s_add_u32 s20, s10, s18
	s_addc_u32 s21, s11, 0
	global_load_dwordx2 v[80:81], v2, s[20:21]
	s_add_u32 s22, s12, 0x3f000
	s_addc_u32 s23, s13, 0
	global_load_dword v130, v3, s[22:23] offset:2048
	global_load_dword v131, v3, s[22:23]
	s_add_u32 s22, s12, 0x3e000
	s_addc_u32 s23, s13, 0
	global_load_dword v132, v3, s[22:23] offset:2048
	global_load_dword v133, v3, s[22:23]
	s_add_u32 s22, s12, 0x3d000
	s_addc_u32 s23, s13, 0
	global_load_dword v134, v3, s[22:23] offset:2048
	global_load_dword v135, v3, s[22:23]
; __device__ __forceinline__ void lru_pass2_unit(int cu, const h2* AD, const float2* LCS, const bf16* LG, bf16* MIX, lds_t* lds, int tid) {
;     ...
;     const float2* cs = LCS + (size_t)b * 34 * 512 + dir * 256 + ch;
;     const int n = dir == 0 ? (c < 32 ? c + 2 : c - 32) : 33 - c;
;     for (int i0 = 0; i0 < n; i0 += 8) { float2 s[8];
; #pragma unroll
;         for (int j = 0; j < 8; ++j) { const int ii = (i0 + j < n) ? i0 + j : 0; const int cc = dir == 0 ? (ii < 2 ? 32 + ii : ii - 2) : 33 - ii; s[j] = cs[(size_t)cc * 512]; }
; #pragma unroll
;         for (int j = 0; j < 8; ++j) if (i0 + j < n) h = s[j].x * h + s[j].y; }
;     const h2* ad = AD + ((size_t)m0 * 2 + dir) * 256 + ch;
;     {
;         h2 fa[16], fb[16];
; #pragma unroll
;         for (int j = 0; j < 16; ++j) { const int r = dir == 0 ? j : 127 - j; fa[j] = ad[(size_t)r * 512]; }
	s_add_u32 s22, s12, 0x3c000
	s_addc_u32 s23, s13, 0
	global_load_dword v136, v3, s[22:23] offset:2048
	global_load_dword v137, v3, s[22:23]
	s_add_u32 s22, s12, 0x3b000
	s_addc_u32 s23, s13, 0
	global_load_dword v138, v3, s[22:23] offset:2048
	global_load_dword v139, v3, s[22:23]
	s_add_u32 s22, s12, 0x3a000
	s_addc_u32 s23, s13, 0
	global_load_dword v140, v3, s[22:23] offset:2048
	global_load_dword v141, v3, s[22:23]
	s_add_u32 s22, s12, 0x39000
	s_addc_u32 s23, s13, 0
	global_load_dword v142, v3, s[22:23] offset:2048
	global_load_dword v143, v3, s[22:23]
	s_add_u32 s22, s12, 0x38000
	s_addc_u32 s23, s13, 0
	global_load_dword v144, v3, s[22:23] offset:2048
	global_load_dword v145, v3, s[22:23]
	s_add_u32 s22, s12, 0x37000
	s_addc_u32 s23, s13, 0
	global_load_dword v146, v3, s[22:23] offset:2048
	global_load_dword v147, v3, s[22:23]
	s_add_u32 s22, s12, 0x36000
	s_addc_u32 s23, s13, 0
	global_load_dword v148, v3, s[22:23] offset:2048
	global_load_dword v149, v3, s[22:23]
	s_add_u32 s22, s12, 0x35000
	s_addc_u32 s23, s13, 0
	global_load_dword v150, v3, s[22:23] offset:2048
	global_load_dword v151, v3, s[22:23]
	s_add_u32 s22, s12, 0x34000
	s_addc_u32 s23, s13, 0
	global_load_dword v152, v3, s[22:23] offset:2048
	global_load_dword v153, v3, s[22:23]
	s_add_u32 s22, s12, 0x33000
	s_addc_u32 s23, s13, 0
	global_load_dword v154, v3, s[22:23] offset:2048
	global_load_dword v155, v3, s[22:23]
	s_add_u32 s22, s12, 0x32000
	s_addc_u32 s23, s13, 0
	global_load_dword v156, v3, s[22:23] offset:2048
	global_load_dword v157, v3, s[22:23]
	s_add_u32 s22, s12, 0x31000
	s_addc_u32 s23, s13, 0
	global_load_dword v158, v3, s[22:23] offset:2048
	s_waitcnt vmcnt(29)
	v_mov_b32_e32 v10, 0
	s_cmp_gt_u32 s9, 0
	s_cbranch_scc0 .Ll2x_d1_cdone
	v_fma_f32 v10, v14, v10, v15
	s_cmp_gt_u32 s9, 1
	s_cbranch_scc0 .Ll2x_d1_cdone
	v_fma_f32 v10, v16, v10, v17
	s_cmp_gt_u32 s9, 2
	s_cbranch_scc0 .Ll2x_d1_cdone
	v_fma_f32 v10, v18, v10, v19
	s_cmp_gt_u32 s9, 3
	s_cbranch_scc0 .Ll2x_d1_cdone
	v_fma_f32 v10, v20, v10, v21
	s_cmp_gt_u32 s9, 4
	s_cbranch_scc0 .Ll2x_d1_cdone
	v_fma_f32 v10, v22, v10, v23
	s_cmp_gt_u32 s9, 5
	s_cbranch_scc0 .Ll2x_d1_cdone
	v_fma_f32 v10, v24, v10, v25
	s_cmp_gt_u32 s9, 6
	s_cbranch_scc0 .Ll2x_d1_cdone
	v_fma_f32 v10, v26, v10, v27
	s_cmp_gt_u32 s9, 7
	s_cbranch_scc0 .Ll2x_d1_cdone
	v_fma_f32 v10, v28, v10, v29
	s_cmp_gt_u32 s9, 8
	s_cbranch_scc0 .Ll2x_d1_cdone
	v_fma_f32 v10, v30, v10, v31
	s_cmp_gt_u32 s9, 9
	s_cbranch_scc0 .Ll2x_d1_cdone
	v_fma_f32 v10, v32, v10, v33
	s_cmp_gt_u32 s9, 10
	s_cbranch_scc0 .Ll2x_d1_cdone
	v_fma_f32 v10, v34, v10, v35
	s_cmp_gt_u32 s9, 11
	s_cbranch_scc0 .Ll2x_d1_cdone
	v_fma_f32 v10, v36, v10, v37
	s_cmp_gt_u32 s9, 12
	s_cbranch_scc0 .Ll2x_d1_cdone
	v_fma_f32 v10, v38, v10, v39
	s_cmp_gt_u32 s9, 13
	s_cbranch_scc0 .Ll2x_d1_cdone
	v_fma_f32 v10, v40, v10, v41
	s_cmp_gt_u32 s9, 14
	s_cbranch_scc0 .Ll2x_d1_cdone
	v_fma_f32 v10, v42, v10, v43
	s_cmp_gt_u32 s9, 15
	s_cbranch_scc0 .Ll2x_d1_cdone
	v_fma_f32 v10, v44, v10, v45
	s_cmp_gt_u32 s9, 16
	s_cbranch_scc0 .Ll2x_d1_cdone
	v_fma_f32 v10, v46, v10, v47
	s_cmp_gt_u32 s9, 17
	s_cbranch_scc0 .Ll2x_d1_cdone
	v_fma_f32 v10, v48, v10, v49
	s_cmp_gt_u32 s9, 18
	s_cbranch_scc0 .Ll2x_d1_cdone
	v_fma_f32 v10, v50, v10, v51
	s_cmp_gt_u32 s9, 19
	s_cbranch_scc0 .Ll2x_d1_cdone
	v_fma_f32 v10, v52, v10, v53
	s_cmp_gt_u32 s9, 20
	s_cbranch_scc0 .Ll2x_d1_cdone
	v_fma_f32 v10, v54, v10, v55
	s_cmp_gt_u32 s9, 21
	s_cbranch_scc0 .Ll2x_d1_cdone
	v_fma_f32 v10, v56, v10, v57
	s_cmp_gt_u32 s9, 22
	s_cbranch_scc0 .Ll2x_d1_cdone
	v_fma_f32 v10, v58, v10, v59
	s_cmp_gt_u32 s9, 23
	s_cbranch_scc0 .Ll2x_d1_cdone
	v_fma_f32 v10, v60, v10, v61
	s_cmp_gt_u32 s9, 24
	s_cbranch_scc0 .Ll2x_d1_cdone
	v_fma_f32 v10, v62, v10, v63
	s_cmp_gt_u32 s9, 25
	s_cbranch_scc0 .Ll2x_d1_cdone
	v_fma_f32 v10, v64, v10, v65
	s_cmp_gt_u32 s9, 26
	s_cbranch_scc0 .Ll2x_d1_cdone
	v_fma_f32 v10, v66, v10, v67
	s_cmp_gt_u32 s9, 27
	s_cbranch_scc0 .Ll2x_d1_cdone
	v_fma_f32 v10, v68, v10, v69
	s_cmp_gt_u32 s9, 28
	s_cbranch_scc0 .Ll2x_d1_cdone
	v_fma_f32 v10, v70, v10, v71
	s_cmp_gt_u32 s9, 29
	s_cbranch_scc0 .Ll2x_d1_cdone
	v_fma_f32 v10, v72, v10, v73
	s_cmp_gt_u32 s9, 30
	s_cbranch_scc0 .Ll2x_d1_cdone
	v_fma_f32 v10, v74, v10, v75
	s_cmp_gt_u32 s9, 31
	s_cbranch_scc0 .Ll2x_d1_cdone
	v_fma_f32 v10, v76, v10, v77
	s_cmp_gt_u32 s9, 32
	s_cbranch_scc0 .Ll2x_d1_cdone
	v_fma_f32 v10, v78, v10, v79
	s_cmp_gt_u32 s9, 33
	s_cbranch_scc0 .Ll2x_d1_cdone
	v_fma_f32 v10, v80, v10, v81
; __device__ __forceinline__ void lru_pass2_unit(int cu, const h2* AD, const float2* LCS, const bf16* LG, bf16* MIX, lds_t* lds, int tid) {
;     ...
;     const h2* ad = AD + ((size_t)m0 * 2 + dir) * 256 + ch;
;     {
;         h2 fa[16], fb[16];
; #pragma unroll
;         for (int j = 0; j < 16; ++j) { const int r = dir == 0 ? j : 127 - j; fa[j] = ad[(size_t)r * 512]; }
; #pragma unroll 1
;         for (int r0 = 0; r0 < 128; r0 += 32) {
; #pragma unroll
;             for (int j = 0; j < 16; ++j) { const int r = dir == 0 ? r0 + 16 + j : 127 - (r0 + 16 + j); fb[j] = ad[(size_t)r * 512]; }
; #pragma unroll
;             for (int j = 0; j < 16; ++j) { const int r = dir == 0 ? r0 + j : 127 - (r0 + j); h = (1.0f - (float)fa[j][0]) * h + (float)fa[j][1]; HS[r * 512 + dir * 256 + ch] = (_Float16)h; }
;             if (r0 + 32 < 128) {
; #pragma unroll
;                 for (int j = 0; j < 16; ++j) { const int r = dir == 0 ? r0 + 32 + j : 127 - (r0 + 32 + j); fa[j] = ad[(size_t)r * 512]; } }
; #pragma unroll
;             for (int j = 0; j < 16; ++j) { const int r = dir == 0 ? r0 + 16 + j : 127 - (r0 + 16 + j); h = (1.0f - (float)fb[j][0]) * h + (float)fb[j][1]; HS[r * 512 + dir * 256 + ch] = (_Float16)h; } } }
.Ll2x_d1_cdone:
	global_load_dword v159, v3, s[22:23]
	s_add_u32 s22, s12, 0x30000
	s_addc_u32 s23, s13, 0
	global_load_dword v160, v3, s[22:23] offset:2048
	global_load_dword v161, v3, s[22:23]
	s_add_u32 s22, s12, 0x2f000
	s_addc_u32 s23, s13, 0
	global_load_dword v162, v3, s[22:23] offset:2048
	global_load_dword v163, v3, s[22:23]
	s_add_u32 s22, s12, 0x2e000
	s_addc_u32 s23, s13, 0
	global_load_dword v164, v3, s[22:23] offset:2048
	global_load_dword v165, v3, s[22:23]
	s_add_u32 s22, s12, 0x2d000
	s_addc_u32 s23, s13, 0
	global_load_dword v166, v3, s[22:23] offset:2048
	global_load_dword v167, v3, s[22:23]
	s_add_u32 s22, s12, 0x2c000
	s_addc_u32 s23, s13, 0
	global_load_dword v168, v3, s[22:23] offset:2048
	global_load_dword v169, v3, s[22:23]
	s_add_u32 s22, s12, 0x2b000
	s_addc_u32 s23, s13, 0
	global_load_dword v170, v3, s[22:23] offset:2048
	global_load_dword v171, v3, s[22:23]
	s_add_u32 s22, s12, 0x2a000
	s_addc_u32 s23, s13, 0
	global_load_dword v172, v3, s[22:23] offset:2048
	global_load_dword v173, v3, s[22:23]
	s_add_u32 s22, s12, 0x29000
	s_addc_u32 s23, s13, 0
	global_load_dword v174, v3, s[22:23] offset:2048
	global_load_dword v175, v3, s[22:23]
	s_add_u32 s22, s12, 0x28000
	s_addc_u32 s23, s13, 0
	global_load_dword v176, v3, s[22:23] offset:2048
	global_load_dword v177, v3, s[22:23]
	s_add_u32 s22, s12, 0x27000
	s_addc_u32 s23, s13, 0
	global_load_dword v178, v3, s[22:23] offset:2048
	global_load_dword v179, v3, s[22:23]
	s_add_u32 s22, s12, 0x26000
	s_addc_u32 s23, s13, 0
	global_load_dword v180, v3, s[22:23] offset:2048
	global_load_dword v181, v3, s[22:23]
	s_add_u32 s22, s12, 0x25000
	s_addc_u32 s23, s13, 0
	global_load_dword v182, v3, s[22:23] offset:2048
	global_load_dword v183, v3, s[22:23]
	s_add_u32 s22, s12, 0x24000
	s_addc_u32 s23, s13, 0
	global_load_dword v184, v3, s[22:23] offset:2048
	global_load_dword v185, v3, s[22:23]
	s_add_u32 s22, s12, 0x23000
	s_addc_u32 s23, s13, 0
	global_load_dword v186, v3, s[22:23] offset:2048
	global_load_dword v187, v3, s[22:23]
	s_add_u32 s22, s12, 0x22000
	s_addc_u32 s23, s13, 0
	global_load_dword v188, v3, s[22:23] offset:2048
	global_load_dword v189, v3, s[22:23]
	s_add_u32 s22, s12, 0x21000
	s_addc_u32 s23, s13, 0
	global_load_dword v190, v3, s[22:23] offset:2048
	global_load_dword v191, v3, s[22:23]
	s_add_u32 s22, s12, 0x20000
	s_addc_u32 s23, s13, 0
	global_load_dword v192, v3, s[22:23] offset:2048
	s_waitcnt vmcnt(47)
	v_cvt_f32_f16_e32 v11, v130
	v_sub_f32_e32 v11, 1.0, v11
	v_fma_mixlo_f16 v12, v11, v10, v130 op_sel:[0,0,1] op_sel_hi:[0,0,1]
	v_fma_mix_f32 v10, v11, v10, v130 op_sel:[0,0,1] op_sel_hi:[0,0,1]
	ds_write_b16 v5, v12 offset:64512
	v_cvt_f32_f16_e32 v11, v131
	v_sub_f32_e32 v11, 1.0, v11
	v_fma_mixlo_f16 v12, v11, v10, v131 op_sel:[0,0,1] op_sel_hi:[0,0,1]
	v_fma_mix_f32 v10, v11, v10, v131 op_sel:[0,0,1] op_sel_hi:[0,0,1]
	ds_write_b16 v5, v12 offset:63488
	v_cvt_f32_f16_e32 v11, v132
	v_sub_f32_e32 v11, 1.0, v11
	v_fma_mixlo_f16 v12, v11, v10, v132 op_sel:[0,0,1] op_sel_hi:[0,0,1]
	v_fma_mix_f32 v10, v11, v10, v132 op_sel:[0,0,1] op_sel_hi:[0,0,1]
	ds_write_b16 v5, v12 offset:62464
	v_cvt_f32_f16_e32 v11, v133
	v_sub_f32_e32 v11, 1.0, v11
	v_fma_mixlo_f16 v12, v11, v10, v133 op_sel:[0,0,1] op_sel_hi:[0,0,1]
	v_fma_mix_f32 v10, v11, v10, v133 op_sel:[0,0,1] op_sel_hi:[0,0,1]
	ds_write_b16 v5, v12 offset:61440
	v_cvt_f32_f16_e32 v11, v134
	v_sub_f32_e32 v11, 1.0, v11
	v_fma_mixlo_f16 v12, v11, v10, v134 op_sel:[0,0,1] op_sel_hi:[0,0,1]
	v_fma_mix_f32 v10, v11, v10, v134 op_sel:[0,0,1] op_sel_hi:[0,0,1]
	ds_write_b16 v5, v12 offset:60416
	v_cvt_f32_f16_e32 v11, v135
	v_sub_f32_e32 v11, 1.0, v11
	v_fma_mixlo_f16 v12, v11, v10, v135 op_sel:[0,0,1] op_sel_hi:[0,0,1]
	v_fma_mix_f32 v10, v11, v10, v135 op_sel:[0,0,1] op_sel_hi:[0,0,1]
	ds_write_b16 v5, v12 offset:59392
	v_cvt_f32_f16_e32 v11, v136
	v_sub_f32_e32 v11, 1.0, v11
	v_fma_mixlo_f16 v12, v11, v10, v136 op_sel:[0,0,1] op_sel_hi:[0,0,1]
	v_fma_mix_f32 v10, v11, v10, v136 op_sel:[0,0,1] op_sel_hi:[0,0,1]
	ds_write_b16 v5, v12 offset:58368
	v_cvt_f32_f16_e32 v11, v137
	v_sub_f32_e32 v11, 1.0, v11
	v_fma_mixlo_f16 v12, v11, v10, v137 op_sel:[0,0,1] op_sel_hi:[0,0,1]
	v_fma_mix_f32 v10, v11, v10, v137 op_sel:[0,0,1] op_sel_hi:[0,0,1]
	ds_write_b16 v5, v12 offset:57344
	v_cvt_f32_f16_e32 v11, v138
	v_sub_f32_e32 v11, 1.0, v11
	v_fma_mixlo_f16 v12, v11, v10, v138 op_sel:[0,0,1] op_sel_hi:[0,0,1]
	v_fma_mix_f32 v10, v11, v10, v138 op_sel:[0,0,1] op_sel_hi:[0,0,1]
	ds_write_b16 v5, v12 offset:56320
	v_cvt_f32_f16_e32 v11, v139
	v_sub_f32_e32 v11, 1.0, v11
	v_fma_mixlo_f16 v12, v11, v10, v139 op_sel:[0,0,1] op_sel_hi:[0,0,1]
	v_fma_mix_f32 v10, v11, v10, v139 op_sel:[0,0,1] op_sel_hi:[0,0,1]
	ds_write_b16 v5, v12 offset:55296
	v_cvt_f32_f16_e32 v11, v140
	v_sub_f32_e32 v11, 1.0, v11
	v_fma_mixlo_f16 v12, v11, v10, v140 op_sel:[0,0,1] op_sel_hi:[0,0,1]
	v_fma_mix_f32 v10, v11, v10, v140 op_sel:[0,0,1] op_sel_hi:[0,0,1]
	ds_write_b16 v5, v12 offset:54272
	v_cvt_f32_f16_e32 v11, v141
	v_sub_f32_e32 v11, 1.0, v11
	v_fma_mixlo_f16 v12, v11, v10, v141 op_sel:[0,0,1] op_sel_hi:[0,0,1]
	v_fma_mix_f32 v10, v11, v10, v141 op_sel:[0,0,1] op_sel_hi:[0,0,1]
	ds_write_b16 v5, v12 offset:53248
	v_cvt_f32_f16_e32 v11, v142
	v_sub_f32_e32 v11, 1.0, v11
	v_fma_mixlo_f16 v12, v11, v10, v142 op_sel:[0,0,1] op_sel_hi:[0,0,1]
	v_fma_mix_f32 v10, v11, v10, v142 op_sel:[0,0,1] op_sel_hi:[0,0,1]
	ds_write_b16 v5, v12 offset:52224
	v_cvt_f32_f16_e32 v11, v143
	v_sub_f32_e32 v11, 1.0, v11
	v_fma_mixlo_f16 v12, v11, v10, v143 op_sel:[0,0,1] op_sel_hi:[0,0,1]
	v_fma_mix_f32 v10, v11, v10, v143 op_sel:[0,0,1] op_sel_hi:[0,0,1]
; __device__ __forceinline__ void lru_pass2_unit(int cu, const h2* AD, const float2* LCS, const bf16* LG, bf16* MIX, lds_t* lds, int tid) {
;     ...
;     const h2* ad = AD + ((size_t)m0 * 2 + dir) * 256 + ch;
;     {
;         h2 fa[16], fb[16];
; #pragma unroll
;         for (int j = 0; j < 16; ++j) { const int r = dir == 0 ? j : 127 - j; fa[j] = ad[(size_t)r * 512]; }
; #pragma unroll 1
;         for (int r0 = 0; r0 < 128; r0 += 32) {
; #pragma unroll
;             for (int j = 0; j < 16; ++j) { const int r = dir == 0 ? r0 + 16 + j : 127 - (r0 + 16 + j); fb[j] = ad[(size_t)r * 512]; }
; #pragma unroll
;             for (int j = 0; j < 16; ++j) { const int r = dir == 0 ? r0 + j : 127 - (r0 + j); h = (1.0f - (float)fa[j][0]) * h + (float)fa[j][1]; HS[r * 512 + dir * 256 + ch] = (_Float16)h; }
;             if (r0 + 32 < 128) {
; #pragma unroll
;                 for (int j = 0; j < 16; ++j) { const int r = dir == 0 ? r0 + 32 + j : 127 - (r0 + 32 + j); fa[j] = ad[(size_t)r * 512]; } }
; #pragma unroll
;             for (int j = 0; j < 16; ++j) { const int r = dir == 0 ? r0 + 16 + j : 127 - (r0 + 16 + j); h = (1.0f - (float)fb[j][0]) * h + (float)fb[j][1]; HS[r * 512 + dir * 256 + ch] = (_Float16)h; } } }
	ds_write_b16 v5, v12 offset:51200
	v_cvt_f32_f16_e32 v11, v144
	v_sub_f32_e32 v11, 1.0, v11
	v_fma_mixlo_f16 v12, v11, v10, v144 op_sel:[0,0,1] op_sel_hi:[0,0,1]
	v_fma_mix_f32 v10, v11, v10, v144 op_sel:[0,0,1] op_sel_hi:[0,0,1]
	ds_write_b16 v5, v12 offset:50176
	v_cvt_f32_f16_e32 v11, v145
	v_sub_f32_e32 v11, 1.0, v11
	v_fma_mixlo_f16 v12, v11, v10, v145 op_sel:[0,0,1] op_sel_hi:[0,0,1]
	v_fma_mix_f32 v10, v11, v10, v145 op_sel:[0,0,1] op_sel_hi:[0,0,1]
	ds_write_b16 v5, v12 offset:49152
	global_load_dword v193, v3, s[22:23]
	s_add_u32 s22, s12, 0x1f000
	s_addc_u32 s23, s13, 0
	global_load_dword v130, v3, s[22:23] offset:2048
	global_load_dword v131, v3, s[22:23]
	s_add_u32 s22, s12, 0x1e000
	s_addc_u32 s23, s13, 0
	global_load_dword v132, v3, s[22:23] offset:2048
	global_load_dword v133, v3, s[22:23]
	s_add_u32 s22, s12, 0x1d000
	s_addc_u32 s23, s13, 0
	global_load_dword v134, v3, s[22:23] offset:2048
	global_load_dword v135, v3, s[22:23]
	s_add_u32 s22, s12, 0x1c000
	s_addc_u32 s23, s13, 0
	global_load_dword v136, v3, s[22:23] offset:2048
	global_load_dword v137, v3, s[22:23]
	s_add_u32 s22, s12, 0x1b000
	s_addc_u32 s23, s13, 0
	global_load_dword v138, v3, s[22:23] offset:2048
	global_load_dword v139, v3, s[22:23]
	s_add_u32 s22, s12, 0x1a000
	s_addc_u32 s23, s13, 0
	global_load_dword v140, v3, s[22:23] offset:2048
	global_load_dword v141, v3, s[22:23]
	s_add_u32 s22, s12, 0x19000
	s_addc_u32 s23, s13, 0
	global_load_dword v142, v3, s[22:23] offset:2048
	global_load_dword v143, v3, s[22:23]
	s_add_u32 s22, s12, 0x18000
	s_addc_u32 s23, s13, 0
	global_load_dword v144, v3, s[22:23] offset:2048
	s_waitcnt vmcnt(47)
	v_cvt_f32_f16_e32 v11, v146
	v_sub_f32_e32 v11, 1.0, v11
	v_fma_mixlo_f16 v12, v11, v10, v146 op_sel:[0,0,1] op_sel_hi:[0,0,1]
	v_fma_mix_f32 v10, v11, v10, v146 op_sel:[0,0,1] op_sel_hi:[0,0,1]
	ds_write_b16 v5, v12 offset:48128
	v_cvt_f32_f16_e32 v11, v147
	v_sub_f32_e32 v11, 1.0, v11
	v_fma_mixlo_f16 v12, v11, v10, v147 op_sel:[0,0,1] op_sel_hi:[0,0,1]
	v_fma_mix_f32 v10, v11, v10, v147 op_sel:[0,0,1] op_sel_hi:[0,0,1]
	ds_write_b16 v5, v12 offset:47104
	v_cvt_f32_f16_e32 v11, v148
	v_sub_f32_e32 v11, 1.0, v11
	v_fma_mixlo_f16 v12, v11, v10, v148 op_sel:[0,0,1] op_sel_hi:[0,0,1]
	v_fma_mix_f32 v10, v11, v10, v148 op_sel:[0,0,1] op_sel_hi:[0,0,1]
	ds_write_b16 v5, v12 offset:46080
	v_cvt_f32_f16_e32 v11, v149
	v_sub_f32_e32 v11, 1.0, v11
	v_fma_mixlo_f16 v12, v11, v10, v149 op_sel:[0,0,1] op_sel_hi:[0,0,1]
	v_fma_mix_f32 v10, v11, v10, v149 op_sel:[0,0,1] op_sel_hi:[0,0,1]
	ds_write_b16 v5, v12 offset:45056
	v_cvt_f32_f16_e32 v11, v150
	v_sub_f32_e32 v11, 1.0, v11
	v_fma_mixlo_f16 v12, v11, v10, v150 op_sel:[0,0,1] op_sel_hi:[0,0,1]
	v_fma_mix_f32 v10, v11, v10, v150 op_sel:[0,0,1] op_sel_hi:[0,0,1]
	ds_write_b16 v5, v12 offset:44032
	v_cvt_f32_f16_e32 v11, v151
	v_sub_f32_e32 v11, 1.0, v11
	v_fma_mixlo_f16 v12, v11, v10, v151 op_sel:[0,0,1] op_sel_hi:[0,0,1]
	v_fma_mix_f32 v10, v11, v10, v151 op_sel:[0,0,1] op_sel_hi:[0,0,1]
	ds_write_b16 v5, v12 offset:43008
	v_cvt_f32_f16_e32 v11, v152
	v_sub_f32_e32 v11, 1.0, v11
	v_fma_mixlo_f16 v12, v11, v10, v152 op_sel:[0,0,1] op_sel_hi:[0,0,1]
	v_fma_mix_f32 v10, v11, v10, v152 op_sel:[0,0,1] op_sel_hi:[0,0,1]
	ds_write_b16 v5, v12 offset:41984
	v_cvt_f32_f16_e32 v11, v153
	v_sub_f32_e32 v11, 1.0, v11
	v_fma_mixlo_f16 v12, v11, v10, v153 op_sel:[0,0,1] op_sel_hi:[0,0,1]
	v_fma_mix_f32 v10, v11, v10, v153 op_sel:[0,0,1] op_sel_hi:[0,0,1]
	ds_write_b16 v5, v12 offset:40960
	v_cvt_f32_f16_e32 v11, v154
	v_sub_f32_e32 v11, 1.0, v11
	v_fma_mixlo_f16 v12, v11, v10, v154 op_sel:[0,0,1] op_sel_hi:[0,0,1]
	v_fma_mix_f32 v10, v11, v10, v154 op_sel:[0,0,1] op_sel_hi:[0,0,1]
	ds_write_b16 v5, v12 offset:39936
	v_cvt_f32_f16_e32 v11, v155
	v_sub_f32_e32 v11, 1.0, v11
	v_fma_mixlo_f16 v12, v11, v10, v155 op_sel:[0,0,1] op_sel_hi:[0,0,1]
	v_fma_mix_f32 v10, v11, v10, v155 op_sel:[0,0,1] op_sel_hi:[0,0,1]
	ds_write_b16 v5, v12 offset:38912
	v_cvt_f32_f16_e32 v11, v156
	v_sub_f32_e32 v11, 1.0, v11
	v_fma_mixlo_f16 v12, v11, v10, v156 op_sel:[0,0,1] op_sel_hi:[0,0,1]
	v_fma_mix_f32 v10, v11, v10, v156 op_sel:[0,0,1] op_sel_hi:[0,0,1]
	ds_write_b16 v5, v12 offset:37888
	v_cvt_f32_f16_e32 v11, v157
	v_sub_f32_e32 v11, 1.0, v11
	v_fma_mixlo_f16 v12, v11, v10, v157 op_sel:[0,0,1] op_sel_hi:[0,0,1]
	v_fma_mix_f32 v10, v11, v10, v157 op_sel:[0,0,1] op_sel_hi:[0,0,1]
	ds_write_b16 v5, v12 offset:36864
	v_cvt_f32_f16_e32 v11, v158
	v_sub_f32_e32 v11, 1.0, v11
	v_fma_mixlo_f16 v12, v11, v10, v158 op_sel:[0,0,1] op_sel_hi:[0,0,1]
	v_fma_mix_f32 v10, v11, v10, v158 op_sel:[0,0,1] op_sel_hi:[0,0,1]
	ds_write_b16 v5, v12 offset:35840
	v_cvt_f32_f16_e32 v11, v159
	v_sub_f32_e32 v11, 1.0, v11
	v_fma_mixlo_f16 v12, v11, v10, v159 op_sel:[0,0,1] op_sel_hi:[0,0,1]
	v_fma_mix_f32 v10, v11, v10, v159 op_sel:[0,0,1] op_sel_hi:[0,0,1]
	ds_write_b16 v5, v12 offset:34816
	v_cvt_f32_f16_e32 v11, v160
	v_sub_f32_e32 v11, 1.0, v11
	v_fma_mixlo_f16 v12, v11, v10, v160 op_sel:[0,0,1] op_sel_hi:[0,0,1]
	v_fma_mix_f32 v10, v11, v10, v160 op_sel:[0,0,1] op_sel_hi:[0,0,1]
	ds_write_b16 v5, v12 offset:33792
	v_cvt_f32_f16_e32 v11, v161
	v_sub_f32_e32 v11, 1.0, v11
	v_fma_mixlo_f16 v12, v11, v10, v161 op_sel:[0,0,1] op_sel_hi:[0,0,1]
	v_fma_mix_f32 v10, v11, v10, v161 op_sel:[0,0,1] op_sel_hi:[0,0,1]
	ds_write_b16 v5, v12 offset:32768
	global_load_dword v145, v3, s[22:23]
	s_add_u32 s22, s12, 0x17000
	s_addc_u32 s23, s13, 0
	global_load_dword v146, v3, s[22:23] offset:2048
	global_load_dword v147, v3, s[22:23]
	s_add_u32 s22, s12, 0x16000
	s_addc_u32 s23, s13, 0
	global_load_dword v148, v3, s[22:23] offset:2048
	global_load_dword v149, v3, s[22:23]
	s_add_u32 s22, s12, 0x15000
	s_addc_u32 s23, s13, 0
	global_load_dword v150, v3, s[22:23] offset:2048
	global_load_dword v151, v3, s[22:23]
	s_add_u32 s22, s12, 0x14000
	s_addc_u32 s23, s13, 0
	global_load_dword v152, v3, s[22:23] offset:2048
	global_load_dword v153, v3, s[22:23]
	s_add_u32 s22, s12, 0x13000
	s_addc_u32 s23, s13, 0
	global_load_dword v154, v3, s[22:23] offset:2048
	global_load_dword v155, v3, s[22:23]
	s_add_u32 s22, s12, 0x12000
	s_addc_u32 s23, s13, 0
	global_load_dword v156, v3, s[22:23] offset:2048
	global_load_dword v157, v3, s[22:23]
	s_add_u32 s22, s12, 0x11000
	s_addc_u32 s23, s13, 0
	global_load_dword v158, v3, s[22:23] offset:2048
	global_load_dword v159, v3, s[22:23]
	s_add_u32 s22, s12, 0x10000
	s_addc_u32 s23, s13, 0
	global_load_dword v160, v3, s[22:23] offset:2048
	s_waitcnt vmcnt(47)
; __device__ __forceinline__ void lru_pass2_unit(int cu, const h2* AD, const float2* LCS, const bf16* LG, bf16* MIX, lds_t* lds, int tid) {
;     ...
;     const h2* ad = AD + ((size_t)m0 * 2 + dir) * 256 + ch;
;     {
;         h2 fa[16], fb[16];
; #pragma unroll
;         for (int j = 0; j < 16; ++j) { const int r = dir == 0 ? j : 127 - j; fa[j] = ad[(size_t)r * 512]; }
; #pragma unroll 1
;         for (int r0 = 0; r0 < 128; r0 += 32) {
; #pragma unroll
;             for (int j = 0; j < 16; ++j) { const int r = dir == 0 ? r0 + 16 + j : 127 - (r0 + 16 + j); fb[j] = ad[(size_t)r * 512]; }
; #pragma unroll
;             for (int j = 0; j < 16; ++j) { const int r = dir == 0 ? r0 + j : 127 - (r0 + j); h = (1.0f - (float)fa[j][0]) * h + (float)fa[j][1]; HS[r * 512 + dir * 256 + ch] = (_Float16)h; }
;             if (r0 + 32 < 128) {
; #pragma unroll
;                 for (int j = 0; j < 16; ++j) { const int r = dir == 0 ? r0 + 32 + j : 127 - (r0 + 32 + j); fa[j] = ad[(size_t)r * 512]; } }
; #pragma unroll
;             for (int j = 0; j < 16; ++j) { const int r = dir == 0 ? r0 + 16 + j : 127 - (r0 + 16 + j); h = (1.0f - (float)fb[j][0]) * h + (float)fb[j][1]; HS[r * 512 + dir * 256 + ch] = (_Float16)h; } } }
	v_cvt_f32_f16_e32 v11, v162
	v_sub_f32_e32 v11, 1.0, v11
	v_fma_mixlo_f16 v12, v11, v10, v162 op_sel:[0,0,1] op_sel_hi:[0,0,1]
	v_fma_mix_f32 v10, v11, v10, v162 op_sel:[0,0,1] op_sel_hi:[0,0,1]
	ds_write_b16 v5, v12 offset:31744
	v_cvt_f32_f16_e32 v11, v163
	v_sub_f32_e32 v11, 1.0, v11
	v_fma_mixlo_f16 v12, v11, v10, v163 op_sel:[0,0,1] op_sel_hi:[0,0,1]
	v_fma_mix_f32 v10, v11, v10, v163 op_sel:[0,0,1] op_sel_hi:[0,0,1]
	ds_write_b16 v5, v12 offset:30720
	v_cvt_f32_f16_e32 v11, v164
	v_sub_f32_e32 v11, 1.0, v11
	v_fma_mixlo_f16 v12, v11, v10, v164 op_sel:[0,0,1] op_sel_hi:[0,0,1]
	v_fma_mix_f32 v10, v11, v10, v164 op_sel:[0,0,1] op_sel_hi:[0,0,1]
	ds_write_b16 v5, v12 offset:29696
	v_cvt_f32_f16_e32 v11, v165
	v_sub_f32_e32 v11, 1.0, v11
	v_fma_mixlo_f16 v12, v11, v10, v165 op_sel:[0,0,1] op_sel_hi:[0,0,1]
	v_fma_mix_f32 v10, v11, v10, v165 op_sel:[0,0,1] op_sel_hi:[0,0,1]
	ds_write_b16 v5, v12 offset:28672
	v_cvt_f32_f16_e32 v11, v166
	v_sub_f32_e32 v11, 1.0, v11
	v_fma_mixlo_f16 v12, v11, v10, v166 op_sel:[0,0,1] op_sel_hi:[0,0,1]
	v_fma_mix_f32 v10, v11, v10, v166 op_sel:[0,0,1] op_sel_hi:[0,0,1]
	ds_write_b16 v5, v12 offset:27648
	v_cvt_f32_f16_e32 v11, v167
	v_sub_f32_e32 v11, 1.0, v11
	v_fma_mixlo_f16 v12, v11, v10, v167 op_sel:[0,0,1] op_sel_hi:[0,0,1]
	v_fma_mix_f32 v10, v11, v10, v167 op_sel:[0,0,1] op_sel_hi:[0,0,1]
	ds_write_b16 v5, v12 offset:26624
	v_cvt_f32_f16_e32 v11, v168
	v_sub_f32_e32 v11, 1.0, v11
	v_fma_mixlo_f16 v12, v11, v10, v168 op_sel:[0,0,1] op_sel_hi:[0,0,1]
	v_fma_mix_f32 v10, v11, v10, v168 op_sel:[0,0,1] op_sel_hi:[0,0,1]
	ds_write_b16 v5, v12 offset:25600
	v_cvt_f32_f16_e32 v11, v169
	v_sub_f32_e32 v11, 1.0, v11
	v_fma_mixlo_f16 v12, v11, v10, v169 op_sel:[0,0,1] op_sel_hi:[0,0,1]
	v_fma_mix_f32 v10, v11, v10, v169 op_sel:[0,0,1] op_sel_hi:[0,0,1]
	ds_write_b16 v5, v12 offset:24576
	v_cvt_f32_f16_e32 v11, v170
	v_sub_f32_e32 v11, 1.0, v11
	v_fma_mixlo_f16 v12, v11, v10, v170 op_sel:[0,0,1] op_sel_hi:[0,0,1]
	v_fma_mix_f32 v10, v11, v10, v170 op_sel:[0,0,1] op_sel_hi:[0,0,1]
	ds_write_b16 v5, v12 offset:23552
	v_cvt_f32_f16_e32 v11, v171
	v_sub_f32_e32 v11, 1.0, v11
	v_fma_mixlo_f16 v12, v11, v10, v171 op_sel:[0,0,1] op_sel_hi:[0,0,1]
	v_fma_mix_f32 v10, v11, v10, v171 op_sel:[0,0,1] op_sel_hi:[0,0,1]
	ds_write_b16 v5, v12 offset:22528
	v_cvt_f32_f16_e32 v11, v172
	v_sub_f32_e32 v11, 1.0, v11
	v_fma_mixlo_f16 v12, v11, v10, v172 op_sel:[0,0,1] op_sel_hi:[0,0,1]
	v_fma_mix_f32 v10, v11, v10, v172 op_sel:[0,0,1] op_sel_hi:[0,0,1]
	ds_write_b16 v5, v12 offset:21504
	v_cvt_f32_f16_e32 v11, v173
	v_sub_f32_e32 v11, 1.0, v11
	v_fma_mixlo_f16 v12, v11, v10, v173 op_sel:[0,0,1] op_sel_hi:[0,0,1]
	v_fma_mix_f32 v10, v11, v10, v173 op_sel:[0,0,1] op_sel_hi:[0,0,1]
	ds_write_b16 v5, v12 offset:20480
	v_cvt_f32_f16_e32 v11, v174
	v_sub_f32_e32 v11, 1.0, v11
	v_fma_mixlo_f16 v12, v11, v10, v174 op_sel:[0,0,1] op_sel_hi:[0,0,1]
	v_fma_mix_f32 v10, v11, v10, v174 op_sel:[0,0,1] op_sel_hi:[0,0,1]
	ds_write_b16 v5, v12 offset:19456
	v_cvt_f32_f16_e32 v11, v175
	v_sub_f32_e32 v11, 1.0, v11
	v_fma_mixlo_f16 v12, v11, v10, v175 op_sel:[0,0,1] op_sel_hi:[0,0,1]
	v_fma_mix_f32 v10, v11, v10, v175 op_sel:[0,0,1] op_sel_hi:[0,0,1]
	ds_write_b16 v5, v12 offset:18432
	v_cvt_f32_f16_e32 v11, v176
	v_sub_f32_e32 v11, 1.0, v11
	v_fma_mixlo_f16 v12, v11, v10, v176 op_sel:[0,0,1] op_sel_hi:[0,0,1]
	v_fma_mix_f32 v10, v11, v10, v176 op_sel:[0,0,1] op_sel_hi:[0,0,1]
	ds_write_b16 v5, v12 offset:17408
	v_cvt_f32_f16_e32 v11, v177
	v_sub_f32_e32 v11, 1.0, v11
	v_fma_mixlo_f16 v12, v11, v10, v177 op_sel:[0,0,1] op_sel_hi:[0,0,1]
	v_fma_mix_f32 v10, v11, v10, v177 op_sel:[0,0,1] op_sel_hi:[0,0,1]
	ds_write_b16 v5, v12 offset:16384
	global_load_dword v161, v3, s[22:23]
	s_add_u32 s22, s12, 0xf000
	s_addc_u32 s23, s13, 0
	global_load_dword v162, v3, s[22:23] offset:2048
	global_load_dword v163, v3, s[22:23]
	s_add_u32 s22, s12, 0xe000
	s_addc_u32 s23, s13, 0
	global_load_dword v164, v3, s[22:23] offset:2048
	global_load_dword v165, v3, s[22:23]
	s_add_u32 s22, s12, 0xd000
	s_addc_u32 s23, s13, 0
	global_load_dword v166, v3, s[22:23] offset:2048
	global_load_dword v167, v3, s[22:23]
	s_add_u32 s22, s12, 0xc000
	s_addc_u32 s23, s13, 0
	global_load_dword v168, v3, s[22:23] offset:2048
	global_load_dword v169, v3, s[22:23]
	s_add_u32 s22, s12, 0xb000
	s_addc_u32 s23, s13, 0
	global_load_dword v170, v3, s[22:23] offset:2048
	global_load_dword v171, v3, s[22:23]
	s_add_u32 s22, s12, 0xa000
	s_addc_u32 s23, s13, 0
	global_load_dword v172, v3, s[22:23] offset:2048
	global_load_dword v173, v3, s[22:23]
	s_add_u32 s22, s12, 0x9000
	s_addc_u32 s23, s13, 0
	global_load_dword v174, v3, s[22:23] offset:2048
	global_load_dword v175, v3, s[22:23]
	s_add_u32 s22, s12, 0x8000
	s_addc_u32 s23, s13, 0
	global_load_dword v176, v3, s[22:23] offset:2048
	s_waitcnt vmcnt(47)
; __device__ __forceinline__ void lru_pass2_unit(int cu, const h2* AD, const float2* LCS, const bf16* LG, bf16* MIX, lds_t* lds, int tid) {
;     ...
;     const h2* ad = AD + ((size_t)m0 * 2 + dir) * 256 + ch;
;     {
;         h2 fa[16], fb[16];
; #pragma unroll
;         for (int j = 0; j < 16; ++j) { const int r = dir == 0 ? j : 127 - j; fa[j] = ad[(size_t)r * 512]; }
; #pragma unroll 1
;         for (int r0 = 0; r0 < 128; r0 += 32) {
; #pragma unroll
;             for (int j = 0; j < 16; ++j) { const int r = dir == 0 ? r0 + 16 + j : 127 - (r0 + 16 + j); fb[j] = ad[(size_t)r * 512]; }
; #pragma unroll
;             for (int j = 0; j < 16; ++j) { const int r = dir == 0 ? r0 + j : 127 - (r0 + j); h = (1.0f - (float)fa[j][0]) * h + (float)fa[j][1]; HS[r * 512 + dir * 256 + ch] = (_Float16)h; }
;             if (r0 + 32 < 128) {
; #pragma unroll
;                 for (int j = 0; j < 16; ++j) { const int r = dir == 0 ? r0 + 32 + j : 127 - (r0 + 32 + j); fa[j] = ad[(size_t)r * 512]; } }
; #pragma unroll
;             for (int j = 0; j < 16; ++j) { const int r = dir == 0 ? r0 + 16 + j : 127 - (r0 + 16 + j); h = (1.0f - (float)fb[j][0]) * h + (float)fb[j][1]; HS[r * 512 + dir * 256 + ch] = (_Float16)h; } } }
	v_cvt_f32_f16_e32 v11, v178
	v_sub_f32_e32 v11, 1.0, v11
	v_fma_mixlo_f16 v12, v11, v10, v178 op_sel:[0,0,1] op_sel_hi:[0,0,1]
	v_fma_mix_f32 v10, v11, v10, v178 op_sel:[0,0,1] op_sel_hi:[0,0,1]
	ds_write_b16 v5, v12 offset:15360
	v_cvt_f32_f16_e32 v11, v179
	v_sub_f32_e32 v11, 1.0, v11
	v_fma_mixlo_f16 v12, v11, v10, v179 op_sel:[0,0,1] op_sel_hi:[0,0,1]
	v_fma_mix_f32 v10, v11, v10, v179 op_sel:[0,0,1] op_sel_hi:[0,0,1]
	ds_write_b16 v5, v12 offset:14336
	v_cvt_f32_f16_e32 v11, v180
	v_sub_f32_e32 v11, 1.0, v11
	v_fma_mixlo_f16 v12, v11, v10, v180 op_sel:[0,0,1] op_sel_hi:[0,0,1]
	v_fma_mix_f32 v10, v11, v10, v180 op_sel:[0,0,1] op_sel_hi:[0,0,1]
	ds_write_b16 v5, v12 offset:13312
	v_cvt_f32_f16_e32 v11, v181
	v_sub_f32_e32 v11, 1.0, v11
	v_fma_mixlo_f16 v12, v11, v10, v181 op_sel:[0,0,1] op_sel_hi:[0,0,1]
	v_fma_mix_f32 v10, v11, v10, v181 op_sel:[0,0,1] op_sel_hi:[0,0,1]
	ds_write_b16 v5, v12 offset:12288
	v_cvt_f32_f16_e32 v11, v182
	v_sub_f32_e32 v11, 1.0, v11
	v_fma_mixlo_f16 v12, v11, v10, v182 op_sel:[0,0,1] op_sel_hi:[0,0,1]
	v_fma_mix_f32 v10, v11, v10, v182 op_sel:[0,0,1] op_sel_hi:[0,0,1]
	ds_write_b16 v5, v12 offset:11264
	v_cvt_f32_f16_e32 v11, v183
	v_sub_f32_e32 v11, 1.0, v11
	v_fma_mixlo_f16 v12, v11, v10, v183 op_sel:[0,0,1] op_sel_hi:[0,0,1]
	v_fma_mix_f32 v10, v11, v10, v183 op_sel:[0,0,1] op_sel_hi:[0,0,1]
	ds_write_b16 v5, v12 offset:10240
	v_cvt_f32_f16_e32 v11, v184
	v_sub_f32_e32 v11, 1.0, v11
	v_fma_mixlo_f16 v12, v11, v10, v184 op_sel:[0,0,1] op_sel_hi:[0,0,1]
	v_fma_mix_f32 v10, v11, v10, v184 op_sel:[0,0,1] op_sel_hi:[0,0,1]
	ds_write_b16 v5, v12 offset:9216
	v_cvt_f32_f16_e32 v11, v185
	v_sub_f32_e32 v11, 1.0, v11
	v_fma_mixlo_f16 v12, v11, v10, v185 op_sel:[0,0,1] op_sel_hi:[0,0,1]
	v_fma_mix_f32 v10, v11, v10, v185 op_sel:[0,0,1] op_sel_hi:[0,0,1]
	ds_write_b16 v5, v12 offset:8192
	v_cvt_f32_f16_e32 v11, v186
	v_sub_f32_e32 v11, 1.0, v11
	v_fma_mixlo_f16 v12, v11, v10, v186 op_sel:[0,0,1] op_sel_hi:[0,0,1]
	v_fma_mix_f32 v10, v11, v10, v186 op_sel:[0,0,1] op_sel_hi:[0,0,1]
	ds_write_b16 v5, v12 offset:7168
	v_cvt_f32_f16_e32 v11, v187
	v_sub_f32_e32 v11, 1.0, v11
	v_fma_mixlo_f16 v12, v11, v10, v187 op_sel:[0,0,1] op_sel_hi:[0,0,1]
	v_fma_mix_f32 v10, v11, v10, v187 op_sel:[0,0,1] op_sel_hi:[0,0,1]
	ds_write_b16 v5, v12 offset:6144
	v_cvt_f32_f16_e32 v11, v188
	v_sub_f32_e32 v11, 1.0, v11
	v_fma_mixlo_f16 v12, v11, v10, v188 op_sel:[0,0,1] op_sel_hi:[0,0,1]
	v_fma_mix_f32 v10, v11, v10, v188 op_sel:[0,0,1] op_sel_hi:[0,0,1]
	ds_write_b16 v5, v12 offset:5120
	v_cvt_f32_f16_e32 v11, v189
	v_sub_f32_e32 v11, 1.0, v11
	v_fma_mixlo_f16 v12, v11, v10, v189 op_sel:[0,0,1] op_sel_hi:[0,0,1]
	v_fma_mix_f32 v10, v11, v10, v189 op_sel:[0,0,1] op_sel_hi:[0,0,1]
	ds_write_b16 v5, v12 offset:4096
	v_cvt_f32_f16_e32 v11, v190
	v_sub_f32_e32 v11, 1.0, v11
	v_fma_mixlo_f16 v12, v11, v10, v190 op_sel:[0,0,1] op_sel_hi:[0,0,1]
	v_fma_mix_f32 v10, v11, v10, v190 op_sel:[0,0,1] op_sel_hi:[0,0,1]
	ds_write_b16 v5, v12 offset:3072
	v_cvt_f32_f16_e32 v11, v191
	v_sub_f32_e32 v11, 1.0, v11
	v_fma_mixlo_f16 v12, v11, v10, v191 op_sel:[0,0,1] op_sel_hi:[0,0,1]
	v_fma_mix_f32 v10, v11, v10, v191 op_sel:[0,0,1] op_sel_hi:[0,0,1]
	ds_write_b16 v5, v12 offset:2048
	v_cvt_f32_f16_e32 v11, v192
	v_sub_f32_e32 v11, 1.0, v11
	v_fma_mixlo_f16 v12, v11, v10, v192 op_sel:[0,0,1] op_sel_hi:[0,0,1]
	v_fma_mix_f32 v10, v11, v10, v192 op_sel:[0,0,1] op_sel_hi:[0,0,1]
	ds_write_b16 v5, v12 offset:1024
	v_cvt_f32_f16_e32 v11, v193
	v_sub_f32_e32 v11, 1.0, v11
	v_fma_mixlo_f16 v12, v11, v10, v193 op_sel:[0,0,1] op_sel_hi:[0,0,1]
	v_fma_mix_f32 v10, v11, v10, v193 op_sel:[0,0,1] op_sel_hi:[0,0,1]
	ds_write_b16 v5, v12 offset:0
	global_load_dword v177, v3, s[22:23]
	s_add_u32 s22, s12, 0x7000
	s_addc_u32 s23, s13, 0
	global_load_dword v178, v3, s[22:23] offset:2048
	global_load_dword v179, v3, s[22:23]
	s_add_u32 s22, s12, 0x6000
	s_addc_u32 s23, s13, 0
	global_load_dword v180, v3, s[22:23] offset:2048
	global_load_dword v181, v3, s[22:23]
	s_add_u32 s22, s12, 0x5000
	s_addc_u32 s23, s13, 0
	global_load_dword v182, v3, s[22:23] offset:2048
	global_load_dword v183, v3, s[22:23]
	s_add_u32 s22, s12, 0x4000
	s_addc_u32 s23, s13, 0
	global_load_dword v184, v3, s[22:23] offset:2048
	global_load_dword v185, v3, s[22:23]
	s_add_u32 s22, s12, 0x3000
	s_addc_u32 s23, s13, 0
	global_load_dword v186, v3, s[22:23] offset:2048
	global_load_dword v187, v3, s[22:23]
	s_add_u32 s22, s12, 0x2000
	s_addc_u32 s23, s13, 0
	global_load_dword v188, v3, s[22:23] offset:2048
	global_load_dword v189, v3, s[22:23]
	s_add_u32 s22, s12, 0x1000
	s_addc_u32 s23, s13, 0
	global_load_dword v190, v3, s[22:23] offset:2048
	global_load_dword v191, v3, s[22:23]
	s_add_u32 s22, s12, 0x0
	s_addc_u32 s23, s13, 0
	global_load_dword v192, v3, s[22:23] offset:2048
	s_waitcnt vmcnt(47)
; #define LAS __attribute__((address_space(3)))
; __device__ __forceinline__ void lru_pass2_unit(int cu, const h2* AD, const float2* LCS, const bf16* LG, bf16* MIX, lds_t* lds, int tid) {
;     ...
;     const h2* ad = AD + ((size_t)m0 * 2 + dir) * 256 + ch;
;     {
;         h2 fa[16], fb[16];
; #pragma unroll
;         for (int j = 0; j < 16; ++j) { const int r = dir == 0 ? j : 127 - j; fa[j] = ad[(size_t)r * 512]; }
; #pragma unroll 1
;         for (int r0 = 0; r0 < 128; r0 += 32) {
; #pragma unroll
;             for (int j = 0; j < 16; ++j) { const int r = dir == 0 ? r0 + 16 + j : 127 - (r0 + 16 + j); fb[j] = ad[(size_t)r * 512]; }
; #pragma unroll
;             for (int j = 0; j < 16; ++j) { const int r = dir == 0 ? r0 + j : 127 - (r0 + j); h = (1.0f - (float)fa[j][0]) * h + (float)fa[j][1]; HS[r * 512 + dir * 256 + ch] = (_Float16)h; }
;             if (r0 + 32 < 128) {
; #pragma unroll
;                 for (int j = 0; j < 16; ++j) { const int r = dir == 0 ? r0 + 32 + j : 127 - (r0 + 32 + j); fa[j] = ad[(size_t)r * 512]; } }
; #pragma unroll
;             for (int j = 0; j < 16; ++j) { const int r = dir == 0 ? r0 + 16 + j : 127 - (r0 + 16 + j); h = (1.0f - (float)fb[j][0]) * h + (float)fb[j][1]; HS[r * 512 + dir * 256 + ch] = (_Float16)h; } } }
;     __syncthreads();
;     { typedef _Float16 h8 __attribute__((ext_vector_type(8))); const int c8 = (tid & 31) * 8;
; #pragma unroll 4
;         for (int i = 0; i < 8; ++i) { const int r = (tid >> 5) + 16 * i; const h8 hf = *(const LAS h8*)(HS + r * 512 + c8), hb = *(const LAS h8*)(HS + r * 512 + 256 + c8);
;             const v4u g = *(const v4u*)(LG + (size_t)(m0 + r) * 256 + c8); v4u o;
	v_cvt_f32_f16_e32 v11, v130
	v_sub_f32_e32 v11, 1.0, v11
	v_fma_mixlo_f16 v12, v11, v10, v130 op_sel:[0,0,1] op_sel_hi:[0,0,1]
	v_fma_mix_f32 v10, v11, v10, v130 op_sel:[0,0,1] op_sel_hi:[0,0,1]
	ds_write_b16 v4, v12 offset:64512
	v_cvt_f32_f16_e32 v11, v131
	v_sub_f32_e32 v11, 1.0, v11
	v_fma_mixlo_f16 v12, v11, v10, v131 op_sel:[0,0,1] op_sel_hi:[0,0,1]
	v_fma_mix_f32 v10, v11, v10, v131 op_sel:[0,0,1] op_sel_hi:[0,0,1]
	ds_write_b16 v4, v12 offset:63488
	v_cvt_f32_f16_e32 v11, v132
	v_sub_f32_e32 v11, 1.0, v11
	v_fma_mixlo_f16 v12, v11, v10, v132 op_sel:[0,0,1] op_sel_hi:[0,0,1]
	v_fma_mix_f32 v10, v11, v10, v132 op_sel:[0,0,1] op_sel_hi:[0,0,1]
	ds_write_b16 v4, v12 offset:62464
	v_cvt_f32_f16_e32 v11, v133
	v_sub_f32_e32 v11, 1.0, v11
	v_fma_mixlo_f16 v12, v11, v10, v133 op_sel:[0,0,1] op_sel_hi:[0,0,1]
	v_fma_mix_f32 v10, v11, v10, v133 op_sel:[0,0,1] op_sel_hi:[0,0,1]
	ds_write_b16 v4, v12 offset:61440
	v_cvt_f32_f16_e32 v11, v134
	v_sub_f32_e32 v11, 1.0, v11
	v_fma_mixlo_f16 v12, v11, v10, v134 op_sel:[0,0,1] op_sel_hi:[0,0,1]
	v_fma_mix_f32 v10, v11, v10, v134 op_sel:[0,0,1] op_sel_hi:[0,0,1]
	ds_write_b16 v4, v12 offset:60416
	v_cvt_f32_f16_e32 v11, v135
	v_sub_f32_e32 v11, 1.0, v11
	v_fma_mixlo_f16 v12, v11, v10, v135 op_sel:[0,0,1] op_sel_hi:[0,0,1]
	v_fma_mix_f32 v10, v11, v10, v135 op_sel:[0,0,1] op_sel_hi:[0,0,1]
	ds_write_b16 v4, v12 offset:59392
	v_cvt_f32_f16_e32 v11, v136
	v_sub_f32_e32 v11, 1.0, v11
	v_fma_mixlo_f16 v12, v11, v10, v136 op_sel:[0,0,1] op_sel_hi:[0,0,1]
	v_fma_mix_f32 v10, v11, v10, v136 op_sel:[0,0,1] op_sel_hi:[0,0,1]
	ds_write_b16 v4, v12 offset:58368
	v_cvt_f32_f16_e32 v11, v137
	v_sub_f32_e32 v11, 1.0, v11
	v_fma_mixlo_f16 v12, v11, v10, v137 op_sel:[0,0,1] op_sel_hi:[0,0,1]
	v_fma_mix_f32 v10, v11, v10, v137 op_sel:[0,0,1] op_sel_hi:[0,0,1]
	ds_write_b16 v4, v12 offset:57344
	v_cvt_f32_f16_e32 v11, v138
	v_sub_f32_e32 v11, 1.0, v11
	v_fma_mixlo_f16 v12, v11, v10, v138 op_sel:[0,0,1] op_sel_hi:[0,0,1]
	v_fma_mix_f32 v10, v11, v10, v138 op_sel:[0,0,1] op_sel_hi:[0,0,1]
	ds_write_b16 v4, v12 offset:56320
	v_cvt_f32_f16_e32 v11, v139
	v_sub_f32_e32 v11, 1.0, v11
	v_fma_mixlo_f16 v12, v11, v10, v139 op_sel:[0,0,1] op_sel_hi:[0,0,1]
	v_fma_mix_f32 v10, v11, v10, v139 op_sel:[0,0,1] op_sel_hi:[0,0,1]
	ds_write_b16 v4, v12 offset:55296
	v_cvt_f32_f16_e32 v11, v140
	v_sub_f32_e32 v11, 1.0, v11
	v_fma_mixlo_f16 v12, v11, v10, v140 op_sel:[0,0,1] op_sel_hi:[0,0,1]
	v_fma_mix_f32 v10, v11, v10, v140 op_sel:[0,0,1] op_sel_hi:[0,0,1]
	ds_write_b16 v4, v12 offset:54272
	v_cvt_f32_f16_e32 v11, v141
	v_sub_f32_e32 v11, 1.0, v11
	v_fma_mixlo_f16 v12, v11, v10, v141 op_sel:[0,0,1] op_sel_hi:[0,0,1]
	v_fma_mix_f32 v10, v11, v10, v141 op_sel:[0,0,1] op_sel_hi:[0,0,1]
	ds_write_b16 v4, v12 offset:53248
	v_cvt_f32_f16_e32 v11, v142
	v_sub_f32_e32 v11, 1.0, v11
	v_fma_mixlo_f16 v12, v11, v10, v142 op_sel:[0,0,1] op_sel_hi:[0,0,1]
	v_fma_mix_f32 v10, v11, v10, v142 op_sel:[0,0,1] op_sel_hi:[0,0,1]
	ds_write_b16 v4, v12 offset:52224
	v_cvt_f32_f16_e32 v11, v143
	v_sub_f32_e32 v11, 1.0, v11
	v_fma_mixlo_f16 v12, v11, v10, v143 op_sel:[0,0,1] op_sel_hi:[0,0,1]
	v_fma_mix_f32 v10, v11, v10, v143 op_sel:[0,0,1] op_sel_hi:[0,0,1]
	ds_write_b16 v4, v12 offset:51200
	v_cvt_f32_f16_e32 v11, v144
	v_sub_f32_e32 v11, 1.0, v11
	v_fma_mixlo_f16 v12, v11, v10, v144 op_sel:[0,0,1] op_sel_hi:[0,0,1]
	v_fma_mix_f32 v10, v11, v10, v144 op_sel:[0,0,1] op_sel_hi:[0,0,1]
	ds_write_b16 v4, v12 offset:50176
	v_cvt_f32_f16_e32 v11, v145
	v_sub_f32_e32 v11, 1.0, v11
	v_fma_mixlo_f16 v12, v11, v10, v145 op_sel:[0,0,1] op_sel_hi:[0,0,1]
	v_fma_mix_f32 v10, v11, v10, v145 op_sel:[0,0,1] op_sel_hi:[0,0,1]
	ds_write_b16 v4, v12 offset:49152
	global_load_dword v193, v3, s[22:23]
	s_mov_b32 s20, s14
	s_mov_b32 s21, s15
	global_load_dwordx4 v[86:89], v8, s[20:21]
	s_add_u32 s20, s20, 0x2000
	s_addc_u32 s21, s21, 0
	global_load_dwordx4 v[90:93], v8, s[20:21]
	s_add_u32 s20, s20, 0x2000
	s_addc_u32 s21, s21, 0
	global_load_dwordx4 v[94:97], v8, s[20:21]
	s_add_u32 s20, s20, 0x2000
	s_addc_u32 s21, s21, 0
	global_load_dwordx4 v[98:101], v8, s[20:21]
	s_add_u32 s20, s20, 0x2000
	s_addc_u32 s21, s21, 0
	global_load_dwordx4 v[102:105], v8, s[20:21]
	s_add_u32 s20, s20, 0x2000
	s_addc_u32 s21, s21, 0
	global_load_dwordx4 v[106:109], v8, s[20:21]
	s_add_u32 s20, s20, 0x2000
	s_addc_u32 s21, s21, 0
	global_load_dwordx4 v[110:113], v8, s[20:21]
	s_add_u32 s20, s20, 0x2000
	s_addc_u32 s21, s21, 0
	global_load_dwordx4 v[226:229], v8, s[20:21]
	s_waitcnt vmcnt(40)
; __device__ __forceinline__ void lru_pass2_unit(int cu, const h2* AD, const float2* LCS, const bf16* LG, bf16* MIX, lds_t* lds, int tid) {
;     ...
;     const h2* ad = AD + ((size_t)m0 * 2 + dir) * 256 + ch;
;     {
;         h2 fa[16], fb[16];
; #pragma unroll
;         for (int j = 0; j < 16; ++j) { const int r = dir == 0 ? j : 127 - j; fa[j] = ad[(size_t)r * 512]; }
; #pragma unroll 1
;         for (int r0 = 0; r0 < 128; r0 += 32) {
; #pragma unroll
;             for (int j = 0; j < 16; ++j) { const int r = dir == 0 ? r0 + 16 + j : 127 - (r0 + 16 + j); fb[j] = ad[(size_t)r * 512]; }
; #pragma unroll
;             for (int j = 0; j < 16; ++j) { const int r = dir == 0 ? r0 + j : 127 - (r0 + j); h = (1.0f - (float)fa[j][0]) * h + (float)fa[j][1]; HS[r * 512 + dir * 256 + ch] = (_Float16)h; }
;             if (r0 + 32 < 128) {
; #pragma unroll
;                 for (int j = 0; j < 16; ++j) { const int r = dir == 0 ? r0 + 32 + j : 127 - (r0 + 32 + j); fa[j] = ad[(size_t)r * 512]; } }
; #pragma unroll
;             for (int j = 0; j < 16; ++j) { const int r = dir == 0 ? r0 + 16 + j : 127 - (r0 + 16 + j); h = (1.0f - (float)fb[j][0]) * h + (float)fb[j][1]; HS[r * 512 + dir * 256 + ch] = (_Float16)h; } } }
	v_cvt_f32_f16_e32 v11, v146
	v_sub_f32_e32 v11, 1.0, v11
	v_fma_mixlo_f16 v12, v11, v10, v146 op_sel:[0,0,1] op_sel_hi:[0,0,1]
	v_fma_mix_f32 v10, v11, v10, v146 op_sel:[0,0,1] op_sel_hi:[0,0,1]
	ds_write_b16 v4, v12 offset:48128
	v_cvt_f32_f16_e32 v11, v147
	v_sub_f32_e32 v11, 1.0, v11
	v_fma_mixlo_f16 v12, v11, v10, v147 op_sel:[0,0,1] op_sel_hi:[0,0,1]
	v_fma_mix_f32 v10, v11, v10, v147 op_sel:[0,0,1] op_sel_hi:[0,0,1]
	ds_write_b16 v4, v12 offset:47104
	v_cvt_f32_f16_e32 v11, v148
	v_sub_f32_e32 v11, 1.0, v11
	v_fma_mixlo_f16 v12, v11, v10, v148 op_sel:[0,0,1] op_sel_hi:[0,0,1]
	v_fma_mix_f32 v10, v11, v10, v148 op_sel:[0,0,1] op_sel_hi:[0,0,1]
	ds_write_b16 v4, v12 offset:46080
	v_cvt_f32_f16_e32 v11, v149
	v_sub_f32_e32 v11, 1.0, v11
	v_fma_mixlo_f16 v12, v11, v10, v149 op_sel:[0,0,1] op_sel_hi:[0,0,1]
	v_fma_mix_f32 v10, v11, v10, v149 op_sel:[0,0,1] op_sel_hi:[0,0,1]
	ds_write_b16 v4, v12 offset:45056
	v_cvt_f32_f16_e32 v11, v150
	v_sub_f32_e32 v11, 1.0, v11
	v_fma_mixlo_f16 v12, v11, v10, v150 op_sel:[0,0,1] op_sel_hi:[0,0,1]
	v_fma_mix_f32 v10, v11, v10, v150 op_sel:[0,0,1] op_sel_hi:[0,0,1]
	ds_write_b16 v4, v12 offset:44032
	v_cvt_f32_f16_e32 v11, v151
	v_sub_f32_e32 v11, 1.0, v11
	v_fma_mixlo_f16 v12, v11, v10, v151 op_sel:[0,0,1] op_sel_hi:[0,0,1]
	v_fma_mix_f32 v10, v11, v10, v151 op_sel:[0,0,1] op_sel_hi:[0,0,1]
	ds_write_b16 v4, v12 offset:43008
	v_cvt_f32_f16_e32 v11, v152
	v_sub_f32_e32 v11, 1.0, v11
	v_fma_mixlo_f16 v12, v11, v10, v152 op_sel:[0,0,1] op_sel_hi:[0,0,1]
	v_fma_mix_f32 v10, v11, v10, v152 op_sel:[0,0,1] op_sel_hi:[0,0,1]
	ds_write_b16 v4, v12 offset:41984
	v_cvt_f32_f16_e32 v11, v153
	v_sub_f32_e32 v11, 1.0, v11
	v_fma_mixlo_f16 v12, v11, v10, v153 op_sel:[0,0,1] op_sel_hi:[0,0,1]
	v_fma_mix_f32 v10, v11, v10, v153 op_sel:[0,0,1] op_sel_hi:[0,0,1]
	ds_write_b16 v4, v12 offset:40960
	v_cvt_f32_f16_e32 v11, v154
	v_sub_f32_e32 v11, 1.0, v11
	v_fma_mixlo_f16 v12, v11, v10, v154 op_sel:[0,0,1] op_sel_hi:[0,0,1]
	v_fma_mix_f32 v10, v11, v10, v154 op_sel:[0,0,1] op_sel_hi:[0,0,1]
	ds_write_b16 v4, v12 offset:39936
	v_cvt_f32_f16_e32 v11, v155
	v_sub_f32_e32 v11, 1.0, v11
	v_fma_mixlo_f16 v12, v11, v10, v155 op_sel:[0,0,1] op_sel_hi:[0,0,1]
	v_fma_mix_f32 v10, v11, v10, v155 op_sel:[0,0,1] op_sel_hi:[0,0,1]
	ds_write_b16 v4, v12 offset:38912
	v_cvt_f32_f16_e32 v11, v156
	v_sub_f32_e32 v11, 1.0, v11
	v_fma_mixlo_f16 v12, v11, v10, v156 op_sel:[0,0,1] op_sel_hi:[0,0,1]
	v_fma_mix_f32 v10, v11, v10, v156 op_sel:[0,0,1] op_sel_hi:[0,0,1]
	ds_write_b16 v4, v12 offset:37888
	v_cvt_f32_f16_e32 v11, v157
	v_sub_f32_e32 v11, 1.0, v11
	v_fma_mixlo_f16 v12, v11, v10, v157 op_sel:[0,0,1] op_sel_hi:[0,0,1]
	v_fma_mix_f32 v10, v11, v10, v157 op_sel:[0,0,1] op_sel_hi:[0,0,1]
	ds_write_b16 v4, v12 offset:36864
	v_cvt_f32_f16_e32 v11, v158
	v_sub_f32_e32 v11, 1.0, v11
	v_fma_mixlo_f16 v12, v11, v10, v158 op_sel:[0,0,1] op_sel_hi:[0,0,1]
	v_fma_mix_f32 v10, v11, v10, v158 op_sel:[0,0,1] op_sel_hi:[0,0,1]
	ds_write_b16 v4, v12 offset:35840
	v_cvt_f32_f16_e32 v11, v159
	v_sub_f32_e32 v11, 1.0, v11
	v_fma_mixlo_f16 v12, v11, v10, v159 op_sel:[0,0,1] op_sel_hi:[0,0,1]
	v_fma_mix_f32 v10, v11, v10, v159 op_sel:[0,0,1] op_sel_hi:[0,0,1]
	ds_write_b16 v4, v12 offset:34816
	v_cvt_f32_f16_e32 v11, v160
	v_sub_f32_e32 v11, 1.0, v11
	v_fma_mixlo_f16 v12, v11, v10, v160 op_sel:[0,0,1] op_sel_hi:[0,0,1]
	v_fma_mix_f32 v10, v11, v10, v160 op_sel:[0,0,1] op_sel_hi:[0,0,1]
	ds_write_b16 v4, v12 offset:33792
	v_cvt_f32_f16_e32 v11, v161
	v_sub_f32_e32 v11, 1.0, v11
	v_fma_mixlo_f16 v12, v11, v10, v161 op_sel:[0,0,1] op_sel_hi:[0,0,1]
	v_fma_mix_f32 v10, v11, v10, v161 op_sel:[0,0,1] op_sel_hi:[0,0,1]
	ds_write_b16 v4, v12 offset:32768
	s_waitcnt vmcnt(24)
	v_cvt_f32_f16_e32 v11, v162
	v_sub_f32_e32 v11, 1.0, v11
	v_fma_mixlo_f16 v12, v11, v10, v162 op_sel:[0,0,1] op_sel_hi:[0,0,1]
	v_fma_mix_f32 v10, v11, v10, v162 op_sel:[0,0,1] op_sel_hi:[0,0,1]
	ds_write_b16 v4, v12 offset:31744
	v_cvt_f32_f16_e32 v11, v163
	v_sub_f32_e32 v11, 1.0, v11
	v_fma_mixlo_f16 v12, v11, v10, v163 op_sel:[0,0,1] op_sel_hi:[0,0,1]
	v_fma_mix_f32 v10, v11, v10, v163 op_sel:[0,0,1] op_sel_hi:[0,0,1]
	ds_write_b16 v4, v12 offset:30720
	v_cvt_f32_f16_e32 v11, v164
	v_sub_f32_e32 v11, 1.0, v11
	v_fma_mixlo_f16 v12, v11, v10, v164 op_sel:[0,0,1] op_sel_hi:[0,0,1]
	v_fma_mix_f32 v10, v11, v10, v164 op_sel:[0,0,1] op_sel_hi:[0,0,1]
	ds_write_b16 v4, v12 offset:29696
	v_cvt_f32_f16_e32 v11, v165
	v_sub_f32_e32 v11, 1.0, v11
	v_fma_mixlo_f16 v12, v11, v10, v165 op_sel:[0,0,1] op_sel_hi:[0,0,1]
	v_fma_mix_f32 v10, v11, v10, v165 op_sel:[0,0,1] op_sel_hi:[0,0,1]
	ds_write_b16 v4, v12 offset:28672
	v_cvt_f32_f16_e32 v11, v166
	v_sub_f32_e32 v11, 1.0, v11
	v_fma_mixlo_f16 v12, v11, v10, v166 op_sel:[0,0,1] op_sel_hi:[0,0,1]
	v_fma_mix_f32 v10, v11, v10, v166 op_sel:[0,0,1] op_sel_hi:[0,0,1]
	ds_write_b16 v4, v12 offset:27648
	v_cvt_f32_f16_e32 v11, v167
	v_sub_f32_e32 v11, 1.0, v11
	v_fma_mixlo_f16 v12, v11, v10, v167 op_sel:[0,0,1] op_sel_hi:[0,0,1]
	v_fma_mix_f32 v10, v11, v10, v167 op_sel:[0,0,1] op_sel_hi:[0,0,1]
	ds_write_b16 v4, v12 offset:26624
	v_cvt_f32_f16_e32 v11, v168
	v_sub_f32_e32 v11, 1.0, v11
	v_fma_mixlo_f16 v12, v11, v10, v168 op_sel:[0,0,1] op_sel_hi:[0,0,1]
	v_fma_mix_f32 v10, v11, v10, v168 op_sel:[0,0,1] op_sel_hi:[0,0,1]
	ds_write_b16 v4, v12 offset:25600
	v_cvt_f32_f16_e32 v11, v169
	v_sub_f32_e32 v11, 1.0, v11
	v_fma_mixlo_f16 v12, v11, v10, v169 op_sel:[0,0,1] op_sel_hi:[0,0,1]
	v_fma_mix_f32 v10, v11, v10, v169 op_sel:[0,0,1] op_sel_hi:[0,0,1]
	ds_write_b16 v4, v12 offset:24576
	v_cvt_f32_f16_e32 v11, v170
	v_sub_f32_e32 v11, 1.0, v11
; __device__ __forceinline__ void lru_pass2_unit(int cu, const h2* AD, const float2* LCS, const bf16* LG, bf16* MIX, lds_t* lds, int tid) {
;     ...
;     const h2* ad = AD + ((size_t)m0 * 2 + dir) * 256 + ch;
;     {
;         h2 fa[16], fb[16];
; #pragma unroll
;         for (int j = 0; j < 16; ++j) { const int r = dir == 0 ? j : 127 - j; fa[j] = ad[(size_t)r * 512]; }
; #pragma unroll 1
;         for (int r0 = 0; r0 < 128; r0 += 32) {
; #pragma unroll
;             for (int j = 0; j < 16; ++j) { const int r = dir == 0 ? r0 + 16 + j : 127 - (r0 + 16 + j); fb[j] = ad[(size_t)r * 512]; }
; #pragma unroll
;             for (int j = 0; j < 16; ++j) { const int r = dir == 0 ? r0 + j : 127 - (r0 + j); h = (1.0f - (float)fa[j][0]) * h + (float)fa[j][1]; HS[r * 512 + dir * 256 + ch] = (_Float16)h; }
;             if (r0 + 32 < 128) {
; #pragma unroll
;                 for (int j = 0; j < 16; ++j) { const int r = dir == 0 ? r0 + 32 + j : 127 - (r0 + 32 + j); fa[j] = ad[(size_t)r * 512]; } }
; #pragma unroll
;             for (int j = 0; j < 16; ++j) { const int r = dir == 0 ? r0 + 16 + j : 127 - (r0 + 16 + j); h = (1.0f - (float)fb[j][0]) * h + (float)fb[j][1]; HS[r * 512 + dir * 256 + ch] = (_Float16)h; } } }
	v_fma_mixlo_f16 v12, v11, v10, v170 op_sel:[0,0,1] op_sel_hi:[0,0,1]
	v_fma_mix_f32 v10, v11, v10, v170 op_sel:[0,0,1] op_sel_hi:[0,0,1]
	ds_write_b16 v4, v12 offset:23552
	v_cvt_f32_f16_e32 v11, v171
	v_sub_f32_e32 v11, 1.0, v11
	v_fma_mixlo_f16 v12, v11, v10, v171 op_sel:[0,0,1] op_sel_hi:[0,0,1]
	v_fma_mix_f32 v10, v11, v10, v171 op_sel:[0,0,1] op_sel_hi:[0,0,1]
	ds_write_b16 v4, v12 offset:22528
	v_cvt_f32_f16_e32 v11, v172
	v_sub_f32_e32 v11, 1.0, v11
	v_fma_mixlo_f16 v12, v11, v10, v172 op_sel:[0,0,1] op_sel_hi:[0,0,1]
	v_fma_mix_f32 v10, v11, v10, v172 op_sel:[0,0,1] op_sel_hi:[0,0,1]
	ds_write_b16 v4, v12 offset:21504
	v_cvt_f32_f16_e32 v11, v173
	v_sub_f32_e32 v11, 1.0, v11
	v_fma_mixlo_f16 v12, v11, v10, v173 op_sel:[0,0,1] op_sel_hi:[0,0,1]
	v_fma_mix_f32 v10, v11, v10, v173 op_sel:[0,0,1] op_sel_hi:[0,0,1]
	ds_write_b16 v4, v12 offset:20480
	v_cvt_f32_f16_e32 v11, v174
	v_sub_f32_e32 v11, 1.0, v11
	v_fma_mixlo_f16 v12, v11, v10, v174 op_sel:[0,0,1] op_sel_hi:[0,0,1]
	v_fma_mix_f32 v10, v11, v10, v174 op_sel:[0,0,1] op_sel_hi:[0,0,1]
	ds_write_b16 v4, v12 offset:19456
	v_cvt_f32_f16_e32 v11, v175
	v_sub_f32_e32 v11, 1.0, v11
	v_fma_mixlo_f16 v12, v11, v10, v175 op_sel:[0,0,1] op_sel_hi:[0,0,1]
	v_fma_mix_f32 v10, v11, v10, v175 op_sel:[0,0,1] op_sel_hi:[0,0,1]
	ds_write_b16 v4, v12 offset:18432
	v_cvt_f32_f16_e32 v11, v176
	v_sub_f32_e32 v11, 1.0, v11
	v_fma_mixlo_f16 v12, v11, v10, v176 op_sel:[0,0,1] op_sel_hi:[0,0,1]
	v_fma_mix_f32 v10, v11, v10, v176 op_sel:[0,0,1] op_sel_hi:[0,0,1]
	ds_write_b16 v4, v12 offset:17408
	v_cvt_f32_f16_e32 v11, v177
	v_sub_f32_e32 v11, 1.0, v11
	v_fma_mixlo_f16 v12, v11, v10, v177 op_sel:[0,0,1] op_sel_hi:[0,0,1]
	v_fma_mix_f32 v10, v11, v10, v177 op_sel:[0,0,1] op_sel_hi:[0,0,1]
	ds_write_b16 v4, v12 offset:16384
	s_waitcnt vmcnt(8)
	v_cvt_f32_f16_e32 v11, v178
	v_sub_f32_e32 v11, 1.0, v11
	v_fma_mixlo_f16 v12, v11, v10, v178 op_sel:[0,0,1] op_sel_hi:[0,0,1]
	v_fma_mix_f32 v10, v11, v10, v178 op_sel:[0,0,1] op_sel_hi:[0,0,1]
	ds_write_b16 v4, v12 offset:15360
	v_cvt_f32_f16_e32 v11, v179
	v_sub_f32_e32 v11, 1.0, v11
	v_fma_mixlo_f16 v12, v11, v10, v179 op_sel:[0,0,1] op_sel_hi:[0,0,1]
	v_fma_mix_f32 v10, v11, v10, v179 op_sel:[0,0,1] op_sel_hi:[0,0,1]
	ds_write_b16 v4, v12 offset:14336
	v_cvt_f32_f16_e32 v11, v180
	v_sub_f32_e32 v11, 1.0, v11
	v_fma_mixlo_f16 v12, v11, v10, v180 op_sel:[0,0,1] op_sel_hi:[0,0,1]
	v_fma_mix_f32 v10, v11, v10, v180 op_sel:[0,0,1] op_sel_hi:[0,0,1]
	ds_write_b16 v4, v12 offset:13312
	v_cvt_f32_f16_e32 v11, v181
	v_sub_f32_e32 v11, 1.0, v11
	v_fma_mixlo_f16 v12, v11, v10, v181 op_sel:[0,0,1] op_sel_hi:[0,0,1]
	v_fma_mix_f32 v10, v11, v10, v181 op_sel:[0,0,1] op_sel_hi:[0,0,1]
	ds_write_b16 v4, v12 offset:12288
	v_cvt_f32_f16_e32 v11, v182
	v_sub_f32_e32 v11, 1.0, v11
	v_fma_mixlo_f16 v12, v11, v10, v182 op_sel:[0,0,1] op_sel_hi:[0,0,1]
	v_fma_mix_f32 v10, v11, v10, v182 op_sel:[0,0,1] op_sel_hi:[0,0,1]
	ds_write_b16 v4, v12 offset:11264
	v_cvt_f32_f16_e32 v11, v183
	v_sub_f32_e32 v11, 1.0, v11
	v_fma_mixlo_f16 v12, v11, v10, v183 op_sel:[0,0,1] op_sel_hi:[0,0,1]
	v_fma_mix_f32 v10, v11, v10, v183 op_sel:[0,0,1] op_sel_hi:[0,0,1]
	ds_write_b16 v4, v12 offset:10240
	v_cvt_f32_f16_e32 v11, v184
	v_sub_f32_e32 v11, 1.0, v11
	v_fma_mixlo_f16 v12, v11, v10, v184 op_sel:[0,0,1] op_sel_hi:[0,0,1]
	v_fma_mix_f32 v10, v11, v10, v184 op_sel:[0,0,1] op_sel_hi:[0,0,1]
	ds_write_b16 v4, v12 offset:9216
	v_cvt_f32_f16_e32 v11, v185
	v_sub_f32_e32 v11, 1.0, v11
	v_fma_mixlo_f16 v12, v11, v10, v185 op_sel:[0,0,1] op_sel_hi:[0,0,1]
	v_fma_mix_f32 v10, v11, v10, v185 op_sel:[0,0,1] op_sel_hi:[0,0,1]
	ds_write_b16 v4, v12 offset:8192
	v_cvt_f32_f16_e32 v11, v186
	v_sub_f32_e32 v11, 1.0, v11
	v_fma_mixlo_f16 v12, v11, v10, v186 op_sel:[0,0,1] op_sel_hi:[0,0,1]
	v_fma_mix_f32 v10, v11, v10, v186 op_sel:[0,0,1] op_sel_hi:[0,0,1]
	ds_write_b16 v4, v12 offset:7168
	v_cvt_f32_f16_e32 v11, v187
	v_sub_f32_e32 v11, 1.0, v11
	v_fma_mixlo_f16 v12, v11, v10, v187 op_sel:[0,0,1] op_sel_hi:[0,0,1]
	v_fma_mix_f32 v10, v11, v10, v187 op_sel:[0,0,1] op_sel_hi:[0,0,1]
	ds_write_b16 v4, v12 offset:6144
	v_cvt_f32_f16_e32 v11, v188
	v_sub_f32_e32 v11, 1.0, v11
	v_fma_mixlo_f16 v12, v11, v10, v188 op_sel:[0,0,1] op_sel_hi:[0,0,1]
	v_fma_mix_f32 v10, v11, v10, v188 op_sel:[0,0,1] op_sel_hi:[0,0,1]
	ds_write_b16 v4, v12 offset:5120
	v_cvt_f32_f16_e32 v11, v189
	v_sub_f32_e32 v11, 1.0, v11
	v_fma_mixlo_f16 v12, v11, v10, v189 op_sel:[0,0,1] op_sel_hi:[0,0,1]
	v_fma_mix_f32 v10, v11, v10, v189 op_sel:[0,0,1] op_sel_hi:[0,0,1]
	ds_write_b16 v4, v12 offset:4096
	v_cvt_f32_f16_e32 v11, v190
	v_sub_f32_e32 v11, 1.0, v11
	v_fma_mixlo_f16 v12, v11, v10, v190 op_sel:[0,0,1] op_sel_hi:[0,0,1]
	v_fma_mix_f32 v10, v11, v10, v190 op_sel:[0,0,1] op_sel_hi:[0,0,1]
	ds_write_b16 v4, v12 offset:3072
	v_cvt_f32_f16_e32 v11, v191
	v_sub_f32_e32 v11, 1.0, v11
	v_fma_mixlo_f16 v12, v11, v10, v191 op_sel:[0,0,1] op_sel_hi:[0,0,1]
	v_fma_mix_f32 v10, v11, v10, v191 op_sel:[0,0,1] op_sel_hi:[0,0,1]
	ds_write_b16 v4, v12 offset:2048
	v_cvt_f32_f16_e32 v11, v192
	v_sub_f32_e32 v11, 1.0, v11
	v_fma_mixlo_f16 v12, v11, v10, v192 op_sel:[0,0,1] op_sel_hi:[0,0,1]
	v_fma_mix_f32 v10, v11, v10, v192 op_sel:[0,0,1] op_sel_hi:[0,0,1]
	ds_write_b16 v4, v12 offset:1024
	v_cvt_f32_f16_e32 v11, v193
	v_sub_f32_e32 v11, 1.0, v11
	v_fma_mixlo_f16 v12, v11, v10, v193 op_sel:[0,0,1] op_sel_hi:[0,0,1]
	v_fma_mix_f32 v10, v11, v10, v193 op_sel:[0,0,1] op_sel_hi:[0,0,1]
	ds_write_b16 v4, v12 offset:0
	s_branch .Ll2x_out
; #define LAS __attribute__((address_space(3)))
; __device__ __forceinline__ unsigned pk2(float lo, float hi) { return f2bf(lo) | (f2bf(hi) << 16); }
; __device__ __forceinline__ void lru_pass2_unit(int cu, const h2* AD, const float2* LCS, const bf16* LG, bf16* MIX, lds_t* lds, int tid) {
;     ...
;     __syncthreads();
;     { typedef _Float16 h8 __attribute__((ext_vector_type(8))); const int c8 = (tid & 31) * 8;
; #pragma unroll 4
;         for (int i = 0; i < 8; ++i) { const int r = (tid >> 5) + 16 * i; const h8 hf = *(const LAS h8*)(HS + r * 512 + c8), hb = *(const LAS h8*)(HS + r * 512 + 256 + c8);
;             const v4u g = *(const v4u*)(LG + (size_t)(m0 + r) * 256 + c8); v4u o;
; #pragma unroll
;             for (int e = 0; e < 4; ++e) o[e] = pk2(((float)hf[2 * e] + (float)hb[2 * e]) * bflo(g[e]), ((float)hf[2 * e + 1] + (float)hb[2 * e + 1]) * bfhi(g[e]));
;             *(v4u*)(MIX + (size_t)(m0 + r) * DM + 768 + c8) = o; } }
;     __syncthreads();
.Ll2x_out:
	s_waitcnt lgkmcnt(0)
	s_barrier
	s_waitcnt vmcnt(0)
	ds_read_b128 v[14:17], v6 offset:0
	ds_read_b128 v[18:21], v6 offset:512
	s_waitcnt lgkmcnt(0)
	v_cvt_f32_f16_e32 v22, v14
	v_cvt_f32_f16_sdwa v23, v14 dst_sel:DWORD dst_unused:UNUSED_PAD src0_sel:WORD_1
	v_cvt_f32_f16_e32 v24, v18
	v_cvt_f32_f16_sdwa v25, v18 dst_sel:DWORD dst_unused:UNUSED_PAD src0_sel:WORD_1
	v_add_f32_e32 v22, v22, v24
	v_add_f32_e32 v23, v23, v25
	v_lshlrev_b32_e32 v24, 16, v86
	v_and_b32_e32 v25, 0xffff0000, v86
	v_mul_f32_e32 v22, v22, v24
	v_mul_f32_e32 v23, v23, v25
	v_cvt_pk_bf16_f32 v38, v22, v23
	v_cvt_f32_f16_e32 v26, v15
	v_cvt_f32_f16_sdwa v27, v15 dst_sel:DWORD dst_unused:UNUSED_PAD src0_sel:WORD_1
	v_cvt_f32_f16_e32 v28, v19
	v_cvt_f32_f16_sdwa v29, v19 dst_sel:DWORD dst_unused:UNUSED_PAD src0_sel:WORD_1
	v_add_f32_e32 v26, v26, v28
	v_add_f32_e32 v27, v27, v29
	v_lshlrev_b32_e32 v28, 16, v87
	v_and_b32_e32 v29, 0xffff0000, v87
	v_mul_f32_e32 v26, v26, v28
	v_mul_f32_e32 v27, v27, v29
	v_cvt_pk_bf16_f32 v39, v26, v27
	v_cvt_f32_f16_e32 v30, v16
	v_cvt_f32_f16_sdwa v31, v16 dst_sel:DWORD dst_unused:UNUSED_PAD src0_sel:WORD_1
	v_cvt_f32_f16_e32 v32, v20
	v_cvt_f32_f16_sdwa v33, v20 dst_sel:DWORD dst_unused:UNUSED_PAD src0_sel:WORD_1
	v_add_f32_e32 v30, v30, v32
	v_add_f32_e32 v31, v31, v33
	v_lshlrev_b32_e32 v32, 16, v88
	v_and_b32_e32 v33, 0xffff0000, v88
	v_mul_f32_e32 v30, v30, v32
	v_mul_f32_e32 v31, v31, v33
	v_cvt_pk_bf16_f32 v40, v30, v31
	v_cvt_f32_f16_e32 v34, v17
	v_cvt_f32_f16_sdwa v35, v17 dst_sel:DWORD dst_unused:UNUSED_PAD src0_sel:WORD_1
	v_cvt_f32_f16_e32 v36, v21
	v_cvt_f32_f16_sdwa v37, v21 dst_sel:DWORD dst_unused:UNUSED_PAD src0_sel:WORD_1
	v_add_f32_e32 v34, v34, v36
	v_add_f32_e32 v35, v35, v37
	v_lshlrev_b32_e32 v36, 16, v89
	v_and_b32_e32 v37, 0xffff0000, v89
	v_mul_f32_e32 v34, v34, v36
	v_mul_f32_e32 v35, v35, v37
	v_cvt_pk_bf16_f32 v41, v34, v35
	global_store_dwordx4 v9, v[38:41], s[16:17] offset:1536
	s_add_u32 s16, s16, 0x8000
	s_addc_u32 s17, s17, 0
	ds_read_b128 v[14:17], v6 offset:16384
	ds_read_b128 v[18:21], v6 offset:16896
	s_waitcnt lgkmcnt(0)
	v_cvt_f32_f16_e32 v22, v14
	v_cvt_f32_f16_sdwa v23, v14 dst_sel:DWORD dst_unused:UNUSED_PAD src0_sel:WORD_1
	v_cvt_f32_f16_e32 v24, v18
	v_cvt_f32_f16_sdwa v25, v18 dst_sel:DWORD dst_unused:UNUSED_PAD src0_sel:WORD_1
	v_add_f32_e32 v22, v22, v24
	v_add_f32_e32 v23, v23, v25
	v_lshlrev_b32_e32 v24, 16, v90
	v_and_b32_e32 v25, 0xffff0000, v90
	v_mul_f32_e32 v22, v22, v24
	v_mul_f32_e32 v23, v23, v25
	v_cvt_pk_bf16_f32 v38, v22, v23
	v_cvt_f32_f16_e32 v26, v15
	v_cvt_f32_f16_sdwa v27, v15 dst_sel:DWORD dst_unused:UNUSED_PAD src0_sel:WORD_1
	v_cvt_f32_f16_e32 v28, v19
	v_cvt_f32_f16_sdwa v29, v19 dst_sel:DWORD dst_unused:UNUSED_PAD src0_sel:WORD_1
	v_add_f32_e32 v26, v26, v28
	v_add_f32_e32 v27, v27, v29
	v_lshlrev_b32_e32 v28, 16, v91
	v_and_b32_e32 v29, 0xffff0000, v91
	v_mul_f32_e32 v26, v26, v28
	v_mul_f32_e32 v27, v27, v29
	v_cvt_pk_bf16_f32 v39, v26, v27
	v_cvt_f32_f16_e32 v30, v16
	v_cvt_f32_f16_sdwa v31, v16 dst_sel:DWORD dst_unused:UNUSED_PAD src0_sel:WORD_1
	v_cvt_f32_f16_e32 v32, v20
	v_cvt_f32_f16_sdwa v33, v20 dst_sel:DWORD dst_unused:UNUSED_PAD src0_sel:WORD_1
	v_add_f32_e32 v30, v30, v32
	v_add_f32_e32 v31, v31, v33
	v_lshlrev_b32_e32 v32, 16, v92
	v_and_b32_e32 v33, 0xffff0000, v92
	v_mul_f32_e32 v30, v30, v32
	v_mul_f32_e32 v31, v31, v33
	v_cvt_pk_bf16_f32 v40, v30, v31
	v_cvt_f32_f16_e32 v34, v17
	v_cvt_f32_f16_sdwa v35, v17 dst_sel:DWORD dst_unused:UNUSED_PAD src0_sel:WORD_1
	v_cvt_f32_f16_e32 v36, v21
	v_cvt_f32_f16_sdwa v37, v21 dst_sel:DWORD dst_unused:UNUSED_PAD src0_sel:WORD_1
	v_add_f32_e32 v34, v34, v36
	v_add_f32_e32 v35, v35, v37
	v_lshlrev_b32_e32 v36, 16, v93
	v_and_b32_e32 v37, 0xffff0000, v93
	v_mul_f32_e32 v34, v34, v36
	v_mul_f32_e32 v35, v35, v37
	v_cvt_pk_bf16_f32 v41, v34, v35
	global_store_dwordx4 v9, v[38:41], s[16:17] offset:1536
	s_add_u32 s16, s16, 0x8000
	s_addc_u32 s17, s17, 0
	ds_read_b128 v[14:17], v6 offset:32768
	ds_read_b128 v[18:21], v6 offset:33280
	s_waitcnt lgkmcnt(0)
	v_cvt_f32_f16_e32 v22, v14
	v_cvt_f32_f16_sdwa v23, v14 dst_sel:DWORD dst_unused:UNUSED_PAD src0_sel:WORD_1
	v_cvt_f32_f16_e32 v24, v18
	v_cvt_f32_f16_sdwa v25, v18 dst_sel:DWORD dst_unused:UNUSED_PAD src0_sel:WORD_1
	v_add_f32_e32 v22, v22, v24
	v_add_f32_e32 v23, v23, v25
	v_lshlrev_b32_e32 v24, 16, v94
	v_and_b32_e32 v25, 0xffff0000, v94
	v_mul_f32_e32 v22, v22, v24
	v_mul_f32_e32 v23, v23, v25
	v_cvt_pk_bf16_f32 v38, v22, v23
	v_cvt_f32_f16_e32 v26, v15
	v_cvt_f32_f16_sdwa v27, v15 dst_sel:DWORD dst_unused:UNUSED_PAD src0_sel:WORD_1
	v_cvt_f32_f16_e32 v28, v19
	v_cvt_f32_f16_sdwa v29, v19 dst_sel:DWORD dst_unused:UNUSED_PAD src0_sel:WORD_1
	v_add_f32_e32 v26, v26, v28
	v_add_f32_e32 v27, v27, v29
	v_lshlrev_b32_e32 v28, 16, v95
	v_and_b32_e32 v29, 0xffff0000, v95
	v_mul_f32_e32 v26, v26, v28
	v_mul_f32_e32 v27, v27, v29
	v_cvt_pk_bf16_f32 v39, v26, v27
	v_cvt_f32_f16_e32 v30, v16
	v_cvt_f32_f16_sdwa v31, v16 dst_sel:DWORD dst_unused:UNUSED_PAD src0_sel:WORD_1
	v_cvt_f32_f16_e32 v32, v20
	v_cvt_f32_f16_sdwa v33, v20 dst_sel:DWORD dst_unused:UNUSED_PAD src0_sel:WORD_1
	v_add_f32_e32 v30, v30, v32
	v_add_f32_e32 v31, v31, v33
	v_lshlrev_b32_e32 v32, 16, v96
	v_and_b32_e32 v33, 0xffff0000, v96
	v_mul_f32_e32 v30, v30, v32
	v_mul_f32_e32 v31, v31, v33
	v_cvt_pk_bf16_f32 v40, v30, v31
	v_cvt_f32_f16_e32 v34, v17
	v_cvt_f32_f16_sdwa v35, v17 dst_sel:DWORD dst_unused:UNUSED_PAD src0_sel:WORD_1
	v_cvt_f32_f16_e32 v36, v21
	v_cvt_f32_f16_sdwa v37, v21 dst_sel:DWORD dst_unused:UNUSED_PAD src0_sel:WORD_1
	v_add_f32_e32 v34, v34, v36
	v_add_f32_e32 v35, v35, v37
	v_lshlrev_b32_e32 v36, 16, v97
	v_and_b32_e32 v37, 0xffff0000, v97
	v_mul_f32_e32 v34, v34, v36
	v_mul_f32_e32 v35, v35, v37
	v_cvt_pk_bf16_f32 v41, v34, v35
	global_store_dwordx4 v9, v[38:41], s[16:17] offset:1536
	s_add_u32 s16, s16, 0x8000
	s_addc_u32 s17, s17, 0
	ds_read_b128 v[14:17], v6 offset:49152
	ds_read_b128 v[18:21], v6 offset:49664
	s_waitcnt lgkmcnt(0)
; #define LAS __attribute__((address_space(3)))
; __device__ __forceinline__ unsigned pk2(float lo, float hi) { return f2bf(lo) | (f2bf(hi) << 16); }
; __device__ __forceinline__ void lru_pass2_unit(int cu, const h2* AD, const float2* LCS, const bf16* LG, bf16* MIX, lds_t* lds, int tid) {
;     ...
;     __syncthreads();
;     { typedef _Float16 h8 __attribute__((ext_vector_type(8))); const int c8 = (tid & 31) * 8;
; #pragma unroll 4
;         for (int i = 0; i < 8; ++i) { const int r = (tid >> 5) + 16 * i; const h8 hf = *(const LAS h8*)(HS + r * 512 + c8), hb = *(const LAS h8*)(HS + r * 512 + 256 + c8);
;             const v4u g = *(const v4u*)(LG + (size_t)(m0 + r) * 256 + c8); v4u o;
; #pragma unroll
;             for (int e = 0; e < 4; ++e) o[e] = pk2(((float)hf[2 * e] + (float)hb[2 * e]) * bflo(g[e]), ((float)hf[2 * e + 1] + (float)hb[2 * e + 1]) * bfhi(g[e]));
;             *(v4u*)(MIX + (size_t)(m0 + r) * DM + 768 + c8) = o; } }
;     __syncthreads();
	v_cvt_f32_f16_e32 v22, v14
	v_cvt_f32_f16_sdwa v23, v14 dst_sel:DWORD dst_unused:UNUSED_PAD src0_sel:WORD_1
	v_cvt_f32_f16_e32 v24, v18
	v_cvt_f32_f16_sdwa v25, v18 dst_sel:DWORD dst_unused:UNUSED_PAD src0_sel:WORD_1
	v_add_f32_e32 v22, v22, v24
	v_add_f32_e32 v23, v23, v25
	v_lshlrev_b32_e32 v24, 16, v98
	v_and_b32_e32 v25, 0xffff0000, v98
	v_mul_f32_e32 v22, v22, v24
	v_mul_f32_e32 v23, v23, v25
	v_cvt_pk_bf16_f32 v38, v22, v23
	v_cvt_f32_f16_e32 v26, v15
	v_cvt_f32_f16_sdwa v27, v15 dst_sel:DWORD dst_unused:UNUSED_PAD src0_sel:WORD_1
	v_cvt_f32_f16_e32 v28, v19
	v_cvt_f32_f16_sdwa v29, v19 dst_sel:DWORD dst_unused:UNUSED_PAD src0_sel:WORD_1
	v_add_f32_e32 v26, v26, v28
	v_add_f32_e32 v27, v27, v29
	v_lshlrev_b32_e32 v28, 16, v99
	v_and_b32_e32 v29, 0xffff0000, v99
	v_mul_f32_e32 v26, v26, v28
	v_mul_f32_e32 v27, v27, v29
	v_cvt_pk_bf16_f32 v39, v26, v27
	v_cvt_f32_f16_e32 v30, v16
	v_cvt_f32_f16_sdwa v31, v16 dst_sel:DWORD dst_unused:UNUSED_PAD src0_sel:WORD_1
	v_cvt_f32_f16_e32 v32, v20
	v_cvt_f32_f16_sdwa v33, v20 dst_sel:DWORD dst_unused:UNUSED_PAD src0_sel:WORD_1
	v_add_f32_e32 v30, v30, v32
	v_add_f32_e32 v31, v31, v33
	v_lshlrev_b32_e32 v32, 16, v100
	v_and_b32_e32 v33, 0xffff0000, v100
	v_mul_f32_e32 v30, v30, v32
	v_mul_f32_e32 v31, v31, v33
	v_cvt_pk_bf16_f32 v40, v30, v31
	v_cvt_f32_f16_e32 v34, v17
	v_cvt_f32_f16_sdwa v35, v17 dst_sel:DWORD dst_unused:UNUSED_PAD src0_sel:WORD_1
	v_cvt_f32_f16_e32 v36, v21
	v_cvt_f32_f16_sdwa v37, v21 dst_sel:DWORD dst_unused:UNUSED_PAD src0_sel:WORD_1
	v_add_f32_e32 v34, v34, v36
	v_add_f32_e32 v35, v35, v37
	v_lshlrev_b32_e32 v36, 16, v101
	v_and_b32_e32 v37, 0xffff0000, v101
	v_mul_f32_e32 v34, v34, v36
	v_mul_f32_e32 v35, v35, v37
	v_cvt_pk_bf16_f32 v41, v34, v35
	global_store_dwordx4 v9, v[38:41], s[16:17] offset:1536
	s_add_u32 s16, s16, 0x8000
	s_addc_u32 s17, s17, 0
	ds_read_b128 v[14:17], v7 offset:0
	ds_read_b128 v[18:21], v7 offset:512
	s_waitcnt lgkmcnt(0)
	v_cvt_f32_f16_e32 v22, v14
	v_cvt_f32_f16_sdwa v23, v14 dst_sel:DWORD dst_unused:UNUSED_PAD src0_sel:WORD_1
	v_cvt_f32_f16_e32 v24, v18
	v_cvt_f32_f16_sdwa v25, v18 dst_sel:DWORD dst_unused:UNUSED_PAD src0_sel:WORD_1
	v_add_f32_e32 v22, v22, v24
	v_add_f32_e32 v23, v23, v25
	v_lshlrev_b32_e32 v24, 16, v102
	v_and_b32_e32 v25, 0xffff0000, v102
	v_mul_f32_e32 v22, v22, v24
	v_mul_f32_e32 v23, v23, v25
	v_cvt_pk_bf16_f32 v38, v22, v23
	v_cvt_f32_f16_e32 v26, v15
	v_cvt_f32_f16_sdwa v27, v15 dst_sel:DWORD dst_unused:UNUSED_PAD src0_sel:WORD_1
	v_cvt_f32_f16_e32 v28, v19
	v_cvt_f32_f16_sdwa v29, v19 dst_sel:DWORD dst_unused:UNUSED_PAD src0_sel:WORD_1
	v_add_f32_e32 v26, v26, v28
	v_add_f32_e32 v27, v27, v29
	v_lshlrev_b32_e32 v28, 16, v103
	v_and_b32_e32 v29, 0xffff0000, v103
	v_mul_f32_e32 v26, v26, v28
	v_mul_f32_e32 v27, v27, v29
	v_cvt_pk_bf16_f32 v39, v26, v27
	v_cvt_f32_f16_e32 v30, v16
	v_cvt_f32_f16_sdwa v31, v16 dst_sel:DWORD dst_unused:UNUSED_PAD src0_sel:WORD_1
	v_cvt_f32_f16_e32 v32, v20
	v_cvt_f32_f16_sdwa v33, v20 dst_sel:DWORD dst_unused:UNUSED_PAD src0_sel:WORD_1
	v_add_f32_e32 v30, v30, v32
	v_add_f32_e32 v31, v31, v33
	v_lshlrev_b32_e32 v32, 16, v104
	v_and_b32_e32 v33, 0xffff0000, v104
	v_mul_f32_e32 v30, v30, v32
	v_mul_f32_e32 v31, v31, v33
	v_cvt_pk_bf16_f32 v40, v30, v31
	v_cvt_f32_f16_e32 v34, v17
	v_cvt_f32_f16_sdwa v35, v17 dst_sel:DWORD dst_unused:UNUSED_PAD src0_sel:WORD_1
	v_cvt_f32_f16_e32 v36, v21
	v_cvt_f32_f16_sdwa v37, v21 dst_sel:DWORD dst_unused:UNUSED_PAD src0_sel:WORD_1
	v_add_f32_e32 v34, v34, v36
	v_add_f32_e32 v35, v35, v37
	v_lshlrev_b32_e32 v36, 16, v105
	v_and_b32_e32 v37, 0xffff0000, v105
	v_mul_f32_e32 v34, v34, v36
	v_mul_f32_e32 v35, v35, v37
	v_cvt_pk_bf16_f32 v41, v34, v35
	global_store_dwordx4 v9, v[38:41], s[16:17] offset:1536
	s_add_u32 s16, s16, 0x8000
	s_addc_u32 s17, s17, 0
	ds_read_b128 v[14:17], v7 offset:16384
	ds_read_b128 v[18:21], v7 offset:16896
	s_waitcnt lgkmcnt(0)
; #define LAS __attribute__((address_space(3)))
; __device__ __forceinline__ unsigned pk2(float lo, float hi) { return f2bf(lo) | (f2bf(hi) << 16); }
; __device__ __forceinline__ void lru_pass2_unit(int cu, const h2* AD, const float2* LCS, const bf16* LG, bf16* MIX, lds_t* lds, int tid) {
;     ...
;     __syncthreads();
;     { typedef _Float16 h8 __attribute__((ext_vector_type(8))); const int c8 = (tid & 31) * 8;
; #pragma unroll 4
;         for (int i = 0; i < 8; ++i) { const int r = (tid >> 5) + 16 * i; const h8 hf = *(const LAS h8*)(HS + r * 512 + c8), hb = *(const LAS h8*)(HS + r * 512 + 256 + c8);
;             const v4u g = *(const v4u*)(LG + (size_t)(m0 + r) * 256 + c8); v4u o;
; #pragma unroll
;             for (int e = 0; e < 4; ++e) o[e] = pk2(((float)hf[2 * e] + (float)hb[2 * e]) * bflo(g[e]), ((float)hf[2 * e + 1] + (float)hb[2 * e + 1]) * bfhi(g[e]));
;             *(v4u*)(MIX + (size_t)(m0 + r) * DM + 768 + c8) = o; } }
;     __syncthreads();
	v_cvt_f32_f16_e32 v22, v14
	v_cvt_f32_f16_sdwa v23, v14 dst_sel:DWORD dst_unused:UNUSED_PAD src0_sel:WORD_1
	v_cvt_f32_f16_e32 v24, v18
	v_cvt_f32_f16_sdwa v25, v18 dst_sel:DWORD dst_unused:UNUSED_PAD src0_sel:WORD_1
	v_add_f32_e32 v22, v22, v24
	v_add_f32_e32 v23, v23, v25
	v_lshlrev_b32_e32 v24, 16, v106
	v_and_b32_e32 v25, 0xffff0000, v106
	v_mul_f32_e32 v22, v22, v24
	v_mul_f32_e32 v23, v23, v25
	v_cvt_pk_bf16_f32 v38, v22, v23
	v_cvt_f32_f16_e32 v26, v15
	v_cvt_f32_f16_sdwa v27, v15 dst_sel:DWORD dst_unused:UNUSED_PAD src0_sel:WORD_1
	v_cvt_f32_f16_e32 v28, v19
	v_cvt_f32_f16_sdwa v29, v19 dst_sel:DWORD dst_unused:UNUSED_PAD src0_sel:WORD_1
	v_add_f32_e32 v26, v26, v28
	v_add_f32_e32 v27, v27, v29
	v_lshlrev_b32_e32 v28, 16, v107
	v_and_b32_e32 v29, 0xffff0000, v107
	v_mul_f32_e32 v26, v26, v28
	v_mul_f32_e32 v27, v27, v29
	v_cvt_pk_bf16_f32 v39, v26, v27
	v_cvt_f32_f16_e32 v30, v16
	v_cvt_f32_f16_sdwa v31, v16 dst_sel:DWORD dst_unused:UNUSED_PAD src0_sel:WORD_1
	v_cvt_f32_f16_e32 v32, v20
	v_cvt_f32_f16_sdwa v33, v20 dst_sel:DWORD dst_unused:UNUSED_PAD src0_sel:WORD_1
	v_add_f32_e32 v30, v30, v32
	v_add_f32_e32 v31, v31, v33
	v_lshlrev_b32_e32 v32, 16, v108
	v_and_b32_e32 v33, 0xffff0000, v108
	v_mul_f32_e32 v30, v30, v32
	v_mul_f32_e32 v31, v31, v33
	v_cvt_pk_bf16_f32 v40, v30, v31
	v_cvt_f32_f16_e32 v34, v17
	v_cvt_f32_f16_sdwa v35, v17 dst_sel:DWORD dst_unused:UNUSED_PAD src0_sel:WORD_1
	v_cvt_f32_f16_e32 v36, v21
	v_cvt_f32_f16_sdwa v37, v21 dst_sel:DWORD dst_unused:UNUSED_PAD src0_sel:WORD_1
	v_add_f32_e32 v34, v34, v36
	v_add_f32_e32 v35, v35, v37
	v_lshlrev_b32_e32 v36, 16, v109
	v_and_b32_e32 v37, 0xffff0000, v109
	v_mul_f32_e32 v34, v34, v36
	v_mul_f32_e32 v35, v35, v37
	v_cvt_pk_bf16_f32 v41, v34, v35
	global_store_dwordx4 v9, v[38:41], s[16:17] offset:1536
	s_add_u32 s16, s16, 0x8000
	s_addc_u32 s17, s17, 0
	ds_read_b128 v[14:17], v7 offset:32768
	ds_read_b128 v[18:21], v7 offset:33280
	s_waitcnt lgkmcnt(0)
	v_cvt_f32_f16_e32 v22, v14
	v_cvt_f32_f16_sdwa v23, v14 dst_sel:DWORD dst_unused:UNUSED_PAD src0_sel:WORD_1
	v_cvt_f32_f16_e32 v24, v18
	v_cvt_f32_f16_sdwa v25, v18 dst_sel:DWORD dst_unused:UNUSED_PAD src0_sel:WORD_1
	v_add_f32_e32 v22, v22, v24
	v_add_f32_e32 v23, v23, v25
	v_lshlrev_b32_e32 v24, 16, v110
	v_and_b32_e32 v25, 0xffff0000, v110
	v_mul_f32_e32 v22, v22, v24
	v_mul_f32_e32 v23, v23, v25
	v_cvt_pk_bf16_f32 v38, v22, v23
	v_cvt_f32_f16_e32 v26, v15
	v_cvt_f32_f16_sdwa v27, v15 dst_sel:DWORD dst_unused:UNUSED_PAD src0_sel:WORD_1
	v_cvt_f32_f16_e32 v28, v19
	v_cvt_f32_f16_sdwa v29, v19 dst_sel:DWORD dst_unused:UNUSED_PAD src0_sel:WORD_1
	v_add_f32_e32 v26, v26, v28
	v_add_f32_e32 v27, v27, v29
	v_lshlrev_b32_e32 v28, 16, v111
	v_and_b32_e32 v29, 0xffff0000, v111
	v_mul_f32_e32 v26, v26, v28
	v_mul_f32_e32 v27, v27, v29
	v_cvt_pk_bf16_f32 v39, v26, v27
	v_cvt_f32_f16_e32 v30, v16
	v_cvt_f32_f16_sdwa v31, v16 dst_sel:DWORD dst_unused:UNUSED_PAD src0_sel:WORD_1
	v_cvt_f32_f16_e32 v32, v20
	v_cvt_f32_f16_sdwa v33, v20 dst_sel:DWORD dst_unused:UNUSED_PAD src0_sel:WORD_1
	v_add_f32_e32 v30, v30, v32
	v_add_f32_e32 v31, v31, v33
	v_lshlrev_b32_e32 v32, 16, v112
	v_and_b32_e32 v33, 0xffff0000, v112
	v_mul_f32_e32 v30, v30, v32
	v_mul_f32_e32 v31, v31, v33
	v_cvt_pk_bf16_f32 v40, v30, v31
	v_cvt_f32_f16_e32 v34, v17
	v_cvt_f32_f16_sdwa v35, v17 dst_sel:DWORD dst_unused:UNUSED_PAD src0_sel:WORD_1
	v_cvt_f32_f16_e32 v36, v21
	v_cvt_f32_f16_sdwa v37, v21 dst_sel:DWORD dst_unused:UNUSED_PAD src0_sel:WORD_1
	v_add_f32_e32 v34, v34, v36
	v_add_f32_e32 v35, v35, v37
	v_lshlrev_b32_e32 v36, 16, v113
	v_and_b32_e32 v37, 0xffff0000, v113
	v_mul_f32_e32 v34, v34, v36
	v_mul_f32_e32 v35, v35, v37
	v_cvt_pk_bf16_f32 v41, v34, v35
	global_store_dwordx4 v9, v[38:41], s[16:17] offset:1536
	s_add_u32 s16, s16, 0x8000
	s_addc_u32 s17, s17, 0
	ds_read_b128 v[14:17], v7 offset:49152
	ds_read_b128 v[18:21], v7 offset:49664
	s_waitcnt lgkmcnt(0)
	v_cvt_f32_f16_e32 v22, v14
	v_cvt_f32_f16_sdwa v23, v14 dst_sel:DWORD dst_unused:UNUSED_PAD src0_sel:WORD_1
	v_cvt_f32_f16_e32 v24, v18
	v_cvt_f32_f16_sdwa v25, v18 dst_sel:DWORD dst_unused:UNUSED_PAD src0_sel:WORD_1
	v_add_f32_e32 v22, v22, v24
	v_add_f32_e32 v23, v23, v25
	v_lshlrev_b32_e32 v24, 16, v226
	v_and_b32_e32 v25, 0xffff0000, v226
	v_mul_f32_e32 v22, v22, v24
	v_mul_f32_e32 v23, v23, v25
	v_cvt_pk_bf16_f32 v38, v22, v23
	v_cvt_f32_f16_e32 v26, v15
	v_cvt_f32_f16_sdwa v27, v15 dst_sel:DWORD dst_unused:UNUSED_PAD src0_sel:WORD_1
	v_cvt_f32_f16_e32 v28, v19
	v_cvt_f32_f16_sdwa v29, v19 dst_sel:DWORD dst_unused:UNUSED_PAD src0_sel:WORD_1
	v_add_f32_e32 v26, v26, v28
	v_add_f32_e32 v27, v27, v29
	v_lshlrev_b32_e32 v28, 16, v227
	v_and_b32_e32 v29, 0xffff0000, v227
	v_mul_f32_e32 v26, v26, v28
	v_mul_f32_e32 v27, v27, v29
	v_cvt_pk_bf16_f32 v39, v26, v27
	v_cvt_f32_f16_e32 v30, v16
	v_cvt_f32_f16_sdwa v31, v16 dst_sel:DWORD dst_unused:UNUSED_PAD src0_sel:WORD_1
	v_cvt_f32_f16_e32 v32, v20
	v_cvt_f32_f16_sdwa v33, v20 dst_sel:DWORD dst_unused:UNUSED_PAD src0_sel:WORD_1
	v_add_f32_e32 v30, v30, v32
	v_add_f32_e32 v31, v31, v33
	v_lshlrev_b32_e32 v32, 16, v228
	v_and_b32_e32 v33, 0xffff0000, v228
	v_mul_f32_e32 v30, v30, v32
	v_mul_f32_e32 v31, v31, v33
	v_cvt_pk_bf16_f32 v40, v30, v31
	v_cvt_f32_f16_e32 v34, v17
	v_cvt_f32_f16_sdwa v35, v17 dst_sel:DWORD dst_unused:UNUSED_PAD src0_sel:WORD_1
	v_cvt_f32_f16_e32 v36, v21
	v_cvt_f32_f16_sdwa v37, v21 dst_sel:DWORD dst_unused:UNUSED_PAD src0_sel:WORD_1
	v_add_f32_e32 v34, v34, v36
	v_add_f32_e32 v35, v35, v37
	v_lshlrev_b32_e32 v36, 16, v229
	v_and_b32_e32 v37, 0xffff0000, v229
	v_mul_f32_e32 v34, v34, v36
	v_mul_f32_e32 v35, v35, v37
	v_cvt_pk_bf16_f32 v41, v34, v35
	global_store_dwordx4 v9, v[38:41], s[16:17] offset:1536
	s_waitcnt lgkmcnt(0)
	s_barrier
	s_branch .LBB0_786
